# all nine main GEMM K-loops: every LDS-DMA on SGPR base (preserved s[98:99] / vcc scratch), zero 64-bit VALU adds left in load segments
# baseline (speedup 1.0000x reference)
; #define PG8_STAGE(bufoff, gbase, voff) do { _Pragma("unroll") for (int _i = 0; _i < 2; ++_i) \
;         __builtin_amdgcn_global_load_lds((const unsigned*)((const char*)(gbase) + (voff)[_i]), (PG8_LAS unsigned*)(lds + (bufoff) + ldsw + _i * 8192), 16, 0, 0); } while (0)
; #define PG8_LDA(dst, b, h) do { _Pragma("unroll") for (int m = 0; m < 4; ++m) _Pragma("unroll") for (int k = 0; k < 2; ++k) dst[m][k] = *(const PG8_LAS bf16x8*)(lds + PG8_SA(b, h) + aoff + m * 2048 + k * 1024); } while (0)
; #define PG8_LDB(dst, b, h) do { _Pragma("unroll") for (int n = 0; n < 2; ++n) _Pragma("unroll") for (int k = 0; k < 2; ++k) dst[n][k] = *(const PG8_LAS bf16x8*)(lds + PG8_SB(b, h) + boff + n * 2048 + k * 1024); } while (0)
; #define PG8_WAIT_V(n) asm volatile("s_waitcnt vmcnt(" #n ")" ::: "memory")
; #define PG8_WAIT_L(n) asm volatile("s_waitcnt lgkmcnt(" #n ")" ::: "memory")
; #define PG8_BAR __builtin_amdgcn_s_barrier()
; #define PG8_SCHED __builtin_amdgcn_sched_barrier(0)
;     ...
;             const bool last = (t == nt - 2);
;             const char* a1 = cA + (size_t)(t + 1) * kstep;
;             const char* a2 = last ? nA : cA + (size_t)(t + 2) * kstep; const char* b2 = last ? nB : cB + (size_t)(t + 2) * kstep;
;             const char* a3 = a2 + kstep; const char* b3 = b2 + kstep;
;             if (last && has_next) S.a_ready(nxt);
;             if constexpr (SP2) {
;             PG8_LDB(B0, 0, 0); PG8_LDB(B1, 0, 1); PG8_SCHED; PG8_LDA(At, 0, 0); PG8_STAGE(PG8_SA(1, 1), a1 + hstepA, voffA);
;             PG8_WAIT_V(8); PG8_WAIT_L(0); PG8_BAR; PG8_MMA(0, 0, At, B0); PG8_MMA(0, 1, At, B1); PG8_BAR; PG8_SCHED;
;             PG8_LDA(At, 0, 1); PG8_STAGE(PG8_SB(0, 0), b2, voffB); PG8_STAGE(PG8_SB(0, 1), b2 + hstepB, voffB); PG8_STAGE(PG8_SA(0, 0), a2, voffA);
;             PG8_WAIT_V(8); PG8_WAIT_L(0); PG8_BAR; PG8_MMA(1, 0, At, B0); PG8_MMA(1, 1, At, B1); PG8_BAR; PG8_SCHED;
.LBB0_538:
	v_add_u32_e32 v162, 0x10000, v153
	s_add_u32 s63, s64, 0xfffc0080
	s_addc_u32 s66, s65, -1
	s_add_i32 s68, 0, 0x10000
	s_cmp_eq_u32 s57, 12
	s_cselect_b32 s75, s6, s66
	s_cselect_b32 s74, s15, s63
	s_cselect_b32 s67, s34, s55
	s_cselect_b32 s66, s35, s45
	s_add_i32 s63, 0, 0x14000
	ds_read_b128 v[142:145], v162
	ds_read_b128 v[146:149], v162 offset:1024
	ds_read_b128 v[158:161], v162 offset:2048
	ds_read_b128 v[186:189], v162 offset:3072
	ds_read_b128 v[190:193], v162 offset:16384
	ds_read_b128 v[194:197], v162 offset:17408
	ds_read_b128 v[198:201], v162 offset:18432
	ds_read_b128 v[202:205], v162 offset:19456
	s_add_i32 m0, s81, 0xc000
	ds_read_b128 v[206:209], v156
	ds_read_b128 v[210:213], v156 offset:1024
	ds_read_b128 v[214:217], v156 offset:2048
	ds_read_b128 v[218:221], v156 offset:3072
	ds_read_b128 v[222:225], v156 offset:4096
	ds_read_b128 v[234:237], v156 offset:5120
	ds_read_b128 v[238:241], v156 offset:6144
	ds_read_b128 v[242:245], v156 offset:7168
	global_load_lds_dwordx4 v138, s[64:65]
	s_add_i32 m0, s81, 0xe000
	s_nop 0
	global_load_lds_dwordx4 v140, s[64:65]
	s_waitcnt vmcnt(8)
	s_waitcnt lgkmcnt(0)
	s_barrier
	s_setprio 1
	v_mfma_i32_16x16x64_i8 v[128:131], v[142:145], v[206:209], v[128:131]
	v_mfma_i32_16x16x64_i8 v[120:123], v[158:161], v[206:209], v[120:123]
	v_mfma_i32_16x16x64_i8 v[112:115], v[142:145], v[214:217], v[112:115]
	v_mfma_i32_16x16x64_i8 v[104:107], v[158:161], v[214:217], v[104:107]
	v_mfma_i32_16x16x64_i8 v[96:99], v[142:145], v[222:225], v[96:99]
	v_mfma_i32_16x16x64_i8 v[88:91], v[158:161], v[222:225], v[88:91]
	v_mfma_i32_16x16x64_i8 v[80:83], v[142:145], v[238:241], v[80:83]
	v_mfma_i32_16x16x64_i8 v[72:75], v[158:161], v[238:241], v[72:75]
	v_mfma_i32_16x16x64_i8 v[128:131], v[146:149], v[210:213], v[128:131]
	v_mfma_i32_16x16x64_i8 v[120:123], v[186:189], v[210:213], v[120:123]
	v_mfma_i32_16x16x64_i8 v[112:115], v[146:149], v[218:221], v[112:115]
	v_mfma_i32_16x16x64_i8 v[104:107], v[186:189], v[218:221], v[104:107]
	v_mfma_i32_16x16x64_i8 v[96:99], v[146:149], v[234:237], v[96:99]
	v_mfma_i32_16x16x64_i8 v[88:91], v[186:189], v[234:237], v[88:91]
	v_mfma_i32_16x16x64_i8 v[80:83], v[146:149], v[242:245], v[80:83]
	v_mfma_i32_16x16x64_i8 v[72:75], v[186:189], v[242:245], v[72:75]
	v_mfma_i32_16x16x64_i8 v[124:127], v[190:193], v[206:209], v[124:127]
	v_mfma_i32_16x16x64_i8 v[116:119], v[198:201], v[206:209], v[116:119]
	v_mfma_i32_16x16x64_i8 v[108:111], v[190:193], v[214:217], v[108:111]
	v_mfma_i32_16x16x64_i8 v[100:103], v[198:201], v[214:217], v[100:103]
	v_mfma_i32_16x16x64_i8 v[92:95], v[190:193], v[222:225], v[92:95]
	v_mfma_i32_16x16x64_i8 v[84:87], v[198:201], v[222:225], v[84:87]
	v_mfma_i32_16x16x64_i8 v[76:79], v[190:193], v[238:241], v[76:79]
	v_mfma_i32_16x16x64_i8 v[68:71], v[198:201], v[238:241], v[68:71]
	v_mfma_i32_16x16x64_i8 v[124:127], v[194:197], v[210:213], v[124:127]
	v_mfma_i32_16x16x64_i8 v[116:119], v[202:205], v[210:213], v[116:119]
	v_mfma_i32_16x16x64_i8 v[108:111], v[194:197], v[218:221], v[108:111]
	v_mfma_i32_16x16x64_i8 v[100:103], v[202:205], v[218:221], v[100:103]
	v_mfma_i32_16x16x64_i8 v[92:95], v[194:197], v[234:237], v[92:95]
	v_mfma_i32_16x16x64_i8 v[84:87], v[202:205], v[234:237], v[84:87]
	v_mfma_i32_16x16x64_i8 v[76:79], v[194:197], v[242:245], v[76:79]
	v_mfma_i32_16x16x64_i8 v[68:71], v[202:205], v[242:245], v[68:71]
	s_setprio 0
	s_barrier
	s_add_i32 s68, s68, s10
	s_mov_b32 m0, s68
	ds_read_b128 v[206:209], v156 offset:16384
	ds_read_b128 v[210:213], v156 offset:17408
	ds_read_b128 v[214:217], v156 offset:18432
	ds_read_b128 v[218:221], v156 offset:19456
	ds_read_b128 v[222:225], v156 offset:20480
	ds_read_b128 v[234:237], v156 offset:21504
	ds_read_b128 v[238:241], v156 offset:22528
	ds_read_b128 v[242:245], v156 offset:23552
	global_load_lds_dwordx4 v34, s[66:67]
	s_add_i32 m0, s68, 0x2000
	s_add_u32 s70, s66, 0x40000
	s_addc_u32 s71, s67, 0
	s_add_i32 s63, s63, s10
	global_load_lds_dwordx4 v136, s[66:67]
	s_mov_b32 m0, s63
	s_nop 0
	global_load_lds_dwordx4 v34, s[70:71]
	s_add_i32 m0, s63, 0x2000
	s_nop 0
	global_load_lds_dwordx4 v136, s[70:71]
	s_mov_b32 m0, s81
	s_nop 0
	global_load_lds_dwordx4 v132, s[74:75]
	s_mov_b32 m0, s82
	s_nop 0
	global_load_lds_dwordx4 v134, s[74:75]
	s_waitcnt vmcnt(8)
	s_waitcnt lgkmcnt(0)
	s_barrier
	s_setprio 1
	v_mfma_i32_16x16x64_i8 v[64:67], v[142:145], v[206:209], v[64:67]
	v_mfma_i32_16x16x64_i8 v[56:59], v[158:161], v[206:209], v[56:59]
	v_mfma_i32_16x16x64_i8 v[48:51], v[142:145], v[214:217], v[48:51]
	v_mfma_i32_16x16x64_i8 v[40:43], v[158:161], v[214:217], v[40:43]
	v_mfma_i32_16x16x64_i8 v[30:33], v[142:145], v[222:225], v[30:33]
	v_mfma_i32_16x16x64_i8 v[22:25], v[158:161], v[222:225], v[22:25]
	v_mfma_i32_16x16x64_i8 v[14:17], v[142:145], v[238:241], v[14:17]
	v_mfma_i32_16x16x64_i8 v[6:9], v[158:161], v[238:241], v[6:9]
	v_mfma_i32_16x16x64_i8 v[64:67], v[146:149], v[210:213], v[64:67]
	v_mfma_i32_16x16x64_i8 v[56:59], v[186:189], v[210:213], v[56:59]
	v_mfma_i32_16x16x64_i8 v[48:51], v[146:149], v[218:221], v[48:51]
	v_mfma_i32_16x16x64_i8 v[40:43], v[186:189], v[218:221], v[40:43]
	v_mfma_i32_16x16x64_i8 v[30:33], v[146:149], v[234:237], v[30:33]
	v_mfma_i32_16x16x64_i8 v[22:25], v[186:189], v[234:237], v[22:25]
	v_mfma_i32_16x16x64_i8 v[14:17], v[146:149], v[242:245], v[14:17]
	v_mfma_i32_16x16x64_i8 v[6:9], v[186:189], v[242:245], v[6:9]
	v_mfma_i32_16x16x64_i8 v[60:63], v[190:193], v[206:209], v[60:63]
	v_mfma_i32_16x16x64_i8 v[52:55], v[198:201], v[206:209], v[52:55]
	v_mfma_i32_16x16x64_i8 v[44:47], v[190:193], v[214:217], v[44:47]
	v_mfma_i32_16x16x64_i8 v[36:39], v[198:201], v[214:217], v[36:39]
	v_mfma_i32_16x16x64_i8 v[26:29], v[190:193], v[222:225], v[26:29]
	v_mfma_i32_16x16x64_i8 v[18:21], v[198:201], v[222:225], v[18:21]
	v_mfma_i32_16x16x64_i8 v[10:13], v[190:193], v[238:241], v[10:13]
	v_mfma_i32_16x16x64_i8 v[2:5], v[198:201], v[238:241], v[2:5]
	v_mfma_i32_16x16x64_i8 v[60:63], v[194:197], v[210:213], v[60:63]
	v_mfma_i32_16x16x64_i8 v[52:55], v[202:205], v[210:213], v[52:55]
	v_mfma_i32_16x16x64_i8 v[44:47], v[194:197], v[218:221], v[44:47]
	v_mfma_i32_16x16x64_i8 v[36:39], v[202:205], v[218:221], v[36:39]
	v_mfma_i32_16x16x64_i8 v[26:29], v[194:197], v[234:237], v[26:29]
	v_mfma_i32_16x16x64_i8 v[18:21], v[202:205], v[234:237], v[18:21]
	v_mfma_i32_16x16x64_i8 v[10:13], v[194:197], v[242:245], v[10:13]
	v_mfma_i32_16x16x64_i8 v[2:5], v[202:205], v[242:245], v[2:5]
	s_setprio 0
	s_barrier
; #define PG8_STAGE(bufoff, gbase, voff) do { _Pragma("unroll") for (int _i = 0; _i < 2; ++_i) \
;         __builtin_amdgcn_global_load_lds((const unsigned*)((const char*)(gbase) + (voff)[_i]), (PG8_LAS unsigned*)(lds + (bufoff) + ldsw + _i * 8192), 16, 0, 0); } while (0)
; #define PG8_LDA(dst, b, h) do { _Pragma("unroll") for (int m = 0; m < 4; ++m) _Pragma("unroll") for (int k = 0; k < 2; ++k) dst[m][k] = *(const PG8_LAS bf16x8*)(lds + PG8_SA(b, h) + aoff + m * 2048 + k * 1024); } while (0)
; #define PG8_LDB(dst, b, h) do { _Pragma("unroll") for (int n = 0; n < 2; ++n) _Pragma("unroll") for (int k = 0; k < 2; ++k) dst[n][k] = *(const PG8_LAS bf16x8*)(lds + PG8_SB(b, h) + boff + n * 2048 + k * 1024); } while (0)
; #define PG8_WAIT_V(n) asm volatile("s_waitcnt vmcnt(" #n ")" ::: "memory")
; #define PG8_WAIT_L(n) asm volatile("s_waitcnt lgkmcnt(" #n ")" ::: "memory")
; #define PG8_BAR __builtin_amdgcn_s_barrier()
; #define PG8_SCHED __builtin_amdgcn_sched_barrier(0)
;     ...
;             PG8_LDB(B0, 1, 0); PG8_LDB(B1, 1, 1); PG8_SCHED; PG8_LDA(At, 1, 0); PG8_STAGE(PG8_SA(0, 1), a2 + hstepA, voffA);
;             PG8_WAIT_V(8); PG8_WAIT_L(0); PG8_BAR; PG8_MMA(0, 0, At, B0); PG8_MMA(0, 1, At, B1); PG8_BAR; PG8_SCHED;
	s_add_i32 s63, 0, 0x18000
	s_add_i32 s68, 0, 0x1c000
	ds_read_b128 v[142:145], v162 offset:32768
	ds_read_b128 v[146:149], v162 offset:33792
	ds_read_b128 v[158:161], v162 offset:34816
	ds_read_b128 v[186:189], v162 offset:35840
	ds_read_b128 v[190:193], v162 offset:49152
	ds_read_b128 v[194:197], v162 offset:50176
	ds_read_b128 v[198:201], v162 offset:51200
	ds_read_b128 v[202:205], v162 offset:52224
	s_add_u32 s70, s74, 0x40000
	s_addc_u32 s71, s75, 0
	s_mov_b32 m0, s83
	ds_read_b128 v[206:209], v156 offset:32768
	ds_read_b128 v[210:213], v156 offset:33792
	ds_read_b128 v[214:217], v156 offset:34816
	ds_read_b128 v[218:221], v156 offset:35840
	ds_read_b128 v[222:225], v156 offset:36864
	ds_read_b128 v[234:237], v156 offset:37888
	ds_read_b128 v[238:241], v156 offset:38912
	ds_read_b128 v[242:245], v156 offset:39936
	global_load_lds_dwordx4 v132, s[70:71]
	s_mov_b32 m0, s84
	s_nop 0
	global_load_lds_dwordx4 v134, s[70:71]
	s_waitcnt vmcnt(8)
	s_waitcnt lgkmcnt(0)
	s_barrier
	s_setprio 1
	v_mfma_i32_16x16x64_i8 v[128:131], v[142:145], v[206:209], v[128:131]
	v_mfma_i32_16x16x64_i8 v[120:123], v[158:161], v[206:209], v[120:123]
	v_mfma_i32_16x16x64_i8 v[112:115], v[142:145], v[214:217], v[112:115]
	v_mfma_i32_16x16x64_i8 v[104:107], v[158:161], v[214:217], v[104:107]
	v_mfma_i32_16x16x64_i8 v[96:99], v[142:145], v[222:225], v[96:99]
	v_mfma_i32_16x16x64_i8 v[88:91], v[158:161], v[222:225], v[88:91]
	v_mfma_i32_16x16x64_i8 v[80:83], v[142:145], v[238:241], v[80:83]
	v_mfma_i32_16x16x64_i8 v[72:75], v[158:161], v[238:241], v[72:75]
	v_mfma_i32_16x16x64_i8 v[128:131], v[146:149], v[210:213], v[128:131]
	v_mfma_i32_16x16x64_i8 v[120:123], v[186:189], v[210:213], v[120:123]
	v_mfma_i32_16x16x64_i8 v[112:115], v[146:149], v[218:221], v[112:115]
	v_mfma_i32_16x16x64_i8 v[104:107], v[186:189], v[218:221], v[104:107]
	v_mfma_i32_16x16x64_i8 v[96:99], v[146:149], v[234:237], v[96:99]
	v_mfma_i32_16x16x64_i8 v[88:91], v[186:189], v[234:237], v[88:91]
	v_mfma_i32_16x16x64_i8 v[80:83], v[146:149], v[242:245], v[80:83]
	v_mfma_i32_16x16x64_i8 v[72:75], v[186:189], v[242:245], v[72:75]
	v_mfma_i32_16x16x64_i8 v[124:127], v[190:193], v[206:209], v[124:127]
	v_mfma_i32_16x16x64_i8 v[116:119], v[198:201], v[206:209], v[116:119]
	v_mfma_i32_16x16x64_i8 v[108:111], v[190:193], v[214:217], v[108:111]
	v_mfma_i32_16x16x64_i8 v[100:103], v[198:201], v[214:217], v[100:103]
	v_mfma_i32_16x16x64_i8 v[92:95], v[190:193], v[222:225], v[92:95]
	v_mfma_i32_16x16x64_i8 v[84:87], v[198:201], v[222:225], v[84:87]
	v_mfma_i32_16x16x64_i8 v[76:79], v[190:193], v[238:241], v[76:79]
	v_mfma_i32_16x16x64_i8 v[68:71], v[198:201], v[238:241], v[68:71]
	v_mfma_i32_16x16x64_i8 v[124:127], v[194:197], v[210:213], v[124:127]
	v_mfma_i32_16x16x64_i8 v[116:119], v[202:205], v[210:213], v[116:119]
	v_mfma_i32_16x16x64_i8 v[108:111], v[194:197], v[218:221], v[108:111]
	v_mfma_i32_16x16x64_i8 v[100:103], v[202:205], v[218:221], v[100:103]
	v_mfma_i32_16x16x64_i8 v[92:95], v[194:197], v[234:237], v[92:95]
	v_mfma_i32_16x16x64_i8 v[84:87], v[202:205], v[234:237], v[84:87]
	v_mfma_i32_16x16x64_i8 v[76:79], v[194:197], v[242:245], v[76:79]
	v_mfma_i32_16x16x64_i8 v[68:71], v[202:205], v[242:245], v[68:71]
	s_setprio 0
	s_barrier
; #define PG8_STAGE(bufoff, gbase, voff) do { _Pragma("unroll") for (int _i = 0; _i < 2; ++_i) \
;         __builtin_amdgcn_global_load_lds((const unsigned*)((const char*)(gbase) + (voff)[_i]), (PG8_LAS unsigned*)(lds + (bufoff) + ldsw + _i * 8192), 16, 0, 0); } while (0)
; #define PG8_LDA(dst, b, h) do { _Pragma("unroll") for (int m = 0; m < 4; ++m) _Pragma("unroll") for (int k = 0; k < 2; ++k) dst[m][k] = *(const PG8_LAS bf16x8*)(lds + PG8_SA(b, h) + aoff + m * 2048 + k * 1024); } while (0)
; #define PG8_WAIT_V(n) asm volatile("s_waitcnt vmcnt(" #n ")" ::: "memory")
; #define PG8_WAIT_L(n) asm volatile("s_waitcnt lgkmcnt(" #n ")" ::: "memory")
; #define PG8_BAR __builtin_amdgcn_s_barrier()
; #define PG8_SCHED __builtin_amdgcn_sched_barrier(0)
;     __device__ __forceinline__ void operator()(const f32x4 (&acc)[2][2][4][2], const Unit& u, int wr, int wc, int fr, int fq) const {
;     ...
;             for (int m = 0; m < 4; ++m) { const size_t ro = (size_t)(row0 + ai * HALF + m * 16) * ldc + col0;
;                 float r[8]; const float scr_ = rs ? rs[row0 + ai * HALF + m * 16] * sc : sc;
;     ...
;             PG8_LDA(At, 1, 1); PG8_STAGE(PG8_SB(1, 0), b3, voffB); PG8_STAGE(PG8_SB(1, 1), b3 + hstepB, voffB); PG8_STAGE(PG8_SA(1, 0), a3, voffA);
;             PG8_WAIT_V(8); PG8_WAIT_L(0); PG8_BAR; PG8_MMA(1, 0, At, B0); PG8_MMA(1, 1, At, B1); PG8_BAR; PG8_SCHED;
	s_add_i32 s63, s63, s10
	s_mov_b32 m0, s63
	ds_read_b128 v[206:209], v156 offset:49152
	ds_read_b128 v[210:213], v156 offset:50176
	ds_read_b128 v[214:217], v156 offset:51200
	ds_read_b128 v[218:221], v156 offset:52224
	ds_read_b128 v[222:225], v156 offset:53248
	ds_read_b128 v[234:237], v156 offset:54272
	ds_read_b128 v[238:241], v156 offset:55296
	ds_read_b128 v[242:245], v156 offset:56320
	s_add_u32 vcc_lo, s66, 0x80
	s_addc_u32 vcc_hi, s67, 0
	global_load_lds_dwordx4 v34, vcc
	s_add_i32 m0, s63, 0x2000
	s_add_u32 s66, s66, 0x40080
	s_addc_u32 s67, s67, 0
	s_add_i32 s63, s68, s10
	s_add_u32 vcc_lo, s66, 0xfffc0000
	s_addc_u32 vcc_hi, s67, -1
	global_load_lds_dwordx4 v136, vcc
	s_mov_b32 m0, s63
	s_nop 0
	global_load_lds_dwordx4 v34, s[66:67]
	s_add_i32 m0, s63, 0x2000
	s_nop 0
	global_load_lds_dwordx4 v136, s[66:67]
	s_mov_b32 m0, s86
	s_nop 0
	s_add_u32 vcc_lo, s74, 0x80
	s_addc_u32 vcc_hi, s75, 0
	global_load_lds_dwordx4 v132, vcc
	s_mov_b32 m0, s87
	s_nop 0
	s_add_u32 vcc_lo, s74, 0x80
	s_addc_u32 vcc_hi, s75, 0
	global_load_lds_dwordx4 v134, vcc
	s_waitcnt vmcnt(8)
	s_waitcnt lgkmcnt(0)
	s_barrier
	s_setprio 1
	v_mfma_i32_16x16x64_i8 v[64:67], v[142:145], v[206:209], v[64:67]
	v_mfma_i32_16x16x64_i8 v[56:59], v[158:161], v[206:209], v[56:59]
	v_mfma_i32_16x16x64_i8 v[48:51], v[142:145], v[214:217], v[48:51]
	v_mfma_i32_16x16x64_i8 v[40:43], v[158:161], v[214:217], v[40:43]
	v_mfma_i32_16x16x64_i8 v[30:33], v[142:145], v[222:225], v[30:33]
	v_mfma_i32_16x16x64_i8 v[22:25], v[158:161], v[222:225], v[22:25]
	v_mfma_i32_16x16x64_i8 v[14:17], v[142:145], v[238:241], v[14:17]
	v_mfma_i32_16x16x64_i8 v[6:9], v[158:161], v[238:241], v[6:9]
	v_mfma_i32_16x16x64_i8 v[64:67], v[146:149], v[210:213], v[64:67]
	v_mfma_i32_16x16x64_i8 v[56:59], v[186:189], v[210:213], v[56:59]
	v_mfma_i32_16x16x64_i8 v[48:51], v[146:149], v[218:221], v[48:51]
	v_mfma_i32_16x16x64_i8 v[40:43], v[186:189], v[218:221], v[40:43]
	v_mfma_i32_16x16x64_i8 v[30:33], v[146:149], v[234:237], v[30:33]
	v_mfma_i32_16x16x64_i8 v[22:25], v[186:189], v[234:237], v[22:25]
	v_mfma_i32_16x16x64_i8 v[14:17], v[146:149], v[242:245], v[14:17]
	v_mfma_i32_16x16x64_i8 v[6:9], v[186:189], v[242:245], v[6:9]
	v_mfma_i32_16x16x64_i8 v[60:63], v[190:193], v[206:209], v[60:63]
	v_mfma_i32_16x16x64_i8 v[52:55], v[198:201], v[206:209], v[52:55]
	v_mfma_i32_16x16x64_i8 v[44:47], v[190:193], v[214:217], v[44:47]
	v_mfma_i32_16x16x64_i8 v[36:39], v[198:201], v[214:217], v[36:39]
	v_mfma_i32_16x16x64_i8 v[26:29], v[190:193], v[222:225], v[26:29]
	v_mfma_i32_16x16x64_i8 v[18:21], v[198:201], v[222:225], v[18:21]
	v_mfma_i32_16x16x64_i8 v[10:13], v[190:193], v[238:241], v[10:13]
	v_mfma_i32_16x16x64_i8 v[2:5], v[198:201], v[238:241], v[2:5]
	v_mfma_i32_16x16x64_i8 v[60:63], v[194:197], v[210:213], v[60:63]
	v_mfma_i32_16x16x64_i8 v[52:55], v[202:205], v[210:213], v[52:55]
	v_mfma_i32_16x16x64_i8 v[44:47], v[194:197], v[218:221], v[44:47]
	v_mfma_i32_16x16x64_i8 v[36:39], v[202:205], v[218:221], v[36:39]
	v_mfma_i32_16x16x64_i8 v[26:29], v[194:197], v[234:237], v[26:29]
	v_mfma_i32_16x16x64_i8 v[18:21], v[202:205], v[234:237], v[18:21]
	v_mfma_i32_16x16x64_i8 v[10:13], v[194:197], v[242:245], v[10:13]
	v_mfma_i32_16x16x64_i8 v[2:5], v[202:205], v[242:245], v[2:5]
	s_setprio 0
	s_barrier
	s_add_i32 s57, s57, 2
	s_add_u32 s64, s64, 0x100
	s_addc_u32 s65, s65, 0
	s_add_u32 s45, s45, 0x100
	s_addc_u32 s55, s55, 0
	s_cmp_gt_u32 s57, 13
	s_cbranch_scc0 .LBB0_538
	v_lshl_add_u32 v144, s62, 8, v152
	v_ashrrev_i32_e32 v145, 31, v144
	v_lshl_add_u64 v[146:147], v[144:145], 2, s[50:51]
	global_load_dword v186, v[146:147], off
	global_load_dword v187, v[146:147], off offset:64
	global_load_dword v188, v[146:147], off offset:128
	global_load_dword v189, v[146:147], off offset:192
	global_load_dword v190, v[146:147], off offset:512
	global_load_dword v191, v[146:147], off offset:576
	global_load_dword v192, v[146:147], off offset:640
	global_load_dword v193, v[146:147], off offset:704
	s_and_b64 vcc, exec, s[52:53]
	s_cbranch_vccz .LBB0_541
	s_barrier

; #define PG8_STAGE(bufoff, gbase, voff) do { _Pragma("unroll") for (int _i = 0; _i < 2; ++_i) \
;         __builtin_amdgcn_global_load_lds((const unsigned*)((const char*)(gbase) + (voff)[_i]), (PG8_LAS unsigned*)(lds + (bufoff) + ldsw + _i * 8192), 16, 0, 0); } while (0)
; #define PG8_LDA(dst, b, h) do { _Pragma("unroll") for (int m = 0; m < 4; ++m) _Pragma("unroll") for (int k = 0; k < 2; ++k) dst[m][k] = *(const PG8_LAS bf16x8*)(lds + PG8_SA(b, h) + aoff + m * 2048 + k * 1024); } while (0)
; #define PG8_LDB(dst, b, h) do { _Pragma("unroll") for (int n = 0; n < 2; ++n) _Pragma("unroll") for (int k = 0; k < 2; ++k) dst[n][k] = *(const PG8_LAS bf16x8*)(lds + PG8_SB(b, h) + boff + n * 2048 + k * 1024); } while (0)
; #define PG8_WAIT_V(n) asm volatile("s_waitcnt vmcnt(" #n ")" ::: "memory")
; #define PG8_WAIT_L(n) asm volatile("s_waitcnt lgkmcnt(" #n ")" ::: "memory")
; #define PG8_BAR __builtin_amdgcn_s_barrier()
; #define PG8_SCHED __builtin_amdgcn_sched_barrier(0)
;     ...
;             const bool last = (t == nt - 2);
;             const char* a1 = cA + (size_t)(t + 1) * kstep;
;             const char* a2 = last ? nA : cA + (size_t)(t + 2) * kstep; const char* b2 = last ? nB : cB + (size_t)(t + 2) * kstep;
;             const char* a3 = a2 + kstep; const char* b3 = b2 + kstep;
;             if (last && has_next) S.a_ready(nxt);
;             if constexpr (SP2) {
;             PG8_LDB(B0, 0, 0); PG8_LDB(B1, 0, 1); PG8_SCHED; PG8_LDA(At, 0, 0); PG8_STAGE(PG8_SA(1, 1), a1 + hstepA, voffA);
;             PG8_WAIT_V(8); PG8_WAIT_L(0); PG8_BAR; PG8_MMA(0, 0, At, B0); PG8_MMA(0, 1, At, B1); PG8_BAR; PG8_SCHED;
;             PG8_LDA(At, 0, 1); PG8_STAGE(PG8_SB(0, 0), b2, voffB); PG8_STAGE(PG8_SB(0, 1), b2 + hstepB, voffB); PG8_STAGE(PG8_SA(0, 0), a2, voffA);
;             PG8_WAIT_V(8); PG8_WAIT_L(0); PG8_BAR; PG8_MMA(1, 0, At, B0); PG8_MMA(1, 1, At, B1); PG8_BAR; PG8_SCHED;
.LBB0_608:
	v_add_u32_e32 v226, 0x10000, v145
	s_add_u32 s52, s50, 0xfff80080
	s_addc_u32 s53, s51, -1
	s_add_i32 s63, 0, 0x10000
	s_cmp_eq_u32 s62, 28
	s_cselect_b32 s55, s37, s53
	s_cselect_b32 s54, s58, s52
	s_cselect_b32 s53, s31, s61
	s_cselect_b32 s52, s59, s60
	s_add_i32 s66, 0, 0x14000
	ds_read_b128 v[148:151], v226
	ds_read_b128 v[152:155], v226 offset:1024
	ds_read_b128 v[156:159], v226 offset:2048
	ds_read_b128 v[160:163], v226 offset:3072
	ds_read_b128 v[186:189], v226 offset:16384
	ds_read_b128 v[190:193], v226 offset:17408
	ds_read_b128 v[194:197], v226 offset:18432
	ds_read_b128 v[198:201], v226 offset:19456
	s_add_i32 m0, s12, 0xc000
	ds_read_b128 v[202:205], v147
	ds_read_b128 v[206:209], v147 offset:1024
	ds_read_b128 v[210:213], v147 offset:2048
	ds_read_b128 v[214:217], v147 offset:3072
	ds_read_b128 v[218:221], v147 offset:4096
	ds_read_b128 v[222:225], v147 offset:5120
	ds_read_b128 v[234:237], v147 offset:6144
	ds_read_b128 v[238:241], v147 offset:7168
	global_load_lds_dwordx4 v138, s[50:51]
	s_add_i32 m0, s12, 0xe000
	s_nop 0
	global_load_lds_dwordx4 v140, s[50:51]
	s_waitcnt vmcnt(8)
	s_waitcnt lgkmcnt(0)
	s_barrier
	s_setprio 1
	v_mfma_f32_16x16x32_bf16 v[128:131], v[148:151], v[202:205], v[128:131]
	v_mfma_f32_16x16x32_bf16 v[124:127], v[156:159], v[202:205], v[124:127]
	v_mfma_f32_16x16x32_bf16 v[112:115], v[148:151], v[210:213], v[112:115]
	v_mfma_f32_16x16x32_bf16 v[108:111], v[156:159], v[210:213], v[108:111]
	v_mfma_f32_16x16x32_bf16 v[96:99], v[148:151], v[218:221], v[96:99]
	v_mfma_f32_16x16x32_bf16 v[92:95], v[156:159], v[218:221], v[92:95]
	v_mfma_f32_16x16x32_bf16 v[80:83], v[148:151], v[234:237], v[80:83]
	v_mfma_f32_16x16x32_bf16 v[76:79], v[156:159], v[234:237], v[76:79]
	v_mfma_f32_16x16x32_bf16 v[128:131], v[152:155], v[206:209], v[128:131]
	v_mfma_f32_16x16x32_bf16 v[124:127], v[160:163], v[206:209], v[124:127]
	v_mfma_f32_16x16x32_bf16 v[112:115], v[152:155], v[214:217], v[112:115]
	v_mfma_f32_16x16x32_bf16 v[108:111], v[160:163], v[214:217], v[108:111]
	v_mfma_f32_16x16x32_bf16 v[96:99], v[152:155], v[222:225], v[96:99]
	v_mfma_f32_16x16x32_bf16 v[92:95], v[160:163], v[222:225], v[92:95]
	v_mfma_f32_16x16x32_bf16 v[80:83], v[152:155], v[238:241], v[80:83]
	v_mfma_f32_16x16x32_bf16 v[76:79], v[160:163], v[238:241], v[76:79]
	v_mfma_f32_16x16x32_bf16 v[120:123], v[186:189], v[202:205], v[120:123]
	v_mfma_f32_16x16x32_bf16 v[116:119], v[194:197], v[202:205], v[116:119]
	v_mfma_f32_16x16x32_bf16 v[104:107], v[186:189], v[210:213], v[104:107]
	v_mfma_f32_16x16x32_bf16 v[100:103], v[194:197], v[210:213], v[100:103]
	v_mfma_f32_16x16x32_bf16 v[88:91], v[186:189], v[218:221], v[88:91]
	v_mfma_f32_16x16x32_bf16 v[84:87], v[194:197], v[218:221], v[84:87]
	v_mfma_f32_16x16x32_bf16 v[72:75], v[186:189], v[234:237], v[72:75]
	v_mfma_f32_16x16x32_bf16 v[68:71], v[194:197], v[234:237], v[68:71]
	v_mfma_f32_16x16x32_bf16 v[120:123], v[190:193], v[206:209], v[120:123]
	v_mfma_f32_16x16x32_bf16 v[116:119], v[198:201], v[206:209], v[116:119]
	v_mfma_f32_16x16x32_bf16 v[104:107], v[190:193], v[214:217], v[104:107]
	v_mfma_f32_16x16x32_bf16 v[100:103], v[198:201], v[214:217], v[100:103]
	v_mfma_f32_16x16x32_bf16 v[88:91], v[190:193], v[222:225], v[88:91]
	v_mfma_f32_16x16x32_bf16 v[84:87], v[198:201], v[222:225], v[84:87]
	v_mfma_f32_16x16x32_bf16 v[72:75], v[190:193], v[238:241], v[72:75]
	v_mfma_f32_16x16x32_bf16 v[68:71], v[198:201], v[238:241], v[68:71]
	s_setprio 0
	s_barrier
	s_add_i32 s63, s63, s6
	s_mov_b32 m0, s63
	ds_read_b128 v[202:205], v147 offset:16384
	ds_read_b128 v[206:209], v147 offset:17408
	ds_read_b128 v[210:213], v147 offset:18432
	ds_read_b128 v[214:217], v147 offset:19456
	ds_read_b128 v[218:221], v147 offset:20480
	ds_read_b128 v[222:225], v147 offset:21504
	ds_read_b128 v[234:237], v147 offset:22528
	ds_read_b128 v[238:241], v147 offset:23552
	global_load_lds_dwordx4 v34, s[52:53]
	s_add_i32 m0, s63, 0x2000
	s_add_u32 s64, s52, 0x80000
	s_addc_u32 s65, s53, 0
	s_add_i32 s63, s66, s6
	global_load_lds_dwordx4 v132, s[52:53]
	s_mov_b32 m0, s63
	s_add_u32 s98, s54, 0x80
	s_addc_u32 s99, s55, 0
	global_load_lds_dwordx4 v34, s[64:65]
	s_add_i32 m0, s63, 0x2000
	s_nop 0
	global_load_lds_dwordx4 v132, s[64:65]
	s_mov_b32 m0, s12
	s_nop 0
	global_load_lds_dwordx4 v136, s[54:55]
	s_mov_b32 m0, s13
	s_nop 0
	global_load_lds_dwordx4 v134, s[54:55]
	s_waitcnt vmcnt(8)
	s_waitcnt lgkmcnt(0)
	s_barrier
	s_setprio 1
	v_mfma_f32_16x16x32_bf16 v[64:67], v[148:151], v[202:205], v[64:67]
	v_mfma_f32_16x16x32_bf16 v[60:63], v[156:159], v[202:205], v[60:63]
	v_mfma_f32_16x16x32_bf16 v[48:51], v[148:151], v[210:213], v[48:51]
	v_mfma_f32_16x16x32_bf16 v[44:47], v[156:159], v[210:213], v[44:47]
	v_mfma_f32_16x16x32_bf16 v[30:33], v[148:151], v[218:221], v[30:33]
	v_mfma_f32_16x16x32_bf16 v[26:29], v[156:159], v[218:221], v[26:29]
	v_mfma_f32_16x16x32_bf16 v[14:17], v[148:151], v[234:237], v[14:17]
	v_mfma_f32_16x16x32_bf16 v[10:13], v[156:159], v[234:237], v[10:13]
	v_mfma_f32_16x16x32_bf16 v[64:67], v[152:155], v[206:209], v[64:67]
	v_mfma_f32_16x16x32_bf16 v[60:63], v[160:163], v[206:209], v[60:63]
	v_mfma_f32_16x16x32_bf16 v[48:51], v[152:155], v[214:217], v[48:51]
	v_mfma_f32_16x16x32_bf16 v[44:47], v[160:163], v[214:217], v[44:47]
	v_mfma_f32_16x16x32_bf16 v[30:33], v[152:155], v[222:225], v[30:33]
	v_mfma_f32_16x16x32_bf16 v[26:29], v[160:163], v[222:225], v[26:29]
	v_mfma_f32_16x16x32_bf16 v[14:17], v[152:155], v[238:241], v[14:17]
	v_mfma_f32_16x16x32_bf16 v[10:13], v[160:163], v[238:241], v[10:13]
	v_mfma_f32_16x16x32_bf16 v[56:59], v[186:189], v[202:205], v[56:59]
	v_mfma_f32_16x16x32_bf16 v[52:55], v[194:197], v[202:205], v[52:55]
	v_mfma_f32_16x16x32_bf16 v[40:43], v[186:189], v[210:213], v[40:43]
	v_mfma_f32_16x16x32_bf16 v[36:39], v[194:197], v[210:213], v[36:39]
	v_mfma_f32_16x16x32_bf16 v[22:25], v[186:189], v[218:221], v[22:25]
	v_mfma_f32_16x16x32_bf16 v[18:21], v[194:197], v[218:221], v[18:21]
	v_mfma_f32_16x16x32_bf16 v[6:9], v[186:189], v[234:237], v[6:9]
	v_mfma_f32_16x16x32_bf16 v[2:5], v[194:197], v[234:237], v[2:5]
	v_mfma_f32_16x16x32_bf16 v[56:59], v[190:193], v[206:209], v[56:59]
	v_mfma_f32_16x16x32_bf16 v[52:55], v[198:201], v[206:209], v[52:55]
	v_mfma_f32_16x16x32_bf16 v[40:43], v[190:193], v[214:217], v[40:43]
	v_mfma_f32_16x16x32_bf16 v[36:39], v[198:201], v[214:217], v[36:39]
	v_mfma_f32_16x16x32_bf16 v[22:25], v[190:193], v[222:225], v[22:25]
	v_mfma_f32_16x16x32_bf16 v[18:21], v[198:201], v[222:225], v[18:21]
	v_mfma_f32_16x16x32_bf16 v[6:9], v[190:193], v[238:241], v[6:9]
	v_mfma_f32_16x16x32_bf16 v[2:5], v[198:201], v[238:241], v[2:5]
	s_setprio 0
	s_barrier
; #define PG8_STAGE(bufoff, gbase, voff) do { _Pragma("unroll") for (int _i = 0; _i < 2; ++_i) \
;         __builtin_amdgcn_global_load_lds((const unsigned*)((const char*)(gbase) + (voff)[_i]), (PG8_LAS unsigned*)(lds + (bufoff) + ldsw + _i * 8192), 16, 0, 0); } while (0)
; #define PG8_LDA(dst, b, h) do { _Pragma("unroll") for (int m = 0; m < 4; ++m) _Pragma("unroll") for (int k = 0; k < 2; ++k) dst[m][k] = *(const PG8_LAS bf16x8*)(lds + PG8_SA(b, h) + aoff + m * 2048 + k * 1024); } while (0)
; #define PG8_LDB(dst, b, h) do { _Pragma("unroll") for (int n = 0; n < 2; ++n) _Pragma("unroll") for (int k = 0; k < 2; ++k) dst[n][k] = *(const PG8_LAS bf16x8*)(lds + PG8_SB(b, h) + boff + n * 2048 + k * 1024); } while (0)
; #define PG8_WAIT_V(n) asm volatile("s_waitcnt vmcnt(" #n ")" ::: "memory")
; #define PG8_WAIT_L(n) asm volatile("s_waitcnt lgkmcnt(" #n ")" ::: "memory")
; #define PG8_BAR __builtin_amdgcn_s_barrier()
; #define PG8_SCHED __builtin_amdgcn_sched_barrier(0)
;     ...
;             PG8_LDB(B0, 1, 0); PG8_LDB(B1, 1, 1); PG8_SCHED; PG8_LDA(At, 1, 0); PG8_STAGE(PG8_SA(0, 1), a2 + hstepA, voffA);
;             PG8_WAIT_V(8); PG8_WAIT_L(0); PG8_BAR; PG8_MMA(0, 0, At, B0); PG8_MMA(0, 1, At, B1); PG8_BAR; PG8_SCHED;
;             PG8_LDA(At, 1, 1); PG8_STAGE(PG8_SB(1, 0), b3, voffB); PG8_STAGE(PG8_SB(1, 1), b3 + hstepB, voffB); PG8_STAGE(PG8_SA(1, 0), a3, voffA);
;             PG8_WAIT_V(8); PG8_WAIT_L(0); PG8_BAR; PG8_MMA(1, 0, At, B0); PG8_MMA(1, 1, At, B1); PG8_BAR; PG8_SCHED;
	s_add_i32 s63, 0, 0x18000
	s_add_i32 s64, 0, 0x1c000
	ds_read_b128 v[148:151], v226 offset:32768
	ds_read_b128 v[152:155], v226 offset:33792
	ds_read_b128 v[156:159], v226 offset:34816
	ds_read_b128 v[160:163], v226 offset:35840
	ds_read_b128 v[186:189], v226 offset:49152
	ds_read_b128 v[190:193], v226 offset:50176
	ds_read_b128 v[194:197], v226 offset:51200
	ds_read_b128 v[198:201], v226 offset:52224
	s_add_u32 s54, s54, 0x80000
	s_addc_u32 s55, s55, 0
	s_mov_b32 m0, s15
	ds_read_b128 v[202:205], v147 offset:32768
	ds_read_b128 v[206:209], v147 offset:33792
	ds_read_b128 v[210:213], v147 offset:34816
	ds_read_b128 v[214:217], v147 offset:35840
	ds_read_b128 v[218:221], v147 offset:36864
	ds_read_b128 v[222:225], v147 offset:37888
	ds_read_b128 v[234:237], v147 offset:38912
	ds_read_b128 v[238:241], v147 offset:39936
	global_load_lds_dwordx4 v136, s[54:55]
	s_mov_b32 m0, s34
	s_nop 0
	global_load_lds_dwordx4 v134, s[54:55]
	s_waitcnt vmcnt(8)
	s_waitcnt lgkmcnt(0)
	s_barrier
	s_setprio 1
	v_mfma_f32_16x16x32_bf16 v[128:131], v[148:151], v[202:205], v[128:131]
	v_mfma_f32_16x16x32_bf16 v[124:127], v[156:159], v[202:205], v[124:127]
	v_mfma_f32_16x16x32_bf16 v[112:115], v[148:151], v[210:213], v[112:115]
	v_mfma_f32_16x16x32_bf16 v[108:111], v[156:159], v[210:213], v[108:111]
	v_mfma_f32_16x16x32_bf16 v[96:99], v[148:151], v[218:221], v[96:99]
	v_mfma_f32_16x16x32_bf16 v[92:95], v[156:159], v[218:221], v[92:95]
	v_mfma_f32_16x16x32_bf16 v[80:83], v[148:151], v[234:237], v[80:83]
	v_mfma_f32_16x16x32_bf16 v[76:79], v[156:159], v[234:237], v[76:79]
	v_mfma_f32_16x16x32_bf16 v[128:131], v[152:155], v[206:209], v[128:131]
	v_mfma_f32_16x16x32_bf16 v[124:127], v[160:163], v[206:209], v[124:127]
	v_mfma_f32_16x16x32_bf16 v[112:115], v[152:155], v[214:217], v[112:115]
	v_mfma_f32_16x16x32_bf16 v[108:111], v[160:163], v[214:217], v[108:111]
	v_mfma_f32_16x16x32_bf16 v[96:99], v[152:155], v[222:225], v[96:99]
	v_mfma_f32_16x16x32_bf16 v[92:95], v[160:163], v[222:225], v[92:95]
	v_mfma_f32_16x16x32_bf16 v[80:83], v[152:155], v[238:241], v[80:83]
	v_mfma_f32_16x16x32_bf16 v[76:79], v[160:163], v[238:241], v[76:79]
	v_mfma_f32_16x16x32_bf16 v[120:123], v[186:189], v[202:205], v[120:123]
	v_mfma_f32_16x16x32_bf16 v[116:119], v[194:197], v[202:205], v[116:119]
	v_mfma_f32_16x16x32_bf16 v[104:107], v[186:189], v[210:213], v[104:107]
	v_mfma_f32_16x16x32_bf16 v[100:103], v[194:197], v[210:213], v[100:103]
	v_mfma_f32_16x16x32_bf16 v[88:91], v[186:189], v[218:221], v[88:91]
	v_mfma_f32_16x16x32_bf16 v[84:87], v[194:197], v[218:221], v[84:87]
	v_mfma_f32_16x16x32_bf16 v[72:75], v[186:189], v[234:237], v[72:75]
	v_mfma_f32_16x16x32_bf16 v[68:71], v[194:197], v[234:237], v[68:71]
	v_mfma_f32_16x16x32_bf16 v[120:123], v[190:193], v[206:209], v[120:123]
	v_mfma_f32_16x16x32_bf16 v[116:119], v[198:201], v[206:209], v[116:119]
	v_mfma_f32_16x16x32_bf16 v[104:107], v[190:193], v[214:217], v[104:107]
	v_mfma_f32_16x16x32_bf16 v[100:103], v[198:201], v[214:217], v[100:103]
	v_mfma_f32_16x16x32_bf16 v[88:91], v[190:193], v[222:225], v[88:91]
	v_mfma_f32_16x16x32_bf16 v[84:87], v[198:201], v[222:225], v[84:87]
	v_mfma_f32_16x16x32_bf16 v[72:75], v[190:193], v[238:241], v[72:75]
	v_mfma_f32_16x16x32_bf16 v[68:71], v[198:201], v[238:241], v[68:71]
	s_setprio 0
	s_barrier
	s_add_i32 s54, s63, s6
	s_mov_b32 m0, s54
	ds_read_b128 v[202:205], v147 offset:49152
	ds_read_b128 v[206:209], v147 offset:50176
	ds_read_b128 v[210:213], v147 offset:51200
	ds_read_b128 v[214:217], v147 offset:52224
	ds_read_b128 v[218:221], v147 offset:53248
	ds_read_b128 v[222:225], v147 offset:54272
	ds_read_b128 v[234:237], v147 offset:55296
	ds_read_b128 v[238:241], v147 offset:56320
	s_add_u32 vcc_lo, s52, 0x80
	s_addc_u32 vcc_hi, s53, 0
	global_load_lds_dwordx4 v34, vcc
	s_add_i32 m0, s54, 0x2000
	s_add_u32 s52, s52, 0x80080
	s_addc_u32 s53, s53, 0
	s_add_i32 s54, s64, s6
	s_add_u32 vcc_lo, s52, 0xfff80000
	s_addc_u32 vcc_hi, s53, -1
	global_load_lds_dwordx4 v132, vcc
	s_mov_b32 m0, s54
	s_nop 0
	global_load_lds_dwordx4 v34, s[52:53]
	s_add_i32 m0, s54, 0x2000
	s_nop 0
	global_load_lds_dwordx4 v132, s[52:53]
	s_mov_b32 m0, s24
	s_nop 0
	global_load_lds_dwordx4 v136, s[98:99]
	s_mov_b32 m0, s35
	s_nop 0
	global_load_lds_dwordx4 v134, s[98:99]
	s_waitcnt vmcnt(8)
	s_waitcnt lgkmcnt(0)
	s_barrier
	s_setprio 1
	v_mfma_f32_16x16x32_bf16 v[64:67], v[148:151], v[202:205], v[64:67]
	v_mfma_f32_16x16x32_bf16 v[60:63], v[156:159], v[202:205], v[60:63]
	v_mfma_f32_16x16x32_bf16 v[48:51], v[148:151], v[210:213], v[48:51]
	v_mfma_f32_16x16x32_bf16 v[44:47], v[156:159], v[210:213], v[44:47]
	v_mfma_f32_16x16x32_bf16 v[30:33], v[148:151], v[218:221], v[30:33]
	v_mfma_f32_16x16x32_bf16 v[26:29], v[156:159], v[218:221], v[26:29]
	v_mfma_f32_16x16x32_bf16 v[14:17], v[148:151], v[234:237], v[14:17]
	v_mfma_f32_16x16x32_bf16 v[10:13], v[156:159], v[234:237], v[10:13]
	v_mfma_f32_16x16x32_bf16 v[64:67], v[152:155], v[206:209], v[64:67]
	v_mfma_f32_16x16x32_bf16 v[60:63], v[160:163], v[206:209], v[60:63]
	v_mfma_f32_16x16x32_bf16 v[48:51], v[152:155], v[214:217], v[48:51]
	v_mfma_f32_16x16x32_bf16 v[44:47], v[160:163], v[214:217], v[44:47]
	v_mfma_f32_16x16x32_bf16 v[30:33], v[152:155], v[222:225], v[30:33]
	v_mfma_f32_16x16x32_bf16 v[26:29], v[160:163], v[222:225], v[26:29]
	v_mfma_f32_16x16x32_bf16 v[14:17], v[152:155], v[238:241], v[14:17]
	v_mfma_f32_16x16x32_bf16 v[10:13], v[160:163], v[238:241], v[10:13]
	v_mfma_f32_16x16x32_bf16 v[56:59], v[186:189], v[202:205], v[56:59]
	v_mfma_f32_16x16x32_bf16 v[52:55], v[194:197], v[202:205], v[52:55]
	v_mfma_f32_16x16x32_bf16 v[40:43], v[186:189], v[210:213], v[40:43]
	v_mfma_f32_16x16x32_bf16 v[36:39], v[194:197], v[210:213], v[36:39]
	v_mfma_f32_16x16x32_bf16 v[22:25], v[186:189], v[218:221], v[22:25]
	v_mfma_f32_16x16x32_bf16 v[18:21], v[194:197], v[218:221], v[18:21]
	v_mfma_f32_16x16x32_bf16 v[6:9], v[186:189], v[234:237], v[6:9]
	v_mfma_f32_16x16x32_bf16 v[2:5], v[194:197], v[234:237], v[2:5]
	v_mfma_f32_16x16x32_bf16 v[56:59], v[190:193], v[206:209], v[56:59]
	v_mfma_f32_16x16x32_bf16 v[52:55], v[198:201], v[206:209], v[52:55]
	v_mfma_f32_16x16x32_bf16 v[40:43], v[190:193], v[214:217], v[40:43]
	v_mfma_f32_16x16x32_bf16 v[36:39], v[198:201], v[214:217], v[36:39]
	v_mfma_f32_16x16x32_bf16 v[22:25], v[190:193], v[222:225], v[22:25]
	v_mfma_f32_16x16x32_bf16 v[18:21], v[198:201], v[222:225], v[18:21]
	v_mfma_f32_16x16x32_bf16 v[6:9], v[190:193], v[238:241], v[6:9]
	v_mfma_f32_16x16x32_bf16 v[2:5], v[198:201], v[238:241], v[2:5]
	s_setprio 0
	s_barrier
	s_add_i32 s62, s62, 2
	s_add_u32 s50, s50, 0x100
	s_addc_u32 s51, s51, 0
	s_add_u32 s60, s60, 0x100
	s_addc_u32 s61, s61, 0
	s_cmp_gt_u32 s62, 29
	s_cbranch_scc0 .LBB0_608
	s_and_b64 vcc, exec, s[28:29]
	s_cbranch_vccz .LBB0_611
	s_barrier

; #define PG8_STAGE(bufoff, gbase, voff) do { _Pragma("unroll") for (int _i = 0; _i < 2; ++_i) \
;         __builtin_amdgcn_global_load_lds((const unsigned*)((const char*)(gbase) + (voff)[_i]), (PG8_LAS unsigned*)(lds + (bufoff) + ldsw + _i * 8192), 16, 0, 0); } while (0)
; #define PG8_LDA(dst, b, h) do { _Pragma("unroll") for (int m = 0; m < 4; ++m) _Pragma("unroll") for (int k = 0; k < 2; ++k) dst[m][k] = *(const PG8_LAS bf16x8*)(lds + PG8_SA(b, h) + aoff + m * 2048 + k * 1024); } while (0)
; #define PG8_LDB(dst, b, h) do { _Pragma("unroll") for (int n = 0; n < 2; ++n) _Pragma("unroll") for (int k = 0; k < 2; ++k) dst[n][k] = *(const PG8_LAS bf16x8*)(lds + PG8_SB(b, h) + boff + n * 2048 + k * 1024); } while (0)
; #define PG8_WAIT_V(n) asm volatile("s_waitcnt vmcnt(" #n ")" ::: "memory")
; #define PG8_WAIT_L(n) asm volatile("s_waitcnt lgkmcnt(" #n ")" ::: "memory")
; #define PG8_BAR __builtin_amdgcn_s_barrier()
; #define PG8_SCHED __builtin_amdgcn_sched_barrier(0)
;     ...
;             const bool last = (t == nt - 2);
;             const char* a1 = cA + (size_t)(t + 1) * kstep;
;             const char* a2 = last ? nA : cA + (size_t)(t + 2) * kstep; const char* b2 = last ? nB : cB + (size_t)(t + 2) * kstep;
;             const char* a3 = a2 + kstep; const char* b3 = b2 + kstep;
;             if (last && has_next) S.a_ready(nxt);
;             if constexpr (SP2) {
;             PG8_LDB(B0, 0, 0); PG8_LDB(B1, 0, 1); PG8_SCHED; PG8_LDA(At, 0, 0); PG8_STAGE(PG8_SA(1, 1), a1 + hstepA, voffA);
;             PG8_WAIT_V(8); PG8_WAIT_L(0); PG8_BAR; PG8_MMA(0, 0, At, B0); PG8_MMA(0, 1, At, B1); PG8_BAR; PG8_SCHED;
;             PG8_LDA(At, 0, 1); PG8_STAGE(PG8_SB(0, 0), b2, voffB); PG8_STAGE(PG8_SB(0, 1), b2 + hstepB, voffB); PG8_STAGE(PG8_SA(0, 0), a2, voffA);
;             PG8_WAIT_V(8); PG8_WAIT_L(0); PG8_BAR; PG8_MMA(1, 0, At, B0); PG8_MMA(1, 1, At, B1); PG8_BAR; PG8_SCHED;
.LBB0_694:
	v_add_u32_e32 v163, 0x10000, v143
	s_add_u32 s44, s42, 0x100
	s_addc_u32 s45, s43, 0
	s_add_i32 s67, 0, 0x10000
	s_cmpk_eq_i32 s66, 0x54
	s_cselect_b32 s53, s37, s45
	s_cselect_b32 s52, s36, s44
	s_cselect_b32 s51, s41, s65
	s_cselect_b32 s50, s40, s64
	s_add_i32 s68, 0, 0x14000
	ds_read_b128 v[146:149], v163
	ds_read_b128 v[150:153], v163 offset:1024
	ds_read_b128 v[154:157], v163 offset:2048
	ds_read_b128 v[158:161], v163 offset:3072
	ds_read_b128 v[186:189], v163 offset:16384
	ds_read_b128 v[190:193], v163 offset:17408
	ds_read_b128 v[194:197], v163 offset:18432
	ds_read_b128 v[198:201], v163 offset:19456
	s_add_i32 m0, s34, 0xc000
	ds_read_b128 v[202:205], v145
	ds_read_b128 v[206:209], v145 offset:1024
	ds_read_b128 v[210:213], v145 offset:2048
	ds_read_b128 v[214:217], v145 offset:3072
	ds_read_b128 v[218:221], v145 offset:4096
	ds_read_b128 v[222:225], v145 offset:5120
	ds_read_b128 v[234:237], v145 offset:6144
	ds_read_b128 v[238:241], v145 offset:7168
	global_load_lds_dwordx4 v138, s[42:43]
	s_add_i32 m0, s34, 0xe000
	s_nop 0
	global_load_lds_dwordx4 v140, s[42:43]
	s_waitcnt vmcnt(8)
	s_waitcnt lgkmcnt(0)
	s_barrier
	s_setprio 1
	v_mfma_f32_16x16x32_bf16 v[128:131], v[146:149], v[202:205], v[128:131]
	v_mfma_f32_16x16x32_bf16 v[124:127], v[154:157], v[202:205], v[124:127]
	v_mfma_f32_16x16x32_bf16 v[120:123], v[146:149], v[210:213], v[120:123]
	v_mfma_f32_16x16x32_bf16 v[116:119], v[154:157], v[210:213], v[116:119]
	v_mfma_f32_16x16x32_bf16 v[104:107], v[146:149], v[218:221], v[104:107]
	v_mfma_f32_16x16x32_bf16 v[100:103], v[154:157], v[218:221], v[100:103]
	v_mfma_f32_16x16x32_bf16 v[88:91], v[146:149], v[234:237], v[88:91]
	v_mfma_f32_16x16x32_bf16 v[84:87], v[154:157], v[234:237], v[84:87]
	v_mfma_f32_16x16x32_bf16 v[128:131], v[150:153], v[206:209], v[128:131]
	v_mfma_f32_16x16x32_bf16 v[124:127], v[158:161], v[206:209], v[124:127]
	v_mfma_f32_16x16x32_bf16 v[120:123], v[150:153], v[214:217], v[120:123]
	v_mfma_f32_16x16x32_bf16 v[116:119], v[158:161], v[214:217], v[116:119]
	v_mfma_f32_16x16x32_bf16 v[104:107], v[150:153], v[222:225], v[104:107]
	v_mfma_f32_16x16x32_bf16 v[100:103], v[158:161], v[222:225], v[100:103]
	v_mfma_f32_16x16x32_bf16 v[88:91], v[150:153], v[238:241], v[88:91]
	v_mfma_f32_16x16x32_bf16 v[84:87], v[158:161], v[238:241], v[84:87]
	v_mfma_f32_16x16x32_bf16 v[112:115], v[186:189], v[202:205], v[112:115]
	v_mfma_f32_16x16x32_bf16 v[108:111], v[194:197], v[202:205], v[108:111]
	v_mfma_f32_16x16x32_bf16 v[96:99], v[186:189], v[210:213], v[96:99]
	v_mfma_f32_16x16x32_bf16 v[92:95], v[194:197], v[210:213], v[92:95]
	v_mfma_f32_16x16x32_bf16 v[80:83], v[186:189], v[218:221], v[80:83]
	v_mfma_f32_16x16x32_bf16 v[76:79], v[194:197], v[218:221], v[76:79]
	v_mfma_f32_16x16x32_bf16 v[72:75], v[186:189], v[234:237], v[72:75]
	v_mfma_f32_16x16x32_bf16 v[68:71], v[194:197], v[234:237], v[68:71]
	v_mfma_f32_16x16x32_bf16 v[112:115], v[190:193], v[206:209], v[112:115]
	v_mfma_f32_16x16x32_bf16 v[108:111], v[198:201], v[206:209], v[108:111]
	v_mfma_f32_16x16x32_bf16 v[96:99], v[190:193], v[214:217], v[96:99]
	v_mfma_f32_16x16x32_bf16 v[92:95], v[198:201], v[214:217], v[92:95]
	v_mfma_f32_16x16x32_bf16 v[80:83], v[190:193], v[222:225], v[80:83]
	v_mfma_f32_16x16x32_bf16 v[76:79], v[198:201], v[222:225], v[76:79]
	v_mfma_f32_16x16x32_bf16 v[72:75], v[190:193], v[238:241], v[72:75]
	v_mfma_f32_16x16x32_bf16 v[68:71], v[198:201], v[238:241], v[68:71]
	s_setprio 0
	s_barrier
	s_add_i32 s42, s67, s15
	s_mov_b32 m0, s42
	ds_read_b128 v[202:205], v145 offset:16384
	ds_read_b128 v[206:209], v145 offset:17408
	ds_read_b128 v[210:213], v145 offset:18432
	ds_read_b128 v[214:217], v145 offset:19456
	ds_read_b128 v[218:221], v145 offset:20480
	ds_read_b128 v[222:225], v145 offset:21504
	ds_read_b128 v[234:237], v145 offset:22528
	ds_read_b128 v[238:241], v145 offset:23552
	global_load_lds_dwordx4 v34, s[50:51]
	s_add_i32 m0, s42, 0x2000
	s_add_u32 s42, s50, 0x160000
	s_addc_u32 s43, s51, 0
	s_add_u32 s98, s50, 0x80
	s_addc_u32 s99, s51, 0
	s_add_i32 s67, s68, s15
	global_load_lds_dwordx4 v136, s[50:51]
	s_mov_b32 m0, s67
	s_nop 0
	global_load_lds_dwordx4 v34, s[42:43]
	s_add_i32 m0, s67, 0x2000
	s_nop 0
	global_load_lds_dwordx4 v136, s[42:43]
	s_mov_b32 m0, s34
	s_nop 0
	global_load_lds_dwordx4 v132, s[52:53]
	s_mov_b32 m0, s35
	s_nop 0
	global_load_lds_dwordx4 v134, s[52:53]
	s_waitcnt vmcnt(8)
	s_waitcnt lgkmcnt(0)
	s_barrier
	s_setprio 1
	v_mfma_f32_16x16x32_bf16 v[64:67], v[146:149], v[202:205], v[64:67]
	v_mfma_f32_16x16x32_bf16 v[60:63], v[154:157], v[202:205], v[60:63]
	v_mfma_f32_16x16x32_bf16 v[56:59], v[146:149], v[210:213], v[56:59]
	v_mfma_f32_16x16x32_bf16 v[52:55], v[154:157], v[210:213], v[52:55]
	v_mfma_f32_16x16x32_bf16 v[40:43], v[146:149], v[218:221], v[40:43]
	v_mfma_f32_16x16x32_bf16 v[36:39], v[154:157], v[218:221], v[36:39]
	v_mfma_f32_16x16x32_bf16 v[22:25], v[146:149], v[234:237], v[22:25]
	v_mfma_f32_16x16x32_bf16 v[18:21], v[154:157], v[234:237], v[18:21]
	v_mfma_f32_16x16x32_bf16 v[64:67], v[150:153], v[206:209], v[64:67]
	v_mfma_f32_16x16x32_bf16 v[60:63], v[158:161], v[206:209], v[60:63]
	v_mfma_f32_16x16x32_bf16 v[56:59], v[150:153], v[214:217], v[56:59]
	v_mfma_f32_16x16x32_bf16 v[52:55], v[158:161], v[214:217], v[52:55]
	v_mfma_f32_16x16x32_bf16 v[40:43], v[150:153], v[222:225], v[40:43]
	v_mfma_f32_16x16x32_bf16 v[36:39], v[158:161], v[222:225], v[36:39]
	v_mfma_f32_16x16x32_bf16 v[22:25], v[150:153], v[238:241], v[22:25]
	v_mfma_f32_16x16x32_bf16 v[18:21], v[158:161], v[238:241], v[18:21]
	v_mfma_f32_16x16x32_bf16 v[48:51], v[186:189], v[202:205], v[48:51]
	v_mfma_f32_16x16x32_bf16 v[44:47], v[194:197], v[202:205], v[44:47]
	v_mfma_f32_16x16x32_bf16 v[30:33], v[186:189], v[210:213], v[30:33]
	v_mfma_f32_16x16x32_bf16 v[26:29], v[194:197], v[210:213], v[26:29]
	v_mfma_f32_16x16x32_bf16 v[14:17], v[186:189], v[218:221], v[14:17]
	v_mfma_f32_16x16x32_bf16 v[10:13], v[194:197], v[218:221], v[10:13]
	v_mfma_f32_16x16x32_bf16 v[6:9], v[186:189], v[234:237], v[6:9]
	v_mfma_f32_16x16x32_bf16 v[2:5], v[194:197], v[234:237], v[2:5]
	v_mfma_f32_16x16x32_bf16 v[48:51], v[190:193], v[206:209], v[48:51]
	v_mfma_f32_16x16x32_bf16 v[44:47], v[198:201], v[206:209], v[44:47]
	v_mfma_f32_16x16x32_bf16 v[30:33], v[190:193], v[214:217], v[30:33]
	v_mfma_f32_16x16x32_bf16 v[26:29], v[198:201], v[214:217], v[26:29]
	v_mfma_f32_16x16x32_bf16 v[14:17], v[190:193], v[222:225], v[14:17]
	v_mfma_f32_16x16x32_bf16 v[10:13], v[198:201], v[222:225], v[10:13]
	v_mfma_f32_16x16x32_bf16 v[6:9], v[190:193], v[238:241], v[6:9]
	v_mfma_f32_16x16x32_bf16 v[2:5], v[198:201], v[238:241], v[2:5]
	s_setprio 0
	s_barrier
; #define PG8_STAGE(bufoff, gbase, voff) do { _Pragma("unroll") for (int _i = 0; _i < 2; ++_i) \
;         __builtin_amdgcn_global_load_lds((const unsigned*)((const char*)(gbase) + (voff)[_i]), (PG8_LAS unsigned*)(lds + (bufoff) + ldsw + _i * 8192), 16, 0, 0); } while (0)
; #define PG8_LDA(dst, b, h) do { _Pragma("unroll") for (int m = 0; m < 4; ++m) _Pragma("unroll") for (int k = 0; k < 2; ++k) dst[m][k] = *(const PG8_LAS bf16x8*)(lds + PG8_SA(b, h) + aoff + m * 2048 + k * 1024); } while (0)
; #define PG8_LDB(dst, b, h) do { _Pragma("unroll") for (int n = 0; n < 2; ++n) _Pragma("unroll") for (int k = 0; k < 2; ++k) dst[n][k] = *(const PG8_LAS bf16x8*)(lds + PG8_SB(b, h) + boff + n * 2048 + k * 1024); } while (0)
; #define PG8_WAIT_V(n) asm volatile("s_waitcnt vmcnt(" #n ")" ::: "memory")
; #define PG8_WAIT_L(n) asm volatile("s_waitcnt lgkmcnt(" #n ")" ::: "memory")
; #define PG8_BAR __builtin_amdgcn_s_barrier()
; #define PG8_SCHED __builtin_amdgcn_sched_barrier(0)
;     ...
;             PG8_LDB(B0, 1, 0); PG8_LDB(B1, 1, 1); PG8_SCHED; PG8_LDA(At, 1, 0); PG8_STAGE(PG8_SA(0, 1), a2 + hstepA, voffA);
;             PG8_WAIT_V(8); PG8_WAIT_L(0); PG8_BAR; PG8_MMA(0, 0, At, B0); PG8_MMA(0, 1, At, B1); PG8_BAR; PG8_SCHED;
;             PG8_LDA(At, 1, 1); PG8_STAGE(PG8_SB(1, 0), b3, voffB); PG8_STAGE(PG8_SB(1, 1), b3 + hstepB, voffB); PG8_STAGE(PG8_SA(1, 0), a3, voffA);
;             PG8_WAIT_V(8); PG8_WAIT_L(0); PG8_BAR; PG8_MMA(1, 0, At, B0); PG8_MMA(1, 1, At, B1); PG8_BAR; PG8_SCHED;
	s_add_i32 s67, 0, 0x18000
	s_add_i32 s68, 0, 0x1c000
	ds_read_b128 v[146:149], v163 offset:32768
	ds_read_b128 v[150:153], v163 offset:33792
	ds_read_b128 v[154:157], v163 offset:34816
	ds_read_b128 v[158:161], v163 offset:35840
	ds_read_b128 v[186:189], v163 offset:49152
	ds_read_b128 v[190:193], v163 offset:50176
	ds_read_b128 v[194:197], v163 offset:51200
	ds_read_b128 v[198:201], v163 offset:52224
	s_add_u32 s42, s52, 0x160000
	s_addc_u32 s43, s53, 0
	s_mov_b32 m0, s54
	ds_read_b128 v[202:205], v145 offset:32768
	ds_read_b128 v[206:209], v145 offset:33792
	ds_read_b128 v[210:213], v145 offset:34816
	ds_read_b128 v[214:217], v145 offset:35840
	ds_read_b128 v[218:221], v145 offset:36864
	ds_read_b128 v[222:225], v145 offset:37888
	ds_read_b128 v[234:237], v145 offset:38912
	ds_read_b128 v[238:241], v145 offset:39936
	global_load_lds_dwordx4 v132, s[42:43]
	s_mov_b32 m0, s55
	s_nop 0
	global_load_lds_dwordx4 v134, s[42:43]
	s_waitcnt vmcnt(8)
	s_waitcnt lgkmcnt(0)
	s_barrier
	s_setprio 1
	v_mfma_f32_16x16x32_bf16 v[128:131], v[146:149], v[202:205], v[128:131]
	v_mfma_f32_16x16x32_bf16 v[124:127], v[154:157], v[202:205], v[124:127]
	v_mfma_f32_16x16x32_bf16 v[120:123], v[146:149], v[210:213], v[120:123]
	v_mfma_f32_16x16x32_bf16 v[116:119], v[154:157], v[210:213], v[116:119]
	v_mfma_f32_16x16x32_bf16 v[104:107], v[146:149], v[218:221], v[104:107]
	v_mfma_f32_16x16x32_bf16 v[100:103], v[154:157], v[218:221], v[100:103]
	v_mfma_f32_16x16x32_bf16 v[88:91], v[146:149], v[234:237], v[88:91]
	v_mfma_f32_16x16x32_bf16 v[84:87], v[154:157], v[234:237], v[84:87]
	v_mfma_f32_16x16x32_bf16 v[128:131], v[150:153], v[206:209], v[128:131]
	v_mfma_f32_16x16x32_bf16 v[124:127], v[158:161], v[206:209], v[124:127]
	v_mfma_f32_16x16x32_bf16 v[120:123], v[150:153], v[214:217], v[120:123]
	v_mfma_f32_16x16x32_bf16 v[116:119], v[158:161], v[214:217], v[116:119]
	v_mfma_f32_16x16x32_bf16 v[104:107], v[150:153], v[222:225], v[104:107]
	v_mfma_f32_16x16x32_bf16 v[100:103], v[158:161], v[222:225], v[100:103]
	v_mfma_f32_16x16x32_bf16 v[88:91], v[150:153], v[238:241], v[88:91]
	v_mfma_f32_16x16x32_bf16 v[84:87], v[158:161], v[238:241], v[84:87]
	v_mfma_f32_16x16x32_bf16 v[112:115], v[186:189], v[202:205], v[112:115]
	v_mfma_f32_16x16x32_bf16 v[108:111], v[194:197], v[202:205], v[108:111]
	v_mfma_f32_16x16x32_bf16 v[96:99], v[186:189], v[210:213], v[96:99]
	v_mfma_f32_16x16x32_bf16 v[92:95], v[194:197], v[210:213], v[92:95]
	v_mfma_f32_16x16x32_bf16 v[80:83], v[186:189], v[218:221], v[80:83]
	v_mfma_f32_16x16x32_bf16 v[76:79], v[194:197], v[218:221], v[76:79]
	v_mfma_f32_16x16x32_bf16 v[72:75], v[186:189], v[234:237], v[72:75]
	v_mfma_f32_16x16x32_bf16 v[68:71], v[194:197], v[234:237], v[68:71]
	v_mfma_f32_16x16x32_bf16 v[112:115], v[190:193], v[206:209], v[112:115]
	v_mfma_f32_16x16x32_bf16 v[108:111], v[198:201], v[206:209], v[108:111]
	v_mfma_f32_16x16x32_bf16 v[96:99], v[190:193], v[214:217], v[96:99]
	v_mfma_f32_16x16x32_bf16 v[92:95], v[198:201], v[214:217], v[92:95]
	v_mfma_f32_16x16x32_bf16 v[80:83], v[190:193], v[222:225], v[80:83]
	v_mfma_f32_16x16x32_bf16 v[76:79], v[198:201], v[222:225], v[76:79]
	v_mfma_f32_16x16x32_bf16 v[72:75], v[190:193], v[238:241], v[72:75]
	v_mfma_f32_16x16x32_bf16 v[68:71], v[198:201], v[238:241], v[68:71]
	s_setprio 0
	s_barrier
	s_add_i32 s42, s67, s15
	s_mov_b32 m0, s42
	ds_read_b128 v[202:205], v145 offset:49152
	ds_read_b128 v[206:209], v145 offset:50176
	ds_read_b128 v[210:213], v145 offset:51200
	ds_read_b128 v[214:217], v145 offset:52224
	ds_read_b128 v[218:221], v145 offset:53248
	ds_read_b128 v[222:225], v145 offset:54272
	ds_read_b128 v[234:237], v145 offset:55296
	ds_read_b128 v[238:241], v145 offset:56320
	s_add_u32 vcc_lo, s50, 0x80
	s_addc_u32 vcc_hi, s51, 0
	global_load_lds_dwordx4 v34, vcc
	s_add_i32 m0, s42, 0x2000
	s_add_u32 s42, s50, 0x160080
	s_addc_u32 s43, s51, 0
	s_add_i32 s50, s68, s15
	global_load_lds_dwordx4 v136, s[98:99]
	s_mov_b32 m0, s50
	s_nop 0
	global_load_lds_dwordx4 v34, s[42:43]
	s_add_i32 m0, s50, 0x2000
	s_nop 0
	global_load_lds_dwordx4 v136, s[42:43]
	s_mov_b32 m0, s56
	s_nop 0
	s_add_u32 vcc_lo, s52, 0x80
	s_addc_u32 vcc_hi, s53, 0
	global_load_lds_dwordx4 v132, vcc
	s_mov_b32 m0, s57
	s_nop 0
	s_add_u32 vcc_lo, s52, 0x80
	s_addc_u32 vcc_hi, s53, 0
	global_load_lds_dwordx4 v134, vcc
	s_waitcnt vmcnt(8)
	s_waitcnt lgkmcnt(0)
	s_barrier
	s_setprio 1
	v_mfma_f32_16x16x32_bf16 v[64:67], v[146:149], v[202:205], v[64:67]
	v_mfma_f32_16x16x32_bf16 v[60:63], v[154:157], v[202:205], v[60:63]
	v_mfma_f32_16x16x32_bf16 v[56:59], v[146:149], v[210:213], v[56:59]
	v_mfma_f32_16x16x32_bf16 v[52:55], v[154:157], v[210:213], v[52:55]
	v_mfma_f32_16x16x32_bf16 v[40:43], v[146:149], v[218:221], v[40:43]
	v_mfma_f32_16x16x32_bf16 v[36:39], v[154:157], v[218:221], v[36:39]
	v_mfma_f32_16x16x32_bf16 v[22:25], v[146:149], v[234:237], v[22:25]
	v_mfma_f32_16x16x32_bf16 v[18:21], v[154:157], v[234:237], v[18:21]
	v_mfma_f32_16x16x32_bf16 v[64:67], v[150:153], v[206:209], v[64:67]
	v_mfma_f32_16x16x32_bf16 v[60:63], v[158:161], v[206:209], v[60:63]
	v_mfma_f32_16x16x32_bf16 v[56:59], v[150:153], v[214:217], v[56:59]
	v_mfma_f32_16x16x32_bf16 v[52:55], v[158:161], v[214:217], v[52:55]
	v_mfma_f32_16x16x32_bf16 v[40:43], v[150:153], v[222:225], v[40:43]
	v_mfma_f32_16x16x32_bf16 v[36:39], v[158:161], v[222:225], v[36:39]
	v_mfma_f32_16x16x32_bf16 v[22:25], v[150:153], v[238:241], v[22:25]
	v_mfma_f32_16x16x32_bf16 v[18:21], v[158:161], v[238:241], v[18:21]
	v_mfma_f32_16x16x32_bf16 v[48:51], v[186:189], v[202:205], v[48:51]
	v_mfma_f32_16x16x32_bf16 v[44:47], v[194:197], v[202:205], v[44:47]
	v_mfma_f32_16x16x32_bf16 v[30:33], v[186:189], v[210:213], v[30:33]
	v_mfma_f32_16x16x32_bf16 v[26:29], v[194:197], v[210:213], v[26:29]
	v_mfma_f32_16x16x32_bf16 v[14:17], v[186:189], v[218:221], v[14:17]
	v_mfma_f32_16x16x32_bf16 v[10:13], v[194:197], v[218:221], v[10:13]
	v_mfma_f32_16x16x32_bf16 v[6:9], v[186:189], v[234:237], v[6:9]
	v_mfma_f32_16x16x32_bf16 v[2:5], v[194:197], v[234:237], v[2:5]
	v_mfma_f32_16x16x32_bf16 v[48:51], v[190:193], v[206:209], v[48:51]
	v_mfma_f32_16x16x32_bf16 v[44:47], v[198:201], v[206:209], v[44:47]
	v_mfma_f32_16x16x32_bf16 v[30:33], v[190:193], v[214:217], v[30:33]
	v_mfma_f32_16x16x32_bf16 v[26:29], v[198:201], v[214:217], v[26:29]
	v_mfma_f32_16x16x32_bf16 v[14:17], v[190:193], v[222:225], v[14:17]
	v_mfma_f32_16x16x32_bf16 v[10:13], v[198:201], v[222:225], v[10:13]
	v_mfma_f32_16x16x32_bf16 v[6:9], v[190:193], v[238:241], v[6:9]
	v_mfma_f32_16x16x32_bf16 v[2:5], v[198:201], v[238:241], v[2:5]
	s_setprio 0
	s_barrier
	s_add_i32 s66, s66, 2
	s_add_u32 s64, s64, 0x100
	s_addc_u32 s65, s65, 0
	s_cmpk_gt_u32 s66, 0x55
	s_mov_b64 s[42:43], s[44:45]
	s_cbranch_scc0 .LBB0_694
	s_and_b64 vcc, exec, s[30:31]
	s_cbranch_vccz .LBB0_697
	s_barrier

; #define PG8_STAGE(bufoff, gbase, voff) do { _Pragma("unroll") for (int _i = 0; _i < 2; ++_i) \
;         __builtin_amdgcn_global_load_lds((const unsigned*)((const char*)(gbase) + (voff)[_i]), (PG8_LAS unsigned*)(lds + (bufoff) + ldsw + _i * 8192), 16, 0, 0); } while (0)
; #define PG8_LDA(dst, b, h) do { _Pragma("unroll") for (int m = 0; m < 4; ++m) _Pragma("unroll") for (int k = 0; k < 2; ++k) dst[m][k] = *(const PG8_LAS bf16x8*)(lds + PG8_SA(b, h) + aoff + m * 2048 + k * 1024); } while (0)
; #define PG8_LDB(dst, b, h) do { _Pragma("unroll") for (int n = 0; n < 2; ++n) _Pragma("unroll") for (int k = 0; k < 2; ++k) dst[n][k] = *(const PG8_LAS bf16x8*)(lds + PG8_SB(b, h) + boff + n * 2048 + k * 1024); } while (0)
; #define PG8_WAIT_V(n) asm volatile("s_waitcnt vmcnt(" #n ")" ::: "memory")
; #define PG8_WAIT_L(n) asm volatile("s_waitcnt lgkmcnt(" #n ")" ::: "memory")
; #define PG8_BAR __builtin_amdgcn_s_barrier()
; #define PG8_SCHED __builtin_amdgcn_sched_barrier(0)
;     ...
;         for (int t = 0; t < nt; t += 2) {
;             const bool last = (t == nt - 2);
;             const char* a1 = cA + (size_t)(t + 1) * kstep;
;             const char* a2 = last ? nA : cA + (size_t)(t + 2) * kstep; const char* b2 = last ? nB : cB + (size_t)(t + 2) * kstep;
;             const char* a3 = a2 + kstep; const char* b3 = b2 + kstep;
;             if (last && has_next) S.a_ready(nxt);
;             if constexpr (SP2) {
;             PG8_LDB(B0, 0, 0); PG8_LDB(B1, 0, 1); PG8_SCHED; PG8_LDA(At, 0, 0); PG8_STAGE(PG8_SA(1, 1), a1 + hstepA, voffA);
;             PG8_WAIT_V(8); PG8_WAIT_L(0); PG8_BAR; PG8_MMA(0, 0, At, B0); PG8_MMA(0, 1, At, B1); PG8_BAR; PG8_SCHED;
;             PG8_LDA(At, 0, 1); PG8_STAGE(PG8_SB(0, 0), b2, voffB); PG8_STAGE(PG8_SB(0, 1), b2 + hstepB, voffB); PG8_STAGE(PG8_SA(0, 0), a2, voffA);
;             PG8_WAIT_V(8); PG8_WAIT_L(0); PG8_BAR; PG8_MMA(1, 0, At, B0); PG8_MMA(1, 1, At, B1); PG8_BAR; PG8_SCHED;
.LBB0_726:
	v_add_u32_e32 v250, 0x10000, v209
	s_add_u32 s40, s42, 0x100
	s_addc_u32 s41, s43, 0
	s_add_i32 s64, 0, 0x10000
	s_cmp_eq_u32 s63, 40
	s_cselect_b32 s51, s31, s41
	s_cselect_b32 s50, s30, s40
	s_cselect_b32 s45, s37, s62
	s_cselect_b32 s44, s36, s61
	s_add_i32 s65, 0, 0x14000
	ds_read_b128 v[26:29], v250
	ds_read_b128 v[30:33], v250 offset:1024
	ds_read_b128 v[18:21], v250 offset:2048
	ds_read_b128 v[22:25], v250 offset:3072
	ds_read_b128 v[10:13], v250 offset:16384
	ds_read_b128 v[14:17], v250 offset:17408
	ds_read_b128 v[2:5], v250 offset:18432
	ds_read_b128 v[6:9], v250 offset:19456
	s_add_i32 m0, s21, 0xc000
	ds_read_b128 v[200:203], v211
	ds_read_b128 v[204:207], v211 offset:1024
	ds_read_b128 v[212:215], v211 offset:2048
	ds_read_b128 v[216:219], v211 offset:3072
	ds_read_b128 v[220:223], v211 offset:4096
	ds_read_b128 v[224:227], v211 offset:5120
	ds_read_b128 v[234:237], v211 offset:6144
	ds_read_b128 v[238:241], v211 offset:7168
	global_load_lds_dwordx4 v196, s[42:43]
	s_add_i32 m0, s21, 0xe000
	s_nop 0
	global_load_lds_dwordx4 v198, s[42:43]
	s_waitcnt vmcnt(8)
	s_waitcnt lgkmcnt(0)
	s_barrier
	s_setprio 1
	v_mfma_f32_16x16x128_f8f6f4 v[160:163], v[26:33], v[200:207], v[160:163]
	v_mfma_f32_16x16x128_f8f6f4 v[156:159], v[18:25], v[200:207], v[156:159]
	v_mfma_f32_16x16x128_f8f6f4 v[152:155], v[26:33], v[212:219], v[152:155]
	v_mfma_f32_16x16x128_f8f6f4 v[144:147], v[18:25], v[212:219], v[144:147]
	v_mfma_f32_16x16x128_f8f6f4 v[136:139], v[26:33], v[220:227], v[136:139]
	v_mfma_f32_16x16x128_f8f6f4 v[128:131], v[18:25], v[220:227], v[128:131]
	v_mfma_f32_16x16x128_f8f6f4 v[120:123], v[26:33], v[234:241], v[120:123]
	v_mfma_f32_16x16x128_f8f6f4 v[112:115], v[18:25], v[234:241], v[112:115]
	v_mfma_f32_16x16x128_f8f6f4 v[148:151], v[10:17], v[200:207], v[148:151]
	v_mfma_f32_16x16x128_f8f6f4 v[140:143], v[2:9], v[200:207], v[140:143]
	v_mfma_f32_16x16x128_f8f6f4 v[132:135], v[10:17], v[212:219], v[132:135]
	v_mfma_f32_16x16x128_f8f6f4 v[124:127], v[2:9], v[212:219], v[124:127]
	v_mfma_f32_16x16x128_f8f6f4 v[116:119], v[10:17], v[220:227], v[116:119]
	v_mfma_f32_16x16x128_f8f6f4 v[108:111], v[2:9], v[220:227], v[108:111]
	v_mfma_f32_16x16x128_f8f6f4 v[104:107], v[10:17], v[234:241], v[104:107]
	v_mfma_f32_16x16x128_f8f6f4 v[100:103], v[2:9], v[234:241], v[100:103]
	s_setprio 0
	s_barrier
	s_add_i32 s42, s64, s15
	s_mov_b32 m0, s42
	ds_read_b128 v[212:215], v211 offset:16384
	ds_read_b128 v[216:219], v211 offset:17408
	ds_read_b128 v[220:223], v211 offset:18432
	ds_read_b128 v[224:227], v211 offset:19456
	ds_read_b128 v[234:237], v211 offset:20480
	ds_read_b128 v[238:241], v211 offset:21504
	ds_read_b128 v[242:245], v211 offset:22528
	ds_read_b128 v[246:249], v211 offset:23552
	global_load_lds_dwordx4 v34, s[44:45]
	s_add_i32 m0, s42, 0x2000
	s_add_u32 s42, s44, 0xb0000
	s_addc_u32 s43, s45, 0
	s_add_u32 s98, s44, 0x80
	s_addc_u32 s99, s45, 0
	s_add_i32 s64, s65, s15
	global_load_lds_dwordx4 v190, s[44:45]
	s_mov_b32 m0, s64
	s_nop 0
	global_load_lds_dwordx4 v34, s[42:43]
	s_add_i32 m0, s64, 0x2000
	s_nop 0
	global_load_lds_dwordx4 v190, s[42:43]
	s_mov_b32 m0, s21
	s_nop 0
	global_load_lds_dwordx4 v186, s[50:51]
	s_mov_b32 m0, s34
	s_nop 0
	global_load_lds_dwordx4 v188, s[50:51]
	s_waitcnt vmcnt(8)
	s_waitcnt lgkmcnt(0)
	s_barrier
	s_setprio 1
	v_mfma_f32_16x16x128_f8f6f4 v[96:99], v[26:33], v[212:219], v[96:99]
	v_mfma_f32_16x16x128_f8f6f4 v[92:95], v[18:25], v[212:219], v[92:95]
	v_mfma_f32_16x16x128_f8f6f4 v[88:91], v[26:33], v[220:227], v[88:91]
	v_mfma_f32_16x16x128_f8f6f4 v[80:83], v[18:25], v[220:227], v[80:83]
	v_mfma_f32_16x16x128_f8f6f4 v[72:75], v[26:33], v[234:241], v[72:75]
	v_mfma_f32_16x16x128_f8f6f4 v[64:67], v[18:25], v[234:241], v[64:67]
	v_mfma_f32_16x16x128_f8f6f4 v[56:59], v[26:33], v[242:249], v[56:59]
	v_mfma_f32_16x16x128_f8f6f4 v[48:51], v[18:25], v[242:249], v[48:51]
	v_mfma_f32_16x16x128_f8f6f4 v[84:87], v[10:17], v[212:219], v[84:87]
	v_mfma_f32_16x16x128_f8f6f4 v[76:79], v[2:9], v[212:219], v[76:79]
	v_mfma_f32_16x16x128_f8f6f4 v[68:71], v[10:17], v[220:227], v[68:71]
	v_mfma_f32_16x16x128_f8f6f4 v[60:63], v[2:9], v[220:227], v[60:63]
	v_mfma_f32_16x16x128_f8f6f4 v[52:55], v[10:17], v[234:241], v[52:55]
	v_mfma_f32_16x16x128_f8f6f4 v[44:47], v[2:9], v[234:241], v[44:47]
	v_mfma_f32_16x16x128_f8f6f4 v[40:43], v[10:17], v[242:249], v[40:43]
	v_mfma_f32_16x16x128_f8f6f4 v[36:39], v[2:9], v[242:249], v[36:39]
	s_setprio 0
	s_barrier
; #define PG8_STAGE(bufoff, gbase, voff) do { _Pragma("unroll") for (int _i = 0; _i < 2; ++_i) \
;         __builtin_amdgcn_global_load_lds((const unsigned*)((const char*)(gbase) + (voff)[_i]), (PG8_LAS unsigned*)(lds + (bufoff) + ldsw + _i * 8192), 16, 0, 0); } while (0)
; #define PG8_LDA(dst, b, h) do { _Pragma("unroll") for (int m = 0; m < 4; ++m) _Pragma("unroll") for (int k = 0; k < 2; ++k) dst[m][k] = *(const PG8_LAS bf16x8*)(lds + PG8_SA(b, h) + aoff + m * 2048 + k * 1024); } while (0)
; #define PG8_LDB(dst, b, h) do { _Pragma("unroll") for (int n = 0; n < 2; ++n) _Pragma("unroll") for (int k = 0; k < 2; ++k) dst[n][k] = *(const PG8_LAS bf16x8*)(lds + PG8_SB(b, h) + boff + n * 2048 + k * 1024); } while (0)
; #define PG8_WAIT_V(n) asm volatile("s_waitcnt vmcnt(" #n ")" ::: "memory")
; #define PG8_WAIT_L(n) asm volatile("s_waitcnt lgkmcnt(" #n ")" ::: "memory")
; #define PG8_BAR __builtin_amdgcn_s_barrier()
; #define PG8_SCHED __builtin_amdgcn_sched_barrier(0)
;     ...
;             PG8_LDB(B0, 1, 0); PG8_LDB(B1, 1, 1); PG8_SCHED; PG8_LDA(At, 1, 0); PG8_STAGE(PG8_SA(0, 1), a2 + hstepA, voffA);
;             PG8_WAIT_V(8); PG8_WAIT_L(0); PG8_BAR; PG8_MMA(0, 0, At, B0); PG8_MMA(0, 1, At, B1); PG8_BAR; PG8_SCHED;
;             PG8_LDA(At, 1, 1); PG8_STAGE(PG8_SB(1, 0), b3, voffB); PG8_STAGE(PG8_SB(1, 1), b3 + hstepB, voffB); PG8_STAGE(PG8_SA(1, 0), a3, voffA);
;             PG8_WAIT_V(8); PG8_WAIT_L(0); PG8_BAR; PG8_MMA(1, 0, At, B0); PG8_MMA(1, 1, At, B1); PG8_BAR; PG8_SCHED;
	s_add_i32 s64, 0, 0x18000
	s_add_i32 s65, 0, 0x1c000
	ds_read_b128 v[2:5], v250 offset:32768
	ds_read_b128 v[6:9], v250 offset:33792
	ds_read_b128 v[10:13], v250 offset:34816
	ds_read_b128 v[14:17], v250 offset:35840
	ds_read_b128 v[18:21], v250 offset:49152
	ds_read_b128 v[22:25], v250 offset:50176
	ds_read_b128 v[26:29], v250 offset:51200
	ds_read_b128 v[30:33], v250 offset:52224
	s_add_u32 s42, s50, 0xb0000
	s_addc_u32 s43, s51, 0
	s_mov_b32 m0, s35
	ds_read_b128 v[212:215], v211 offset:32768
	ds_read_b128 v[216:219], v211 offset:33792
	ds_read_b128 v[220:223], v211 offset:34816
	ds_read_b128 v[224:227], v211 offset:35840
	ds_read_b128 v[234:237], v211 offset:36864
	ds_read_b128 v[238:241], v211 offset:37888
	ds_read_b128 v[242:245], v211 offset:38912
	ds_read_b128 v[246:249], v211 offset:39936
	global_load_lds_dwordx4 v186, s[42:43]
	s_mov_b32 m0, s52
	s_nop 0
	global_load_lds_dwordx4 v188, s[42:43]
	s_waitcnt vmcnt(8)
	s_waitcnt lgkmcnt(0)
	s_barrier
	s_setprio 1
	v_mfma_f32_16x16x128_f8f6f4 v[160:163], v[2:9], v[212:219], v[160:163]
	v_mfma_f32_16x16x128_f8f6f4 v[156:159], v[10:17], v[212:219], v[156:159]
	v_mfma_f32_16x16x128_f8f6f4 v[152:155], v[2:9], v[220:227], v[152:155]
	v_mfma_f32_16x16x128_f8f6f4 v[144:147], v[10:17], v[220:227], v[144:147]
	v_mfma_f32_16x16x128_f8f6f4 v[136:139], v[2:9], v[234:241], v[136:139]
	v_mfma_f32_16x16x128_f8f6f4 v[128:131], v[10:17], v[234:241], v[128:131]
	v_mfma_f32_16x16x128_f8f6f4 v[120:123], v[2:9], v[242:249], v[120:123]
	v_mfma_f32_16x16x128_f8f6f4 v[112:115], v[10:17], v[242:249], v[112:115]
	v_mfma_f32_16x16x128_f8f6f4 v[148:151], v[18:25], v[212:219], v[148:151]
	v_mfma_f32_16x16x128_f8f6f4 v[140:143], v[26:33], v[212:219], v[140:143]
	v_mfma_f32_16x16x128_f8f6f4 v[132:135], v[18:25], v[220:227], v[132:135]
	v_mfma_f32_16x16x128_f8f6f4 v[124:127], v[26:33], v[220:227], v[124:127]
	v_mfma_f32_16x16x128_f8f6f4 v[116:119], v[18:25], v[234:241], v[116:119]
	v_mfma_f32_16x16x128_f8f6f4 v[108:111], v[26:33], v[234:241], v[108:111]
	v_mfma_f32_16x16x128_f8f6f4 v[104:107], v[18:25], v[242:249], v[104:107]
	v_mfma_f32_16x16x128_f8f6f4 v[100:103], v[26:33], v[242:249], v[100:103]
	s_setprio 0
	s_barrier
	s_add_i32 s42, s64, s15
	s_mov_b32 m0, s42
	ds_read_b128 v[212:215], v211 offset:49152
	ds_read_b128 v[216:219], v211 offset:50176
	ds_read_b128 v[220:223], v211 offset:51200
	ds_read_b128 v[224:227], v211 offset:52224
	ds_read_b128 v[234:237], v211 offset:53248
	ds_read_b128 v[238:241], v211 offset:54272
	ds_read_b128 v[242:245], v211 offset:55296
	ds_read_b128 v[246:249], v211 offset:56320
	s_add_u32 vcc_lo, s44, 0x80
	s_addc_u32 vcc_hi, s45, 0
	global_load_lds_dwordx4 v34, vcc
	s_add_i32 m0, s42, 0x2000
	s_add_u32 s42, s44, 0xb0080
	s_addc_u32 s43, s45, 0
	s_add_i32 s44, s65, s15
	global_load_lds_dwordx4 v190, s[98:99]
	s_mov_b32 m0, s44
	s_nop 0
	global_load_lds_dwordx4 v34, s[42:43]
	s_add_i32 m0, s44, 0x2000
	s_nop 0
	global_load_lds_dwordx4 v190, s[42:43]
	s_mov_b32 m0, s53
	s_nop 0
	s_add_u32 vcc_lo, s50, 0x80
	s_addc_u32 vcc_hi, s51, 0
	global_load_lds_dwordx4 v186, vcc
	s_mov_b32 m0, s54
	s_nop 0
	s_add_u32 vcc_lo, s50, 0x80
	s_addc_u32 vcc_hi, s51, 0
	global_load_lds_dwordx4 v188, vcc
	s_waitcnt vmcnt(8)
	s_waitcnt lgkmcnt(0)
	s_barrier
	s_setprio 1
	v_mfma_f32_16x16x128_f8f6f4 v[96:99], v[2:9], v[212:219], v[96:99]
	v_mfma_f32_16x16x128_f8f6f4 v[92:95], v[10:17], v[212:219], v[92:95]
	v_mfma_f32_16x16x128_f8f6f4 v[88:91], v[2:9], v[220:227], v[88:91]
	v_mfma_f32_16x16x128_f8f6f4 v[80:83], v[10:17], v[220:227], v[80:83]
	v_mfma_f32_16x16x128_f8f6f4 v[72:75], v[2:9], v[234:241], v[72:75]
	v_mfma_f32_16x16x128_f8f6f4 v[64:67], v[10:17], v[234:241], v[64:67]
	v_mfma_f32_16x16x128_f8f6f4 v[56:59], v[2:9], v[242:249], v[56:59]
	v_mfma_f32_16x16x128_f8f6f4 v[48:51], v[10:17], v[242:249], v[48:51]
	v_mfma_f32_16x16x128_f8f6f4 v[84:87], v[18:25], v[212:219], v[84:87]
	v_mfma_f32_16x16x128_f8f6f4 v[76:79], v[26:33], v[212:219], v[76:79]
	v_mfma_f32_16x16x128_f8f6f4 v[68:71], v[18:25], v[220:227], v[68:71]
	v_mfma_f32_16x16x128_f8f6f4 v[60:63], v[26:33], v[220:227], v[60:63]
	v_mfma_f32_16x16x128_f8f6f4 v[52:55], v[18:25], v[234:241], v[52:55]
	v_mfma_f32_16x16x128_f8f6f4 v[44:47], v[26:33], v[234:241], v[44:47]
	v_mfma_f32_16x16x128_f8f6f4 v[40:43], v[18:25], v[242:249], v[40:43]
	v_mfma_f32_16x16x128_f8f6f4 v[36:39], v[26:33], v[242:249], v[36:39]
	s_setprio 0
	s_barrier
	s_add_i32 s63, s63, 2
	s_add_u32 s61, s61, 0x100
	s_addc_u32 s62, s62, 0
	s_cmp_gt_u32 s63, 41
	s_mov_b64 s[42:43], s[40:41]
	s_cbranch_scc0 .LBB0_726
	s_and_b64 vcc, exec, s[28:29]
	s_cbranch_vccz .LBB0_729
	s_barrier

; #define PG8_STAGE(bufoff, gbase, voff) do { _Pragma("unroll") for (int _i = 0; _i < 2; ++_i) \
;         __builtin_amdgcn_global_load_lds((const unsigned*)((const char*)(gbase) + (voff)[_i]), (PG8_LAS unsigned*)(lds + (bufoff) + ldsw + _i * 8192), 16, 0, 0); } while (0)
; #define PG8_LDA(dst, b, h) do { _Pragma("unroll") for (int m = 0; m < 4; ++m) _Pragma("unroll") for (int k = 0; k < 2; ++k) dst[m][k] = *(const PG8_LAS bf16x8*)(lds + PG8_SA(b, h) + aoff + m * 2048 + k * 1024); } while (0)
; #define PG8_LDB(dst, b, h) do { _Pragma("unroll") for (int n = 0; n < 2; ++n) _Pragma("unroll") for (int k = 0; k < 2; ++k) dst[n][k] = *(const PG8_LAS bf16x8*)(lds + PG8_SB(b, h) + boff + n * 2048 + k * 1024); } while (0)
; #define PG8_WAIT_V(n) asm volatile("s_waitcnt vmcnt(" #n ")" ::: "memory")
; #define PG8_WAIT_L(n) asm volatile("s_waitcnt lgkmcnt(" #n ")" ::: "memory")
; #define PG8_BAR __builtin_amdgcn_s_barrier()
; #define PG8_SCHED __builtin_amdgcn_sched_barrier(0)
;     ...
;         for (int t = 0; t < nt; t += 2) {
;             const bool last = (t == nt - 2);
;             const char* a1 = cA + (size_t)(t + 1) * kstep;
;             const char* a2 = last ? nA : cA + (size_t)(t + 2) * kstep; const char* b2 = last ? nB : cB + (size_t)(t + 2) * kstep;
;             const char* a3 = a2 + kstep; const char* b3 = b2 + kstep;
;             if (last && has_next) S.a_ready(nxt);
;             if constexpr (SP2) {
;             PG8_LDB(B0, 0, 0); PG8_LDB(B1, 0, 1); PG8_SCHED; PG8_LDA(At, 0, 0); PG8_STAGE(PG8_SA(1, 1), a1 + hstepA, voffA);
;             PG8_WAIT_V(8); PG8_WAIT_L(0); PG8_BAR; PG8_MMA(0, 0, At, B0); PG8_MMA(0, 1, At, B1); PG8_BAR; PG8_SCHED;
;             PG8_LDA(At, 0, 1); PG8_STAGE(PG8_SB(0, 0), b2, voffB); PG8_STAGE(PG8_SB(0, 1), b2 + hstepB, voffB); PG8_STAGE(PG8_SA(0, 0), a2, voffA);
;             PG8_WAIT_V(8); PG8_WAIT_L(0); PG8_BAR; PG8_MMA(1, 0, At, B0); PG8_MMA(1, 1, At, B1); PG8_BAR; PG8_SCHED;
.LBB0_923:
	v_add_u32_e32 v226, 0x10000, v153
	s_add_u32 s56, s52, 0xfff80080
	s_addc_u32 s57, s53, -1
	s_add_i32 s68, 0, 0x10000
	s_cmp_eq_u32 s47, 28
	s_cselect_b32 s59, s6, s57
	s_cselect_b32 s58, s15, s56
	s_cselect_b32 s57, s34, s41
	s_cselect_b32 s56, s35, s37
	s_add_i32 s76, 0, 0x14000
	s_waitcnt vmcnt(0)
	ds_read_b128 v[132:135], v226
	ds_read_b128 v[136:139], v226 offset:1024
	ds_read_b128 v[156:159], v226 offset:2048
	ds_read_b128 v[160:163], v226 offset:3072
	ds_read_b128 v[186:189], v226 offset:16384
	ds_read_b128 v[190:193], v226 offset:17408
	ds_read_b128 v[194:197], v226 offset:18432
	ds_read_b128 v[198:201], v226 offset:19456
	s_add_i32 m0, s10, 0xc000
	ds_read_b128 v[202:205], v155
	ds_read_b128 v[206:209], v155 offset:1024
	ds_read_b128 v[210:213], v155 offset:2048
	ds_read_b128 v[214:217], v155 offset:3072
	ds_read_b128 v[218:221], v155 offset:4096
	ds_read_b128 v[222:225], v155 offset:5120
	ds_read_b128 v[234:237], v155 offset:6144
	ds_read_b128 v[238:241], v155 offset:7168
	global_load_lds_dwordx4 v148, s[52:53]
	s_add_i32 m0, s10, 0xe000
	s_nop 0
	global_load_lds_dwordx4 v150, s[52:53]
	s_waitcnt vmcnt(8)
	s_waitcnt lgkmcnt(0)
	s_barrier
	s_setprio 1
	v_mfma_f32_16x16x32_bf16 v[128:131], v[132:135], v[202:205], v[128:131]
	v_mfma_f32_16x16x32_bf16 v[124:127], v[156:159], v[202:205], v[124:127]
	v_mfma_f32_16x16x32_bf16 v[112:115], v[132:135], v[210:213], v[112:115]
	v_mfma_f32_16x16x32_bf16 v[108:111], v[156:159], v[210:213], v[108:111]
	v_mfma_f32_16x16x32_bf16 v[96:99], v[132:135], v[218:221], v[96:99]
	v_mfma_f32_16x16x32_bf16 v[92:95], v[156:159], v[218:221], v[92:95]
	v_mfma_f32_16x16x32_bf16 v[80:83], v[132:135], v[234:237], v[80:83]
	v_mfma_f32_16x16x32_bf16 v[76:79], v[156:159], v[234:237], v[76:79]
	v_mfma_f32_16x16x32_bf16 v[128:131], v[136:139], v[206:209], v[128:131]
	v_mfma_f32_16x16x32_bf16 v[124:127], v[160:163], v[206:209], v[124:127]
	v_mfma_f32_16x16x32_bf16 v[112:115], v[136:139], v[214:217], v[112:115]
	v_mfma_f32_16x16x32_bf16 v[108:111], v[160:163], v[214:217], v[108:111]
	v_mfma_f32_16x16x32_bf16 v[96:99], v[136:139], v[222:225], v[96:99]
	v_mfma_f32_16x16x32_bf16 v[92:95], v[160:163], v[222:225], v[92:95]
	v_mfma_f32_16x16x32_bf16 v[80:83], v[136:139], v[238:241], v[80:83]
	v_mfma_f32_16x16x32_bf16 v[76:79], v[160:163], v[238:241], v[76:79]
	v_mfma_f32_16x16x32_bf16 v[120:123], v[186:189], v[202:205], v[120:123]
	v_mfma_f32_16x16x32_bf16 v[116:119], v[194:197], v[202:205], v[116:119]
	v_mfma_f32_16x16x32_bf16 v[104:107], v[186:189], v[210:213], v[104:107]
	v_mfma_f32_16x16x32_bf16 v[100:103], v[194:197], v[210:213], v[100:103]
	v_mfma_f32_16x16x32_bf16 v[88:91], v[186:189], v[218:221], v[88:91]
	v_mfma_f32_16x16x32_bf16 v[84:87], v[194:197], v[218:221], v[84:87]
	v_mfma_f32_16x16x32_bf16 v[72:75], v[186:189], v[234:237], v[72:75]
	v_mfma_f32_16x16x32_bf16 v[68:71], v[194:197], v[234:237], v[68:71]
	v_mfma_f32_16x16x32_bf16 v[120:123], v[190:193], v[206:209], v[120:123]
	v_mfma_f32_16x16x32_bf16 v[116:119], v[198:201], v[206:209], v[116:119]
	v_mfma_f32_16x16x32_bf16 v[104:107], v[190:193], v[214:217], v[104:107]
	v_mfma_f32_16x16x32_bf16 v[100:103], v[198:201], v[214:217], v[100:103]
	v_mfma_f32_16x16x32_bf16 v[88:91], v[190:193], v[222:225], v[88:91]
	v_mfma_f32_16x16x32_bf16 v[84:87], v[198:201], v[222:225], v[84:87]
	v_mfma_f32_16x16x32_bf16 v[72:75], v[190:193], v[238:241], v[72:75]
	v_mfma_f32_16x16x32_bf16 v[68:71], v[198:201], v[238:241], v[68:71]
	s_setprio 0
	s_barrier
	s_add_i32 s68, s68, s9
	s_mov_b32 m0, s68
	ds_read_b128 v[202:205], v155 offset:16384
	ds_read_b128 v[206:209], v155 offset:17408
	ds_read_b128 v[210:213], v155 offset:18432
	ds_read_b128 v[214:217], v155 offset:19456
	ds_read_b128 v[218:221], v155 offset:20480
	ds_read_b128 v[222:225], v155 offset:21504
	ds_read_b128 v[234:237], v155 offset:22528
	ds_read_b128 v[238:241], v155 offset:23552
	global_load_lds_dwordx4 v142, s[56:57]
	s_add_i32 m0, s68, 0x2000
	s_add_u32 s70, s56, 0x80000
	s_addc_u32 s71, s57, 0
	s_add_i32 s68, s76, s9
	global_load_lds_dwordx4 v146, s[56:57]
	s_mov_b32 m0, s68
	s_add_u32 s98, s58, 0x80
	s_addc_u32 s99, s59, 0
	global_load_lds_dwordx4 v142, s[70:71]
	s_add_i32 m0, s68, 0x2000
	s_nop 0
	global_load_lds_dwordx4 v146, s[70:71]
	s_mov_b32 m0, s10
	s_nop 0
	global_load_lds_dwordx4 v140, s[58:59]
	s_mov_b32 m0, s11
	s_nop 0
	global_load_lds_dwordx4 v144, s[58:59]
	s_waitcnt vmcnt(8)
	s_waitcnt lgkmcnt(0)
	s_barrier
	s_setprio 1
	v_mfma_f32_16x16x32_bf16 v[64:67], v[132:135], v[202:205], v[64:67]
	v_mfma_f32_16x16x32_bf16 v[60:63], v[156:159], v[202:205], v[60:63]
	v_mfma_f32_16x16x32_bf16 v[48:51], v[132:135], v[210:213], v[48:51]
	v_mfma_f32_16x16x32_bf16 v[44:47], v[156:159], v[210:213], v[44:47]
	v_mfma_f32_16x16x32_bf16 v[30:33], v[132:135], v[218:221], v[30:33]
	v_mfma_f32_16x16x32_bf16 v[26:29], v[156:159], v[218:221], v[26:29]
	v_mfma_f32_16x16x32_bf16 v[14:17], v[132:135], v[234:237], v[14:17]
	v_mfma_f32_16x16x32_bf16 v[10:13], v[156:159], v[234:237], v[10:13]
	v_mfma_f32_16x16x32_bf16 v[64:67], v[136:139], v[206:209], v[64:67]
	v_mfma_f32_16x16x32_bf16 v[60:63], v[160:163], v[206:209], v[60:63]
	v_mfma_f32_16x16x32_bf16 v[48:51], v[136:139], v[214:217], v[48:51]
	v_mfma_f32_16x16x32_bf16 v[44:47], v[160:163], v[214:217], v[44:47]
	v_mfma_f32_16x16x32_bf16 v[30:33], v[136:139], v[222:225], v[30:33]
	v_mfma_f32_16x16x32_bf16 v[26:29], v[160:163], v[222:225], v[26:29]
	v_mfma_f32_16x16x32_bf16 v[14:17], v[136:139], v[238:241], v[14:17]
	v_mfma_f32_16x16x32_bf16 v[10:13], v[160:163], v[238:241], v[10:13]
	v_mfma_f32_16x16x32_bf16 v[56:59], v[186:189], v[202:205], v[56:59]
	v_mfma_f32_16x16x32_bf16 v[52:55], v[194:197], v[202:205], v[52:55]
	v_mfma_f32_16x16x32_bf16 v[40:43], v[186:189], v[210:213], v[40:43]
	v_mfma_f32_16x16x32_bf16 v[36:39], v[194:197], v[210:213], v[36:39]
	v_mfma_f32_16x16x32_bf16 v[22:25], v[186:189], v[218:221], v[22:25]
	v_mfma_f32_16x16x32_bf16 v[18:21], v[194:197], v[218:221], v[18:21]
	v_mfma_f32_16x16x32_bf16 v[6:9], v[186:189], v[234:237], v[6:9]
	v_mfma_f32_16x16x32_bf16 v[2:5], v[194:197], v[234:237], v[2:5]
	v_mfma_f32_16x16x32_bf16 v[56:59], v[190:193], v[206:209], v[56:59]
	v_mfma_f32_16x16x32_bf16 v[52:55], v[198:201], v[206:209], v[52:55]
	v_mfma_f32_16x16x32_bf16 v[40:43], v[190:193], v[214:217], v[40:43]
	v_mfma_f32_16x16x32_bf16 v[36:39], v[198:201], v[214:217], v[36:39]
	v_mfma_f32_16x16x32_bf16 v[22:25], v[190:193], v[222:225], v[22:25]
	v_mfma_f32_16x16x32_bf16 v[18:21], v[198:201], v[222:225], v[18:21]
	v_mfma_f32_16x16x32_bf16 v[6:9], v[190:193], v[238:241], v[6:9]
	v_mfma_f32_16x16x32_bf16 v[2:5], v[198:201], v[238:241], v[2:5]
	s_setprio 0
	s_barrier
; #define PG8_STAGE(bufoff, gbase, voff) do { _Pragma("unroll") for (int _i = 0; _i < 2; ++_i) \
;         __builtin_amdgcn_global_load_lds((const unsigned*)((const char*)(gbase) + (voff)[_i]), (PG8_LAS unsigned*)(lds + (bufoff) + ldsw + _i * 8192), 16, 0, 0); } while (0)
; #define PG8_LDA(dst, b, h) do { _Pragma("unroll") for (int m = 0; m < 4; ++m) _Pragma("unroll") for (int k = 0; k < 2; ++k) dst[m][k] = *(const PG8_LAS bf16x8*)(lds + PG8_SA(b, h) + aoff + m * 2048 + k * 1024); } while (0)
; #define PG8_LDB(dst, b, h) do { _Pragma("unroll") for (int n = 0; n < 2; ++n) _Pragma("unroll") for (int k = 0; k < 2; ++k) dst[n][k] = *(const PG8_LAS bf16x8*)(lds + PG8_SB(b, h) + boff + n * 2048 + k * 1024); } while (0)
; #define PG8_WAIT_V(n) asm volatile("s_waitcnt vmcnt(" #n ")" ::: "memory")
; #define PG8_WAIT_L(n) asm volatile("s_waitcnt lgkmcnt(" #n ")" ::: "memory")
; #define PG8_BAR __builtin_amdgcn_s_barrier()
; #define PG8_SCHED __builtin_amdgcn_sched_barrier(0)
;     ...
;             PG8_LDB(B0, 1, 0); PG8_LDB(B1, 1, 1); PG8_SCHED; PG8_LDA(At, 1, 0); PG8_STAGE(PG8_SA(0, 1), a2 + hstepA, voffA);
;             PG8_WAIT_V(8); PG8_WAIT_L(0); PG8_BAR; PG8_MMA(0, 0, At, B0); PG8_MMA(0, 1, At, B1); PG8_BAR; PG8_SCHED;
;             PG8_LDA(At, 1, 1); PG8_STAGE(PG8_SB(1, 0), b3, voffB); PG8_STAGE(PG8_SB(1, 1), b3 + hstepB, voffB); PG8_STAGE(PG8_SA(1, 0), a3, voffA);
;             PG8_WAIT_V(8); PG8_WAIT_L(0); PG8_BAR; PG8_MMA(1, 0, At, B0); PG8_MMA(1, 1, At, B1); PG8_BAR; PG8_SCHED;
	s_add_i32 s68, 0, 0x18000
	s_add_i32 s70, 0, 0x1c000
	ds_read_b128 v[132:135], v226 offset:32768
	ds_read_b128 v[136:139], v226 offset:33792
	ds_read_b128 v[156:159], v226 offset:34816
	ds_read_b128 v[160:163], v226 offset:35840
	ds_read_b128 v[186:189], v226 offset:49152
	ds_read_b128 v[190:193], v226 offset:50176
	ds_read_b128 v[194:197], v226 offset:51200
	ds_read_b128 v[198:201], v226 offset:52224
	s_add_u32 s58, s58, 0x80000
	s_addc_u32 s59, s59, 0
	s_mov_b32 m0, s12
	ds_read_b128 v[202:205], v155 offset:32768
	ds_read_b128 v[206:209], v155 offset:33792
	ds_read_b128 v[210:213], v155 offset:34816
	ds_read_b128 v[214:217], v155 offset:35840
	ds_read_b128 v[218:221], v155 offset:36864
	ds_read_b128 v[222:225], v155 offset:37888
	ds_read_b128 v[234:237], v155 offset:38912
	ds_read_b128 v[238:241], v155 offset:39936
	global_load_lds_dwordx4 v140, s[58:59]
	s_mov_b32 m0, s13
	s_nop 0
	global_load_lds_dwordx4 v144, s[58:59]
	s_waitcnt vmcnt(8)
	s_waitcnt lgkmcnt(0)
	s_barrier
	s_setprio 1
	v_mfma_f32_16x16x32_bf16 v[128:131], v[132:135], v[202:205], v[128:131]
	v_mfma_f32_16x16x32_bf16 v[124:127], v[156:159], v[202:205], v[124:127]
	v_mfma_f32_16x16x32_bf16 v[112:115], v[132:135], v[210:213], v[112:115]
	v_mfma_f32_16x16x32_bf16 v[108:111], v[156:159], v[210:213], v[108:111]
	v_mfma_f32_16x16x32_bf16 v[96:99], v[132:135], v[218:221], v[96:99]
	v_mfma_f32_16x16x32_bf16 v[92:95], v[156:159], v[218:221], v[92:95]
	v_mfma_f32_16x16x32_bf16 v[80:83], v[132:135], v[234:237], v[80:83]
	v_mfma_f32_16x16x32_bf16 v[76:79], v[156:159], v[234:237], v[76:79]
	v_mfma_f32_16x16x32_bf16 v[128:131], v[136:139], v[206:209], v[128:131]
	v_mfma_f32_16x16x32_bf16 v[124:127], v[160:163], v[206:209], v[124:127]
	v_mfma_f32_16x16x32_bf16 v[112:115], v[136:139], v[214:217], v[112:115]
	v_mfma_f32_16x16x32_bf16 v[108:111], v[160:163], v[214:217], v[108:111]
	v_mfma_f32_16x16x32_bf16 v[96:99], v[136:139], v[222:225], v[96:99]
	v_mfma_f32_16x16x32_bf16 v[92:95], v[160:163], v[222:225], v[92:95]
	v_mfma_f32_16x16x32_bf16 v[80:83], v[136:139], v[238:241], v[80:83]
	v_mfma_f32_16x16x32_bf16 v[76:79], v[160:163], v[238:241], v[76:79]
	v_mfma_f32_16x16x32_bf16 v[120:123], v[186:189], v[202:205], v[120:123]
	v_mfma_f32_16x16x32_bf16 v[116:119], v[194:197], v[202:205], v[116:119]
	v_mfma_f32_16x16x32_bf16 v[104:107], v[186:189], v[210:213], v[104:107]
	v_mfma_f32_16x16x32_bf16 v[100:103], v[194:197], v[210:213], v[100:103]
	v_mfma_f32_16x16x32_bf16 v[88:91], v[186:189], v[218:221], v[88:91]
	v_mfma_f32_16x16x32_bf16 v[84:87], v[194:197], v[218:221], v[84:87]
	v_mfma_f32_16x16x32_bf16 v[72:75], v[186:189], v[234:237], v[72:75]
	v_mfma_f32_16x16x32_bf16 v[68:71], v[194:197], v[234:237], v[68:71]
	v_mfma_f32_16x16x32_bf16 v[120:123], v[190:193], v[206:209], v[120:123]
	v_mfma_f32_16x16x32_bf16 v[116:119], v[198:201], v[206:209], v[116:119]
	v_mfma_f32_16x16x32_bf16 v[104:107], v[190:193], v[214:217], v[104:107]
	v_mfma_f32_16x16x32_bf16 v[100:103], v[198:201], v[214:217], v[100:103]
	v_mfma_f32_16x16x32_bf16 v[88:91], v[190:193], v[222:225], v[88:91]
	v_mfma_f32_16x16x32_bf16 v[84:87], v[198:201], v[222:225], v[84:87]
	v_mfma_f32_16x16x32_bf16 v[72:75], v[190:193], v[238:241], v[72:75]
	v_mfma_f32_16x16x32_bf16 v[68:71], v[198:201], v[238:241], v[68:71]
	s_setprio 0
	s_barrier
	s_add_i32 s58, s68, s9
	s_mov_b32 m0, s58
	ds_read_b128 v[202:205], v155 offset:49152
	ds_read_b128 v[206:209], v155 offset:50176
	ds_read_b128 v[210:213], v155 offset:51200
	ds_read_b128 v[214:217], v155 offset:52224
	ds_read_b128 v[218:221], v155 offset:53248
	ds_read_b128 v[222:225], v155 offset:54272
	ds_read_b128 v[234:237], v155 offset:55296
	ds_read_b128 v[238:241], v155 offset:56320
	s_add_u32 vcc_lo, s56, 0x80
	s_addc_u32 vcc_hi, s57, 0
	global_load_lds_dwordx4 v142, vcc
	s_add_i32 m0, s58, 0x2000
	s_add_u32 s56, s56, 0x80080
	s_addc_u32 s57, s57, 0
	s_add_i32 s58, s70, s9
	s_add_u32 vcc_lo, s56, 0xfff80000
	s_addc_u32 vcc_hi, s57, -1
	global_load_lds_dwordx4 v146, vcc
	s_mov_b32 m0, s58
	s_nop 0
	global_load_lds_dwordx4 v142, s[56:57]
	s_add_i32 m0, s58, 0x2000
	s_nop 0
	global_load_lds_dwordx4 v146, s[56:57]
	s_mov_b32 m0, s55
	s_nop 0
	global_load_lds_dwordx4 v140, s[98:99]
	s_mov_b32 m0, s66
	s_nop 0
	global_load_lds_dwordx4 v144, s[98:99]
	s_waitcnt vmcnt(8)
	s_waitcnt lgkmcnt(0)
	s_barrier
	s_setprio 1
	v_mfma_f32_16x16x32_bf16 v[64:67], v[132:135], v[202:205], v[64:67]
	v_mfma_f32_16x16x32_bf16 v[60:63], v[156:159], v[202:205], v[60:63]
	v_mfma_f32_16x16x32_bf16 v[48:51], v[132:135], v[210:213], v[48:51]
	v_mfma_f32_16x16x32_bf16 v[44:47], v[156:159], v[210:213], v[44:47]
	v_mfma_f32_16x16x32_bf16 v[30:33], v[132:135], v[218:221], v[30:33]
	v_mfma_f32_16x16x32_bf16 v[26:29], v[156:159], v[218:221], v[26:29]
	v_mfma_f32_16x16x32_bf16 v[14:17], v[132:135], v[234:237], v[14:17]
	v_mfma_f32_16x16x32_bf16 v[10:13], v[156:159], v[234:237], v[10:13]
	v_mfma_f32_16x16x32_bf16 v[64:67], v[136:139], v[206:209], v[64:67]
	v_mfma_f32_16x16x32_bf16 v[60:63], v[160:163], v[206:209], v[60:63]
	v_mfma_f32_16x16x32_bf16 v[48:51], v[136:139], v[214:217], v[48:51]
	v_mfma_f32_16x16x32_bf16 v[44:47], v[160:163], v[214:217], v[44:47]
	v_mfma_f32_16x16x32_bf16 v[30:33], v[136:139], v[222:225], v[30:33]
	v_mfma_f32_16x16x32_bf16 v[26:29], v[160:163], v[222:225], v[26:29]
	v_mfma_f32_16x16x32_bf16 v[14:17], v[136:139], v[238:241], v[14:17]
	v_mfma_f32_16x16x32_bf16 v[10:13], v[160:163], v[238:241], v[10:13]
	v_mfma_f32_16x16x32_bf16 v[56:59], v[186:189], v[202:205], v[56:59]
	v_mfma_f32_16x16x32_bf16 v[52:55], v[194:197], v[202:205], v[52:55]
	v_mfma_f32_16x16x32_bf16 v[40:43], v[186:189], v[210:213], v[40:43]
	v_mfma_f32_16x16x32_bf16 v[36:39], v[194:197], v[210:213], v[36:39]
	v_mfma_f32_16x16x32_bf16 v[22:25], v[186:189], v[218:221], v[22:25]
	v_mfma_f32_16x16x32_bf16 v[18:21], v[194:197], v[218:221], v[18:21]
	v_mfma_f32_16x16x32_bf16 v[6:9], v[186:189], v[234:237], v[6:9]
	v_mfma_f32_16x16x32_bf16 v[2:5], v[194:197], v[234:237], v[2:5]
	v_mfma_f32_16x16x32_bf16 v[56:59], v[190:193], v[206:209], v[56:59]
	v_mfma_f32_16x16x32_bf16 v[52:55], v[198:201], v[206:209], v[52:55]
	v_mfma_f32_16x16x32_bf16 v[40:43], v[190:193], v[214:217], v[40:43]
	v_mfma_f32_16x16x32_bf16 v[36:39], v[198:201], v[214:217], v[36:39]
	v_mfma_f32_16x16x32_bf16 v[22:25], v[190:193], v[222:225], v[22:25]
	v_mfma_f32_16x16x32_bf16 v[18:21], v[198:201], v[222:225], v[18:21]
	v_mfma_f32_16x16x32_bf16 v[6:9], v[190:193], v[238:241], v[6:9]
	v_mfma_f32_16x16x32_bf16 v[2:5], v[198:201], v[238:241], v[2:5]
	s_setprio 0
	s_barrier
	s_add_i32 s47, s47, 2
	s_add_u32 s52, s52, 0x100
	s_addc_u32 s53, s53, 0
	s_add_u32 s37, s37, 0x100
	s_addc_u32 s41, s41, 0
	s_cmp_gt_u32 s47, 29
	s_cbranch_scc0 .LBB0_923
	s_and_b64 vcc, exec, s[30:31]
	s_cbranch_vccz .LBB0_926
	s_barrier

; #define PG8_STAGE(bufoff, gbase, voff) do { _Pragma("unroll") for (int _i = 0; _i < 2; ++_i) \
;         __builtin_amdgcn_global_load_lds((const unsigned*)((const char*)(gbase) + (voff)[_i]), (PG8_LAS unsigned*)(lds + (bufoff) + ldsw + _i * 8192), 16, 0, 0); } while (0)
; #define PG8_LDA(dst, b, h) do { _Pragma("unroll") for (int m = 0; m < 4; ++m) _Pragma("unroll") for (int k = 0; k < 2; ++k) dst[m][k] = *(const PG8_LAS bf16x8*)(lds + PG8_SA(b, h) + aoff + m * 2048 + k * 1024); } while (0)
; #define PG8_LDB(dst, b, h) do { _Pragma("unroll") for (int n = 0; n < 2; ++n) _Pragma("unroll") for (int k = 0; k < 2; ++k) dst[n][k] = *(const PG8_LAS bf16x8*)(lds + PG8_SB(b, h) + boff + n * 2048 + k * 1024); } while (0)
; #define PG8_WAIT_V(n) asm volatile("s_waitcnt vmcnt(" #n ")" ::: "memory")
; #define PG8_WAIT_L(n) asm volatile("s_waitcnt lgkmcnt(" #n ")" ::: "memory")
; #define PG8_BAR __builtin_amdgcn_s_barrier()
; #define PG8_SCHED __builtin_amdgcn_sched_barrier(0)
;     ...
;         for (int t = 0; t < nt; t += 2) {
;             const bool last = (t == nt - 2);
;             const char* a1 = cA + (size_t)(t + 1) * kstep;
;             const char* a2 = last ? nA : cA + (size_t)(t + 2) * kstep; const char* b2 = last ? nB : cB + (size_t)(t + 2) * kstep;
;             const char* a3 = a2 + kstep; const char* b3 = b2 + kstep;
;             if (last && has_next) S.a_ready(nxt);
;             if constexpr (SP2) {
;             PG8_LDB(B0, 0, 0); PG8_LDB(B1, 0, 1); PG8_SCHED; PG8_LDA(At, 0, 0); PG8_STAGE(PG8_SA(1, 1), a1 + hstepA, voffA);
;             PG8_WAIT_V(8); PG8_WAIT_L(0); PG8_BAR; PG8_MMA(0, 0, At, B0); PG8_MMA(0, 1, At, B1); PG8_BAR; PG8_SCHED;
;             PG8_LDA(At, 0, 1); PG8_STAGE(PG8_SB(0, 0), b2, voffB); PG8_STAGE(PG8_SB(0, 1), b2 + hstepB, voffB); PG8_STAGE(PG8_SA(0, 0), a2, voffA);
;             PG8_WAIT_V(8); PG8_WAIT_L(0); PG8_BAR; PG8_MMA(1, 0, At, B0); PG8_MMA(1, 1, At, B1); PG8_BAR; PG8_SCHED;
.LBB0_1133:
	v_add_u32_e32 v226, 0x10000, v208
	s_add_u32 s52, s50, 0xfffc0080
	s_addc_u32 s53, s51, -1
	s_add_i32 s75, 0, 0x10000
	s_cmp_eq_u32 s74, 12
	s_cselect_b32 s55, s37, s53
	s_cselect_b32 s54, s67, s52
	s_cselect_b32 s53, s31, s71
	s_cselect_b32 s52, s68, s70
	s_add_i32 s76, 0, 0x14000
	ds_read_b128 v[26:29], v226
	ds_read_b128 v[30:33], v226 offset:1024
	ds_read_b128 v[18:21], v226 offset:2048
	ds_read_b128 v[22:25], v226 offset:3072
	ds_read_b128 v[10:13], v226 offset:16384
	ds_read_b128 v[14:17], v226 offset:17408
	ds_read_b128 v[2:5], v226 offset:18432
	ds_read_b128 v[6:9], v226 offset:19456
	s_add_i32 m0, s57, 0xc000
	ds_read_b128 v[198:201], v209
	ds_read_b128 v[202:205], v209 offset:1024
	ds_read_b128 v[210:213], v209 offset:2048
	ds_read_b128 v[214:217], v209 offset:3072
	ds_read_b128 v[218:221], v209 offset:4096
	ds_read_b128 v[222:225], v209 offset:5120
	ds_read_b128 v[234:237], v209 offset:6144
	ds_read_b128 v[238:241], v209 offset:7168
	global_load_lds_dwordx4 v194, s[50:51]
	s_add_i32 m0, s57, 0xe000
	s_nop 0
	global_load_lds_dwordx4 v196, s[50:51]
	s_waitcnt vmcnt(8)
	s_waitcnt lgkmcnt(0)
	s_barrier
	s_setprio 1
	v_mfma_f32_16x16x128_f8f6f4 v[160:163], v[26:33], v[198:205], v[160:163]
	v_mfma_f32_16x16x128_f8f6f4 v[156:159], v[18:25], v[198:205], v[156:159]
	v_mfma_f32_16x16x128_f8f6f4 v[144:147], v[26:33], v[210:217], v[144:147]
	v_mfma_f32_16x16x128_f8f6f4 v[140:143], v[18:25], v[210:217], v[140:143]
	v_mfma_f32_16x16x128_f8f6f4 v[128:131], v[26:33], v[218:225], v[128:131]
	v_mfma_f32_16x16x128_f8f6f4 v[124:127], v[18:25], v[218:225], v[124:127]
	v_mfma_f32_16x16x128_f8f6f4 v[112:115], v[26:33], v[234:241], v[112:115]
	v_mfma_f32_16x16x128_f8f6f4 v[108:111], v[18:25], v[234:241], v[108:111]
	v_mfma_f32_16x16x128_f8f6f4 v[152:155], v[10:17], v[198:205], v[152:155]
	v_mfma_f32_16x16x128_f8f6f4 v[148:151], v[2:9], v[198:205], v[148:151]
	v_mfma_f32_16x16x128_f8f6f4 v[136:139], v[10:17], v[210:217], v[136:139]
	v_mfma_f32_16x16x128_f8f6f4 v[132:135], v[2:9], v[210:217], v[132:135]
	v_mfma_f32_16x16x128_f8f6f4 v[120:123], v[10:17], v[218:225], v[120:123]
	v_mfma_f32_16x16x128_f8f6f4 v[116:119], v[2:9], v[218:225], v[116:119]
	v_mfma_f32_16x16x128_f8f6f4 v[104:107], v[10:17], v[234:241], v[104:107]
	v_mfma_f32_16x16x128_f8f6f4 v[100:103], v[2:9], v[234:241], v[100:103]
	s_setprio 0
	s_barrier
	s_add_i32 s75, s75, s11
	s_mov_b32 m0, s75
	ds_read_b128 v[210:213], v209 offset:16384
	ds_read_b128 v[214:217], v209 offset:17408
	ds_read_b128 v[218:221], v209 offset:18432
	ds_read_b128 v[222:225], v209 offset:19456
	ds_read_b128 v[234:237], v209 offset:20480
	ds_read_b128 v[238:241], v209 offset:21504
	ds_read_b128 v[242:245], v209 offset:22528
	ds_read_b128 v[246:249], v209 offset:23552
	global_load_lds_dwordx4 v34, s[52:53]
	s_add_i32 m0, s75, 0x2000
	s_add_u32 s78, s52, 0x40000
	s_addc_u32 s79, s53, 0
	s_add_i32 s75, s76, s11
	global_load_lds_dwordx4 v186, s[52:53]
	s_mov_b32 m0, s75
	s_add_u32 s98, s54, 0x80
	s_addc_u32 s99, s55, 0
	global_load_lds_dwordx4 v34, s[78:79]
	s_add_i32 m0, s75, 0x2000
	s_nop 0
	global_load_lds_dwordx4 v186, s[78:79]
	s_mov_b32 m0, s57
	s_nop 0
	global_load_lds_dwordx4 v190, s[54:55]
	s_mov_b32 m0, s6
	s_nop 0
	global_load_lds_dwordx4 v188, s[54:55]
	s_waitcnt vmcnt(8)
	s_waitcnt lgkmcnt(0)
	s_barrier
	s_setprio 1
	v_mfma_f32_16x16x128_f8f6f4 v[96:99], v[26:33], v[210:217], v[96:99]
	v_mfma_f32_16x16x128_f8f6f4 v[92:95], v[18:25], v[210:217], v[92:95]
	v_mfma_f32_16x16x128_f8f6f4 v[80:83], v[26:33], v[218:225], v[80:83]
	v_mfma_f32_16x16x128_f8f6f4 v[76:79], v[18:25], v[218:225], v[76:79]
	v_mfma_f32_16x16x128_f8f6f4 v[64:67], v[26:33], v[234:241], v[64:67]
	v_mfma_f32_16x16x128_f8f6f4 v[60:63], v[18:25], v[234:241], v[60:63]
	v_mfma_f32_16x16x128_f8f6f4 v[48:51], v[26:33], v[242:249], v[48:51]
	v_mfma_f32_16x16x128_f8f6f4 v[44:47], v[18:25], v[242:249], v[44:47]
	v_mfma_f32_16x16x128_f8f6f4 v[88:91], v[10:17], v[210:217], v[88:91]
	v_mfma_f32_16x16x128_f8f6f4 v[84:87], v[2:9], v[210:217], v[84:87]
	v_mfma_f32_16x16x128_f8f6f4 v[72:75], v[10:17], v[218:225], v[72:75]
	v_mfma_f32_16x16x128_f8f6f4 v[68:71], v[2:9], v[218:225], v[68:71]
	v_mfma_f32_16x16x128_f8f6f4 v[56:59], v[10:17], v[234:241], v[56:59]
	v_mfma_f32_16x16x128_f8f6f4 v[52:55], v[2:9], v[234:241], v[52:55]
	v_mfma_f32_16x16x128_f8f6f4 v[40:43], v[10:17], v[242:249], v[40:43]
	v_mfma_f32_16x16x128_f8f6f4 v[36:39], v[2:9], v[242:249], v[36:39]
	s_setprio 0
	s_barrier
; #define PG8_STAGE(bufoff, gbase, voff) do { _Pragma("unroll") for (int _i = 0; _i < 2; ++_i) \
;         __builtin_amdgcn_global_load_lds((const unsigned*)((const char*)(gbase) + (voff)[_i]), (PG8_LAS unsigned*)(lds + (bufoff) + ldsw + _i * 8192), 16, 0, 0); } while (0)
; #define PG8_LDA(dst, b, h) do { _Pragma("unroll") for (int m = 0; m < 4; ++m) _Pragma("unroll") for (int k = 0; k < 2; ++k) dst[m][k] = *(const PG8_LAS bf16x8*)(lds + PG8_SA(b, h) + aoff + m * 2048 + k * 1024); } while (0)
; #define PG8_LDB(dst, b, h) do { _Pragma("unroll") for (int n = 0; n < 2; ++n) _Pragma("unroll") for (int k = 0; k < 2; ++k) dst[n][k] = *(const PG8_LAS bf16x8*)(lds + PG8_SB(b, h) + boff + n * 2048 + k * 1024); } while (0)
; #define PG8_WAIT_V(n) asm volatile("s_waitcnt vmcnt(" #n ")" ::: "memory")
; #define PG8_WAIT_L(n) asm volatile("s_waitcnt lgkmcnt(" #n ")" ::: "memory")
; #define PG8_BAR __builtin_amdgcn_s_barrier()
; #define PG8_SCHED __builtin_amdgcn_sched_barrier(0)
;     ...
;             PG8_LDB(B0, 1, 0); PG8_LDB(B1, 1, 1); PG8_SCHED; PG8_LDA(At, 1, 0); PG8_STAGE(PG8_SA(0, 1), a2 + hstepA, voffA);
;             PG8_WAIT_V(8); PG8_WAIT_L(0); PG8_BAR; PG8_MMA(0, 0, At, B0); PG8_MMA(0, 1, At, B1); PG8_BAR; PG8_SCHED;
;             PG8_LDA(At, 1, 1); PG8_STAGE(PG8_SB(1, 0), b3, voffB); PG8_STAGE(PG8_SB(1, 1), b3 + hstepB, voffB); PG8_STAGE(PG8_SA(1, 0), a3, voffA);
;             PG8_WAIT_V(8); PG8_WAIT_L(0); PG8_BAR; PG8_MMA(1, 0, At, B0); PG8_MMA(1, 1, At, B1); PG8_BAR; PG8_SCHED;
	s_add_i32 s75, 0, 0x18000
	s_add_i32 s76, 0, 0x1c000
	ds_read_b128 v[2:5], v226 offset:32768
	ds_read_b128 v[6:9], v226 offset:33792
	ds_read_b128 v[10:13], v226 offset:34816
	ds_read_b128 v[14:17], v226 offset:35840
	ds_read_b128 v[18:21], v226 offset:49152
	ds_read_b128 v[22:25], v226 offset:50176
	ds_read_b128 v[26:29], v226 offset:51200
	ds_read_b128 v[30:33], v226 offset:52224
	s_add_u32 s54, s54, 0x40000
	s_addc_u32 s55, s55, 0
	s_mov_b32 m0, s15
	ds_read_b128 v[210:213], v209 offset:32768
	ds_read_b128 v[214:217], v209 offset:33792
	ds_read_b128 v[218:221], v209 offset:34816
	ds_read_b128 v[222:225], v209 offset:35840
	ds_read_b128 v[234:237], v209 offset:36864
	ds_read_b128 v[238:241], v209 offset:37888
	ds_read_b128 v[242:245], v209 offset:38912
	ds_read_b128 v[246:249], v209 offset:39936
	global_load_lds_dwordx4 v190, s[54:55]
	s_mov_b32 m0, s34
	s_nop 0
	global_load_lds_dwordx4 v188, s[54:55]
	s_waitcnt vmcnt(8)
	s_waitcnt lgkmcnt(0)
	s_barrier
	s_setprio 1
	v_mfma_f32_16x16x128_f8f6f4 v[160:163], v[2:9], v[210:217], v[160:163]
	v_mfma_f32_16x16x128_f8f6f4 v[156:159], v[10:17], v[210:217], v[156:159]
	v_mfma_f32_16x16x128_f8f6f4 v[144:147], v[2:9], v[218:225], v[144:147]
	v_mfma_f32_16x16x128_f8f6f4 v[140:143], v[10:17], v[218:225], v[140:143]
	v_mfma_f32_16x16x128_f8f6f4 v[128:131], v[2:9], v[234:241], v[128:131]
	v_mfma_f32_16x16x128_f8f6f4 v[124:127], v[10:17], v[234:241], v[124:127]
	v_mfma_f32_16x16x128_f8f6f4 v[112:115], v[2:9], v[242:249], v[112:115]
	v_mfma_f32_16x16x128_f8f6f4 v[108:111], v[10:17], v[242:249], v[108:111]
	v_mfma_f32_16x16x128_f8f6f4 v[152:155], v[18:25], v[210:217], v[152:155]
	v_mfma_f32_16x16x128_f8f6f4 v[148:151], v[26:33], v[210:217], v[148:151]
	v_mfma_f32_16x16x128_f8f6f4 v[136:139], v[18:25], v[218:225], v[136:139]
	v_mfma_f32_16x16x128_f8f6f4 v[132:135], v[26:33], v[218:225], v[132:135]
	v_mfma_f32_16x16x128_f8f6f4 v[120:123], v[18:25], v[234:241], v[120:123]
	v_mfma_f32_16x16x128_f8f6f4 v[116:119], v[26:33], v[234:241], v[116:119]
	v_mfma_f32_16x16x128_f8f6f4 v[104:107], v[18:25], v[242:249], v[104:107]
	v_mfma_f32_16x16x128_f8f6f4 v[100:103], v[26:33], v[242:249], v[100:103]
	s_setprio 0
	s_barrier
	s_add_i32 s54, s75, s11
	s_mov_b32 m0, s54
	ds_read_b128 v[210:213], v209 offset:49152
	ds_read_b128 v[214:217], v209 offset:50176
	ds_read_b128 v[218:221], v209 offset:51200
	ds_read_b128 v[222:225], v209 offset:52224
	ds_read_b128 v[234:237], v209 offset:53248
	ds_read_b128 v[238:241], v209 offset:54272
	ds_read_b128 v[242:245], v209 offset:55296
	ds_read_b128 v[246:249], v209 offset:56320
	s_add_u32 vcc_lo, s52, 0x80
	s_addc_u32 vcc_hi, s53, 0
	global_load_lds_dwordx4 v34, vcc
	s_add_i32 m0, s54, 0x2000
	s_add_u32 s52, s52, 0x40080
	s_addc_u32 s53, s53, 0
	s_add_i32 s54, s76, s11
	s_add_u32 vcc_lo, s52, 0xfffc0000
	s_addc_u32 vcc_hi, s53, -1
	global_load_lds_dwordx4 v186, vcc
	s_mov_b32 m0, s54
	s_nop 0
	global_load_lds_dwordx4 v34, s[52:53]
	s_add_i32 m0, s54, 0x2000
	s_nop 0
	global_load_lds_dwordx4 v186, s[52:53]
	s_mov_b32 m0, s35
	s_nop 0
	global_load_lds_dwordx4 v190, s[98:99]
	s_mov_b32 m0, s58
	s_nop 0
	global_load_lds_dwordx4 v188, s[98:99]
	s_waitcnt vmcnt(8)
	s_waitcnt lgkmcnt(0)
	s_barrier
	s_setprio 1
	v_mfma_f32_16x16x128_f8f6f4 v[96:99], v[2:9], v[210:217], v[96:99]
	v_mfma_f32_16x16x128_f8f6f4 v[92:95], v[10:17], v[210:217], v[92:95]
	v_mfma_f32_16x16x128_f8f6f4 v[80:83], v[2:9], v[218:225], v[80:83]
	v_mfma_f32_16x16x128_f8f6f4 v[76:79], v[10:17], v[218:225], v[76:79]
	v_mfma_f32_16x16x128_f8f6f4 v[64:67], v[2:9], v[234:241], v[64:67]
	v_mfma_f32_16x16x128_f8f6f4 v[60:63], v[10:17], v[234:241], v[60:63]
	v_mfma_f32_16x16x128_f8f6f4 v[48:51], v[2:9], v[242:249], v[48:51]
	v_mfma_f32_16x16x128_f8f6f4 v[44:47], v[10:17], v[242:249], v[44:47]
	v_mfma_f32_16x16x128_f8f6f4 v[88:91], v[18:25], v[210:217], v[88:91]
	v_mfma_f32_16x16x128_f8f6f4 v[84:87], v[26:33], v[210:217], v[84:87]
	v_mfma_f32_16x16x128_f8f6f4 v[72:75], v[18:25], v[218:225], v[72:75]
	v_mfma_f32_16x16x128_f8f6f4 v[68:71], v[26:33], v[218:225], v[68:71]
	v_mfma_f32_16x16x128_f8f6f4 v[56:59], v[18:25], v[234:241], v[56:59]
	v_mfma_f32_16x16x128_f8f6f4 v[52:55], v[26:33], v[234:241], v[52:55]
	v_mfma_f32_16x16x128_f8f6f4 v[40:43], v[18:25], v[242:249], v[40:43]
	v_mfma_f32_16x16x128_f8f6f4 v[36:39], v[26:33], v[242:249], v[36:39]
	s_setprio 0
	s_barrier
	s_add_i32 s74, s74, 2
	s_add_u32 s50, s50, 0x100
	s_addc_u32 s51, s51, 0
	s_add_u32 s70, s70, 0x100
	s_addc_u32 s71, s71, 0
	s_cmp_gt_u32 s74, 13
	s_cbranch_scc0 .LBB0_1133
	s_and_b64 vcc, exec, s[28:29]
	s_cbranch_vccz .LBB0_1136
	s_barrier

; #define PG8_STAGE(bufoff, gbase, voff) do { _Pragma("unroll") for (int _i = 0; _i < 2; ++_i) \
;         __builtin_amdgcn_global_load_lds((const unsigned*)((const char*)(gbase) + (voff)[_i]), (PG8_LAS unsigned*)(lds + (bufoff) + ldsw + _i * 8192), 16, 0, 0); } while (0)
; #define PG8_LDA(dst, b, h) do { _Pragma("unroll") for (int m = 0; m < 4; ++m) _Pragma("unroll") for (int k = 0; k < 2; ++k) dst[m][k] = *(const PG8_LAS bf16x8*)(lds + PG8_SA(b, h) + aoff + m * 2048 + k * 1024); } while (0)
; #define PG8_LDB(dst, b, h) do { _Pragma("unroll") for (int n = 0; n < 2; ++n) _Pragma("unroll") for (int k = 0; k < 2; ++k) dst[n][k] = *(const PG8_LAS bf16x8*)(lds + PG8_SB(b, h) + boff + n * 2048 + k * 1024); } while (0)
; #define PG8_WAIT_V(n) asm volatile("s_waitcnt vmcnt(" #n ")" ::: "memory")
; #define PG8_WAIT_L(n) asm volatile("s_waitcnt lgkmcnt(" #n ")" ::: "memory")
; #define PG8_BAR __builtin_amdgcn_s_barrier()
; #define PG8_SCHED __builtin_amdgcn_sched_barrier(0)
;     ...
;         for (int t = 0; t < nt; t += 2) {
;             const bool last = (t == nt - 2);
;             const char* a1 = cA + (size_t)(t + 1) * kstep;
;             const char* a2 = last ? nA : cA + (size_t)(t + 2) * kstep; const char* b2 = last ? nB : cB + (size_t)(t + 2) * kstep;
;             const char* a3 = a2 + kstep; const char* b3 = b2 + kstep;
;             if (last && has_next) S.a_ready(nxt);
;             if constexpr (SP2) {
;             PG8_LDB(B0, 0, 0); PG8_LDB(B1, 0, 1); PG8_SCHED; PG8_LDA(At, 0, 0); PG8_STAGE(PG8_SA(1, 1), a1 + hstepA, voffA);
;             PG8_WAIT_V(8); PG8_WAIT_L(0); PG8_BAR; PG8_MMA(0, 0, At, B0); PG8_MMA(0, 1, At, B1); PG8_BAR; PG8_SCHED;
;             PG8_LDA(At, 0, 1); PG8_STAGE(PG8_SB(0, 0), b2, voffB); PG8_STAGE(PG8_SB(0, 1), b2 + hstepB, voffB); PG8_STAGE(PG8_SA(0, 0), a2, voffA);
;             PG8_WAIT_V(8); PG8_WAIT_L(0); PG8_BAR; PG8_MMA(1, 0, At, B0); PG8_MMA(1, 1, At, B1); PG8_BAR; PG8_SCHED;
.LBB0_1153:
	v_add_u32_e32 v162, 0x10000, v155
	s_add_u32 s34, s26, 0xfff80080
	s_addc_u32 s35, s27, -1
	s_add_i32 s37, 0, 0x10000
	s_cmp_eq_u32 s19, 28
	s_cselect_b32 s57, s6, s35
	s_cselect_b32 s56, s10, s34
	s_cselect_b32 s41, s11, s15
	s_cselect_b32 s40, s12, s13
	s_add_i32 s49, 0, 0x14000
	ds_read_b128 v[132:135], v162
	ds_read_b128 v[136:139], v162 offset:1024
	s_waitcnt vmcnt(0)
	ds_read_b128 v[158:161], v162 offset:2048
	ds_read_b128 v[186:189], v162 offset:3072
	ds_read_b128 v[190:193], v162 offset:16384
	ds_read_b128 v[194:197], v162 offset:17408
	ds_read_b128 v[198:201], v162 offset:18432
	ds_read_b128 v[202:205], v162 offset:19456
	s_add_i32 m0, s8, 0xc000
	ds_read_b128 v[206:209], v157
	ds_read_b128 v[210:213], v157 offset:1024
	ds_read_b128 v[214:217], v157 offset:2048
	ds_read_b128 v[218:221], v157 offset:3072
	ds_read_b128 v[222:225], v157 offset:4096
	ds_read_b128 v[234:237], v157 offset:5120
	ds_read_b128 v[238:241], v157 offset:6144
	ds_read_b128 v[242:245], v157 offset:7168
	global_load_lds_dwordx4 v150, s[26:27]
	s_add_i32 m0, s8, 0xe000
	s_nop 0
	global_load_lds_dwordx4 v152, s[26:27]
	s_waitcnt vmcnt(8)
	s_waitcnt lgkmcnt(0)
	s_barrier
	s_setprio 1
	v_mfma_f32_16x16x32_bf16 v[128:131], v[132:135], v[206:209], v[128:131]
	v_mfma_f32_16x16x32_bf16 v[124:127], v[158:161], v[206:209], v[124:127]
	v_mfma_f32_16x16x32_bf16 v[112:115], v[132:135], v[214:217], v[112:115]
	v_mfma_f32_16x16x32_bf16 v[108:111], v[158:161], v[214:217], v[108:111]
	v_mfma_f32_16x16x32_bf16 v[96:99], v[132:135], v[222:225], v[96:99]
	v_mfma_f32_16x16x32_bf16 v[92:95], v[158:161], v[222:225], v[92:95]
	v_mfma_f32_16x16x32_bf16 v[80:83], v[132:135], v[238:241], v[80:83]
	v_mfma_f32_16x16x32_bf16 v[76:79], v[158:161], v[238:241], v[76:79]
	v_mfma_f32_16x16x32_bf16 v[128:131], v[136:139], v[210:213], v[128:131]
	v_mfma_f32_16x16x32_bf16 v[124:127], v[186:189], v[210:213], v[124:127]
	v_mfma_f32_16x16x32_bf16 v[112:115], v[136:139], v[218:221], v[112:115]
	v_mfma_f32_16x16x32_bf16 v[108:111], v[186:189], v[218:221], v[108:111]
	v_mfma_f32_16x16x32_bf16 v[96:99], v[136:139], v[234:237], v[96:99]
	v_mfma_f32_16x16x32_bf16 v[92:95], v[186:189], v[234:237], v[92:95]
	v_mfma_f32_16x16x32_bf16 v[80:83], v[136:139], v[242:245], v[80:83]
	v_mfma_f32_16x16x32_bf16 v[76:79], v[186:189], v[242:245], v[76:79]
	v_mfma_f32_16x16x32_bf16 v[120:123], v[190:193], v[206:209], v[120:123]
	v_mfma_f32_16x16x32_bf16 v[116:119], v[198:201], v[206:209], v[116:119]
	v_mfma_f32_16x16x32_bf16 v[104:107], v[190:193], v[214:217], v[104:107]
	v_mfma_f32_16x16x32_bf16 v[100:103], v[198:201], v[214:217], v[100:103]
	v_mfma_f32_16x16x32_bf16 v[88:91], v[190:193], v[222:225], v[88:91]
	v_mfma_f32_16x16x32_bf16 v[84:87], v[198:201], v[222:225], v[84:87]
	v_mfma_f32_16x16x32_bf16 v[72:75], v[190:193], v[238:241], v[72:75]
	v_mfma_f32_16x16x32_bf16 v[68:71], v[198:201], v[238:241], v[68:71]
	v_mfma_f32_16x16x32_bf16 v[120:123], v[194:197], v[210:213], v[120:123]
	v_mfma_f32_16x16x32_bf16 v[116:119], v[202:205], v[210:213], v[116:119]
	v_mfma_f32_16x16x32_bf16 v[104:107], v[194:197], v[218:221], v[104:107]
	v_mfma_f32_16x16x32_bf16 v[100:103], v[202:205], v[218:221], v[100:103]
	v_mfma_f32_16x16x32_bf16 v[88:91], v[194:197], v[234:237], v[88:91]
	v_mfma_f32_16x16x32_bf16 v[84:87], v[202:205], v[234:237], v[84:87]
	v_mfma_f32_16x16x32_bf16 v[72:75], v[194:197], v[242:245], v[72:75]
	v_mfma_f32_16x16x32_bf16 v[68:71], v[202:205], v[242:245], v[68:71]
	s_setprio 0
	s_barrier
	s_add_i32 s34, s37, s7
	s_mov_b32 m0, s34
	ds_read_b128 v[206:209], v157 offset:16384
	ds_read_b128 v[210:213], v157 offset:17408
	ds_read_b128 v[214:217], v157 offset:18432
	ds_read_b128 v[218:221], v157 offset:19456
	ds_read_b128 v[222:225], v157 offset:20480
	ds_read_b128 v[234:237], v157 offset:21504
	ds_read_b128 v[238:241], v157 offset:22528
	ds_read_b128 v[242:245], v157 offset:23552
	global_load_lds_dwordx4 v142, s[40:41]
	s_add_i32 m0, s34, 0x2000
	s_add_u32 s34, s40, 0x80000
	s_addc_u32 s35, s41, 0
	s_add_i32 s37, s49, s7
	global_load_lds_dwordx4 v146, s[40:41]
	s_mov_b32 m0, s37
	s_nop 0
	global_load_lds_dwordx4 v142, s[34:35]
	s_add_i32 m0, s37, 0x2000
	s_nop 0
	global_load_lds_dwordx4 v146, s[34:35]
	s_mov_b32 m0, s8
	s_nop 0
	global_load_lds_dwordx4 v140, s[56:57]
	s_mov_b32 m0, s9
	s_nop 0
	global_load_lds_dwordx4 v144, s[56:57]
	s_waitcnt vmcnt(8)
	s_waitcnt lgkmcnt(0)
	s_barrier
	s_setprio 1
	v_mfma_f32_16x16x32_bf16 v[64:67], v[132:135], v[206:209], v[64:67]
	v_mfma_f32_16x16x32_bf16 v[60:63], v[158:161], v[206:209], v[60:63]
	v_mfma_f32_16x16x32_bf16 v[48:51], v[132:135], v[214:217], v[48:51]
	v_mfma_f32_16x16x32_bf16 v[44:47], v[158:161], v[214:217], v[44:47]
	v_mfma_f32_16x16x32_bf16 v[30:33], v[132:135], v[222:225], v[30:33]
	v_mfma_f32_16x16x32_bf16 v[26:29], v[158:161], v[222:225], v[26:29]
	v_mfma_f32_16x16x32_bf16 v[14:17], v[132:135], v[238:241], v[14:17]
	v_mfma_f32_16x16x32_bf16 v[10:13], v[158:161], v[238:241], v[10:13]
	v_mfma_f32_16x16x32_bf16 v[64:67], v[136:139], v[210:213], v[64:67]
	v_mfma_f32_16x16x32_bf16 v[60:63], v[186:189], v[210:213], v[60:63]
	v_mfma_f32_16x16x32_bf16 v[48:51], v[136:139], v[218:221], v[48:51]
	v_mfma_f32_16x16x32_bf16 v[44:47], v[186:189], v[218:221], v[44:47]
	v_mfma_f32_16x16x32_bf16 v[30:33], v[136:139], v[234:237], v[30:33]
	v_mfma_f32_16x16x32_bf16 v[26:29], v[186:189], v[234:237], v[26:29]
	v_mfma_f32_16x16x32_bf16 v[14:17], v[136:139], v[242:245], v[14:17]
	v_mfma_f32_16x16x32_bf16 v[10:13], v[186:189], v[242:245], v[10:13]
	v_mfma_f32_16x16x32_bf16 v[56:59], v[190:193], v[206:209], v[56:59]
	v_mfma_f32_16x16x32_bf16 v[52:55], v[198:201], v[206:209], v[52:55]
	v_mfma_f32_16x16x32_bf16 v[40:43], v[190:193], v[214:217], v[40:43]
	v_mfma_f32_16x16x32_bf16 v[36:39], v[198:201], v[214:217], v[36:39]
	v_mfma_f32_16x16x32_bf16 v[22:25], v[190:193], v[222:225], v[22:25]
	v_mfma_f32_16x16x32_bf16 v[18:21], v[198:201], v[222:225], v[18:21]
	v_mfma_f32_16x16x32_bf16 v[6:9], v[190:193], v[238:241], v[6:9]
	v_mfma_f32_16x16x32_bf16 v[2:5], v[198:201], v[238:241], v[2:5]
	v_mfma_f32_16x16x32_bf16 v[56:59], v[194:197], v[210:213], v[56:59]
	v_mfma_f32_16x16x32_bf16 v[52:55], v[202:205], v[210:213], v[52:55]
	v_mfma_f32_16x16x32_bf16 v[40:43], v[194:197], v[218:221], v[40:43]
	v_mfma_f32_16x16x32_bf16 v[36:39], v[202:205], v[218:221], v[36:39]
	v_mfma_f32_16x16x32_bf16 v[22:25], v[194:197], v[234:237], v[22:25]
	v_mfma_f32_16x16x32_bf16 v[18:21], v[202:205], v[234:237], v[18:21]
	v_mfma_f32_16x16x32_bf16 v[6:9], v[194:197], v[242:245], v[6:9]
	v_mfma_f32_16x16x32_bf16 v[2:5], v[202:205], v[242:245], v[2:5]
	s_setprio 0
	s_barrier
; #define PG8_STAGE(bufoff, gbase, voff) do { _Pragma("unroll") for (int _i = 0; _i < 2; ++_i) \
;         __builtin_amdgcn_global_load_lds((const unsigned*)((const char*)(gbase) + (voff)[_i]), (PG8_LAS unsigned*)(lds + (bufoff) + ldsw + _i * 8192), 16, 0, 0); } while (0)
; #define PG8_LDA(dst, b, h) do { _Pragma("unroll") for (int m = 0; m < 4; ++m) _Pragma("unroll") for (int k = 0; k < 2; ++k) dst[m][k] = *(const PG8_LAS bf16x8*)(lds + PG8_SA(b, h) + aoff + m * 2048 + k * 1024); } while (0)
; #define PG8_LDB(dst, b, h) do { _Pragma("unroll") for (int n = 0; n < 2; ++n) _Pragma("unroll") for (int k = 0; k < 2; ++k) dst[n][k] = *(const PG8_LAS bf16x8*)(lds + PG8_SB(b, h) + boff + n * 2048 + k * 1024); } while (0)
; #define PG8_WAIT_V(n) asm volatile("s_waitcnt vmcnt(" #n ")" ::: "memory")
; #define PG8_WAIT_L(n) asm volatile("s_waitcnt lgkmcnt(" #n ")" ::: "memory")
; #define PG8_BAR __builtin_amdgcn_s_barrier()
; #define PG8_SCHED __builtin_amdgcn_sched_barrier(0)
;     ...
;             PG8_LDB(B0, 1, 0); PG8_LDB(B1, 1, 1); PG8_SCHED; PG8_LDA(At, 1, 0); PG8_STAGE(PG8_SA(0, 1), a2 + hstepA, voffA);
;             PG8_WAIT_V(8); PG8_WAIT_L(0); PG8_BAR; PG8_MMA(0, 0, At, B0); PG8_MMA(0, 1, At, B1); PG8_BAR; PG8_SCHED;
;             PG8_LDA(At, 1, 1); PG8_STAGE(PG8_SB(1, 0), b3, voffB); PG8_STAGE(PG8_SB(1, 1), b3 + hstepB, voffB); PG8_STAGE(PG8_SA(1, 0), a3, voffA);
;             PG8_WAIT_V(8); PG8_WAIT_L(0); PG8_BAR; PG8_MMA(1, 0, At, B0); PG8_MMA(1, 1, At, B1); PG8_BAR; PG8_SCHED;
	s_add_i32 s37, 0, 0x18000
	s_add_i32 s49, 0, 0x1c000
	ds_read_b128 v[132:135], v162 offset:32768
	ds_read_b128 v[136:139], v162 offset:33792
	ds_read_b128 v[158:161], v162 offset:34816
	ds_read_b128 v[186:189], v162 offset:35840
	ds_read_b128 v[190:193], v162 offset:49152
	ds_read_b128 v[194:197], v162 offset:50176
	ds_read_b128 v[198:201], v162 offset:51200
	ds_read_b128 v[202:205], v162 offset:52224
	s_add_u32 s34, s56, 0x80000
	s_addc_u32 s35, s57, 0
	s_mov_b32 m0, s58
	ds_read_b128 v[206:209], v157 offset:32768
	ds_read_b128 v[210:213], v157 offset:33792
	ds_read_b128 v[214:217], v157 offset:34816
	ds_read_b128 v[218:221], v157 offset:35840
	ds_read_b128 v[222:225], v157 offset:36864
	ds_read_b128 v[234:237], v157 offset:37888
	ds_read_b128 v[238:241], v157 offset:38912
	ds_read_b128 v[242:245], v157 offset:39936
	global_load_lds_dwordx4 v140, s[34:35]
	s_mov_b32 m0, s59
	s_nop 0
	global_load_lds_dwordx4 v144, s[34:35]
	s_waitcnt vmcnt(8)
	s_waitcnt lgkmcnt(0)
	s_barrier
	s_setprio 1
	v_mfma_f32_16x16x32_bf16 v[128:131], v[132:135], v[206:209], v[128:131]
	v_mfma_f32_16x16x32_bf16 v[124:127], v[158:161], v[206:209], v[124:127]
	v_mfma_f32_16x16x32_bf16 v[112:115], v[132:135], v[214:217], v[112:115]
	v_mfma_f32_16x16x32_bf16 v[108:111], v[158:161], v[214:217], v[108:111]
	v_mfma_f32_16x16x32_bf16 v[96:99], v[132:135], v[222:225], v[96:99]
	v_mfma_f32_16x16x32_bf16 v[92:95], v[158:161], v[222:225], v[92:95]
	v_mfma_f32_16x16x32_bf16 v[80:83], v[132:135], v[238:241], v[80:83]
	v_mfma_f32_16x16x32_bf16 v[76:79], v[158:161], v[238:241], v[76:79]
	v_mfma_f32_16x16x32_bf16 v[128:131], v[136:139], v[210:213], v[128:131]
	v_mfma_f32_16x16x32_bf16 v[124:127], v[186:189], v[210:213], v[124:127]
	v_mfma_f32_16x16x32_bf16 v[112:115], v[136:139], v[218:221], v[112:115]
	v_mfma_f32_16x16x32_bf16 v[108:111], v[186:189], v[218:221], v[108:111]
	v_mfma_f32_16x16x32_bf16 v[96:99], v[136:139], v[234:237], v[96:99]
	v_mfma_f32_16x16x32_bf16 v[92:95], v[186:189], v[234:237], v[92:95]
	v_mfma_f32_16x16x32_bf16 v[80:83], v[136:139], v[242:245], v[80:83]
	v_mfma_f32_16x16x32_bf16 v[76:79], v[186:189], v[242:245], v[76:79]
	v_mfma_f32_16x16x32_bf16 v[120:123], v[190:193], v[206:209], v[120:123]
	v_mfma_f32_16x16x32_bf16 v[116:119], v[198:201], v[206:209], v[116:119]
	v_mfma_f32_16x16x32_bf16 v[104:107], v[190:193], v[214:217], v[104:107]
	v_mfma_f32_16x16x32_bf16 v[100:103], v[198:201], v[214:217], v[100:103]
	v_mfma_f32_16x16x32_bf16 v[88:91], v[190:193], v[222:225], v[88:91]
	v_mfma_f32_16x16x32_bf16 v[84:87], v[198:201], v[222:225], v[84:87]
	v_mfma_f32_16x16x32_bf16 v[72:75], v[190:193], v[238:241], v[72:75]
	v_mfma_f32_16x16x32_bf16 v[68:71], v[198:201], v[238:241], v[68:71]
	v_mfma_f32_16x16x32_bf16 v[120:123], v[194:197], v[210:213], v[120:123]
	v_mfma_f32_16x16x32_bf16 v[116:119], v[202:205], v[210:213], v[116:119]
	v_mfma_f32_16x16x32_bf16 v[104:107], v[194:197], v[218:221], v[104:107]
	v_mfma_f32_16x16x32_bf16 v[100:103], v[202:205], v[218:221], v[100:103]
	v_mfma_f32_16x16x32_bf16 v[88:91], v[194:197], v[234:237], v[88:91]
	v_mfma_f32_16x16x32_bf16 v[84:87], v[202:205], v[234:237], v[84:87]
	v_mfma_f32_16x16x32_bf16 v[72:75], v[194:197], v[242:245], v[72:75]
	v_mfma_f32_16x16x32_bf16 v[68:71], v[202:205], v[242:245], v[68:71]
	s_setprio 0
	s_barrier
	s_add_i32 s34, s37, s7
	s_mov_b32 m0, s34
	ds_read_b128 v[206:209], v157 offset:49152
	ds_read_b128 v[210:213], v157 offset:50176
	ds_read_b128 v[214:217], v157 offset:51200
	ds_read_b128 v[218:221], v157 offset:52224
	ds_read_b128 v[222:225], v157 offset:53248
	ds_read_b128 v[234:237], v157 offset:54272
	ds_read_b128 v[238:241], v157 offset:55296
	ds_read_b128 v[242:245], v157 offset:56320
	s_add_u32 vcc_lo, s40, 0x80
	s_addc_u32 vcc_hi, s41, 0
	global_load_lds_dwordx4 v142, vcc
	s_add_i32 m0, s34, 0x2000
	s_add_u32 s34, s40, 0x80080
	s_addc_u32 s35, s41, 0
	s_add_i32 s37, s49, s7
	s_add_u32 vcc_lo, s40, 0x80
	s_addc_u32 vcc_hi, s41, 0
	global_load_lds_dwordx4 v146, vcc
	s_mov_b32 m0, s37
	s_nop 0
	global_load_lds_dwordx4 v142, s[34:35]
	s_add_i32 m0, s37, 0x2000
	s_nop 0
	global_load_lds_dwordx4 v146, s[34:35]
	s_mov_b32 m0, s66
	s_nop 0
	s_add_u32 vcc_lo, s56, 0x80
	s_addc_u32 vcc_hi, s57, 0
	global_load_lds_dwordx4 v140, vcc
	s_mov_b32 m0, s67
	s_nop 0
	s_add_u32 vcc_lo, s56, 0x80
	s_addc_u32 vcc_hi, s57, 0
	global_load_lds_dwordx4 v144, vcc
	s_waitcnt vmcnt(8)
	s_waitcnt lgkmcnt(0)
	s_barrier
	s_setprio 1
	v_mfma_f32_16x16x32_bf16 v[64:67], v[132:135], v[206:209], v[64:67]
	v_mfma_f32_16x16x32_bf16 v[60:63], v[158:161], v[206:209], v[60:63]
	v_mfma_f32_16x16x32_bf16 v[48:51], v[132:135], v[214:217], v[48:51]
	v_mfma_f32_16x16x32_bf16 v[44:47], v[158:161], v[214:217], v[44:47]
	v_mfma_f32_16x16x32_bf16 v[30:33], v[132:135], v[222:225], v[30:33]
	v_mfma_f32_16x16x32_bf16 v[26:29], v[158:161], v[222:225], v[26:29]
	v_mfma_f32_16x16x32_bf16 v[14:17], v[132:135], v[238:241], v[14:17]
	v_mfma_f32_16x16x32_bf16 v[10:13], v[158:161], v[238:241], v[10:13]
	v_mfma_f32_16x16x32_bf16 v[64:67], v[136:139], v[210:213], v[64:67]
	v_mfma_f32_16x16x32_bf16 v[60:63], v[186:189], v[210:213], v[60:63]
	v_mfma_f32_16x16x32_bf16 v[48:51], v[136:139], v[218:221], v[48:51]
	v_mfma_f32_16x16x32_bf16 v[44:47], v[186:189], v[218:221], v[44:47]
	v_mfma_f32_16x16x32_bf16 v[30:33], v[136:139], v[234:237], v[30:33]
	v_mfma_f32_16x16x32_bf16 v[26:29], v[186:189], v[234:237], v[26:29]
	v_mfma_f32_16x16x32_bf16 v[14:17], v[136:139], v[242:245], v[14:17]
	v_mfma_f32_16x16x32_bf16 v[10:13], v[186:189], v[242:245], v[10:13]
	v_mfma_f32_16x16x32_bf16 v[56:59], v[190:193], v[206:209], v[56:59]
	v_mfma_f32_16x16x32_bf16 v[52:55], v[198:201], v[206:209], v[52:55]
	v_mfma_f32_16x16x32_bf16 v[40:43], v[190:193], v[214:217], v[40:43]
	v_mfma_f32_16x16x32_bf16 v[36:39], v[198:201], v[214:217], v[36:39]
	v_mfma_f32_16x16x32_bf16 v[22:25], v[190:193], v[222:225], v[22:25]
	v_mfma_f32_16x16x32_bf16 v[18:21], v[198:201], v[222:225], v[18:21]
	v_mfma_f32_16x16x32_bf16 v[6:9], v[190:193], v[238:241], v[6:9]
	v_mfma_f32_16x16x32_bf16 v[2:5], v[198:201], v[238:241], v[2:5]
	v_mfma_f32_16x16x32_bf16 v[56:59], v[194:197], v[210:213], v[56:59]
	v_mfma_f32_16x16x32_bf16 v[52:55], v[202:205], v[210:213], v[52:55]
	v_mfma_f32_16x16x32_bf16 v[40:43], v[194:197], v[218:221], v[40:43]
	v_mfma_f32_16x16x32_bf16 v[36:39], v[202:205], v[218:221], v[36:39]
	v_mfma_f32_16x16x32_bf16 v[22:25], v[194:197], v[234:237], v[22:25]
	v_mfma_f32_16x16x32_bf16 v[18:21], v[202:205], v[234:237], v[18:21]
	v_mfma_f32_16x16x32_bf16 v[6:9], v[194:197], v[242:245], v[6:9]
	v_mfma_f32_16x16x32_bf16 v[2:5], v[202:205], v[242:245], v[2:5]
	s_setprio 0
	s_barrier
	s_add_i32 s19, s19, 2
	s_add_u32 s26, s26, 0x100
	s_addc_u32 s27, s27, 0
	s_add_u32 s13, s13, 0x100
	s_addc_u32 s15, s15, 0
	s_cmp_gt_u32 s19, 29
	s_cbranch_scc0 .LBB0_1153
	s_and_b64 vcc, exec, s[46:47]
	s_cbranch_vccz .LBB0_1156
	s_barrier

; #define PG8_STAGE(bufoff, gbase, voff) do { _Pragma("unroll") for (int _i = 0; _i < 2; ++_i) \
;         __builtin_amdgcn_global_load_lds((const unsigned*)((const char*)(gbase) + (voff)[_i]), (PG8_LAS unsigned*)(lds + (bufoff) + ldsw + _i * 8192), 16, 0, 0); } while (0)
; #define PG8_LDA(dst, b, h) do { _Pragma("unroll") for (int m = 0; m < 4; ++m) _Pragma("unroll") for (int k = 0; k < 2; ++k) dst[m][k] = *(const PG8_LAS bf16x8*)(lds + PG8_SA(b, h) + aoff + m * 2048 + k * 1024); } while (0)
; #define PG8_LDB(dst, b, h) do { _Pragma("unroll") for (int n = 0; n < 2; ++n) _Pragma("unroll") for (int k = 0; k < 2; ++k) dst[n][k] = *(const PG8_LAS bf16x8*)(lds + PG8_SB(b, h) + boff + n * 2048 + k * 1024); } while (0)
; #define PG8_WAIT_V(n) asm volatile("s_waitcnt vmcnt(" #n ")" ::: "memory")
; #define PG8_WAIT_L(n) asm volatile("s_waitcnt lgkmcnt(" #n ")" ::: "memory")
; #define PG8_BAR __builtin_amdgcn_s_barrier()
; #define PG8_SCHED __builtin_amdgcn_sched_barrier(0)
;     ...
;         for (int t = 0; t < nt; t += 2) {
;             const bool last = (t == nt - 2);
;             const char* a1 = cA + (size_t)(t + 1) * kstep;
;             const char* a2 = last ? nA : cA + (size_t)(t + 2) * kstep; const char* b2 = last ? nB : cB + (size_t)(t + 2) * kstep;
;             const char* a3 = a2 + kstep; const char* b3 = b2 + kstep;
;             if (last && has_next) S.a_ready(nxt);
;             if constexpr (SP2) {
;             PG8_LDB(B0, 0, 0); PG8_LDB(B1, 0, 1); PG8_SCHED; PG8_LDA(At, 0, 0); PG8_STAGE(PG8_SA(1, 1), a1 + hstepA, voffA);
;             PG8_WAIT_V(8); PG8_WAIT_L(0); PG8_BAR; PG8_MMA(0, 0, At, B0); PG8_MMA(0, 1, At, B1); PG8_BAR; PG8_SCHED;
;             PG8_LDA(At, 0, 1); PG8_STAGE(PG8_SB(0, 0), b2, voffB); PG8_STAGE(PG8_SB(0, 1), b2 + hstepB, voffB); PG8_STAGE(PG8_SA(0, 0), a2, voffA);
;             PG8_WAIT_V(8); PG8_WAIT_L(0); PG8_BAR; PG8_MMA(1, 0, At, B0); PG8_MMA(1, 1, At, B1); PG8_BAR; PG8_SCHED;
.LBB0_2023:
	v_add_u32_e32 v163, 0x10000, v235
	s_add_u32 s35, s40, 0xfffc0080
	s_addc_u32 s37, s41, -1
	s_add_i32 s43, 0, 0x10000
	s_cmp_eq_u32 s34, 12
	s_cselect_b32 s57, s49, s37
	s_cselect_b32 s56, s48, s35
	s_cselect_b32 s55, s51, s24
	s_cselect_b32 s54, s50, s15
	s_add_i32 s35, 0, 0x14000
	ds_read_b128 v[142:145], v163
	ds_read_b128 v[146:149], v163 offset:1024
	ds_read_b128 v[150:153], v163 offset:2048
	ds_read_b128 v[154:157], v163 offset:3072
	ds_read_b128 v[158:161], v163 offset:16384
	ds_read_b128 v[186:189], v163 offset:17408
	ds_read_b128 v[190:193], v163 offset:18432
	ds_read_b128 v[194:197], v163 offset:19456
	s_add_i32 m0, s53, 0xc000
	ds_read_b128 v[198:201], v237
	ds_read_b128 v[202:205], v237 offset:1024
	ds_read_b128 v[206:209], v237 offset:2048
	ds_read_b128 v[210:213], v237 offset:3072
	ds_read_b128 v[214:217], v237 offset:4096
	ds_read_b128 v[218:221], v237 offset:5120
	ds_read_b128 v[222:225], v237 offset:6144
	ds_read_b128 v[238:241], v237 offset:7168
	global_load_lds_dwordx4 v138, s[40:41]
	s_add_i32 m0, s53, 0xe000
	s_nop 0
	global_load_lds_dwordx4 v140, s[40:41]
	s_waitcnt vmcnt(8)
	s_waitcnt lgkmcnt(0)
	s_barrier
	s_setprio 1
	v_mfma_f32_16x16x32_bf16 v[128:131], v[142:145], v[198:201], v[128:131]
	v_mfma_f32_16x16x32_bf16 v[124:127], v[150:153], v[198:201], v[124:127]
	v_mfma_f32_16x16x32_bf16 v[120:123], v[142:145], v[206:209], v[120:123]
	v_mfma_f32_16x16x32_bf16 v[116:119], v[150:153], v[206:209], v[116:119]
	v_mfma_f32_16x16x32_bf16 v[112:115], v[142:145], v[214:217], v[112:115]
	v_mfma_f32_16x16x32_bf16 v[108:111], v[150:153], v[214:217], v[108:111]
	v_mfma_f32_16x16x32_bf16 v[104:107], v[142:145], v[222:225], v[104:107]
	v_mfma_f32_16x16x32_bf16 v[100:103], v[150:153], v[222:225], v[100:103]
	v_mfma_f32_16x16x32_bf16 v[128:131], v[146:149], v[202:205], v[128:131]
	v_mfma_f32_16x16x32_bf16 v[124:127], v[154:157], v[202:205], v[124:127]
	v_mfma_f32_16x16x32_bf16 v[120:123], v[146:149], v[210:213], v[120:123]
	v_mfma_f32_16x16x32_bf16 v[116:119], v[154:157], v[210:213], v[116:119]
	v_mfma_f32_16x16x32_bf16 v[112:115], v[146:149], v[218:221], v[112:115]
	v_mfma_f32_16x16x32_bf16 v[108:111], v[154:157], v[218:221], v[108:111]
	v_mfma_f32_16x16x32_bf16 v[104:107], v[146:149], v[238:241], v[104:107]
	v_mfma_f32_16x16x32_bf16 v[100:103], v[154:157], v[238:241], v[100:103]
	v_mfma_f32_16x16x32_bf16 v[96:99], v[158:161], v[198:201], v[96:99]
	v_mfma_f32_16x16x32_bf16 v[92:95], v[190:193], v[198:201], v[92:95]
	v_mfma_f32_16x16x32_bf16 v[88:91], v[158:161], v[206:209], v[88:91]
	v_mfma_f32_16x16x32_bf16 v[84:87], v[190:193], v[206:209], v[84:87]
	v_mfma_f32_16x16x32_bf16 v[80:83], v[158:161], v[214:217], v[80:83]
	v_mfma_f32_16x16x32_bf16 v[76:79], v[190:193], v[214:217], v[76:79]
	v_mfma_f32_16x16x32_bf16 v[72:75], v[158:161], v[222:225], v[72:75]
	v_mfma_f32_16x16x32_bf16 v[68:71], v[190:193], v[222:225], v[68:71]
	v_mfma_f32_16x16x32_bf16 v[96:99], v[186:189], v[202:205], v[96:99]
	v_mfma_f32_16x16x32_bf16 v[92:95], v[194:197], v[202:205], v[92:95]
	v_mfma_f32_16x16x32_bf16 v[88:91], v[186:189], v[210:213], v[88:91]
	v_mfma_f32_16x16x32_bf16 v[84:87], v[194:197], v[210:213], v[84:87]
	v_mfma_f32_16x16x32_bf16 v[80:83], v[186:189], v[218:221], v[80:83]
	v_mfma_f32_16x16x32_bf16 v[76:79], v[194:197], v[218:221], v[76:79]
	v_mfma_f32_16x16x32_bf16 v[72:75], v[186:189], v[238:241], v[72:75]
	v_mfma_f32_16x16x32_bf16 v[68:71], v[194:197], v[238:241], v[68:71]
	s_setprio 0
	s_barrier
	s_add_i32 s37, s43, s21
	s_mov_b32 m0, s37
	ds_read_b128 v[198:201], v237 offset:16384
	ds_read_b128 v[202:205], v237 offset:17408
	ds_read_b128 v[206:209], v237 offset:18432
	ds_read_b128 v[210:213], v237 offset:19456
	ds_read_b128 v[214:217], v237 offset:20480
	ds_read_b128 v[218:221], v237 offset:21504
	ds_read_b128 v[222:225], v237 offset:22528
	ds_read_b128 v[238:241], v237 offset:23552
	global_load_lds_dwordx4 v34, s[54:55]
	s_add_i32 m0, s37, 0x2000
	s_add_u32 s66, s54, 0x40000
	s_addc_u32 s67, s55, 0
	s_add_i32 s35, s35, s21
	global_load_lds_dwordx4 v136, s[54:55]
	s_mov_b32 m0, s35
	s_nop 0
	global_load_lds_dwordx4 v34, s[66:67]
	s_add_i32 m0, s35, 0x2000
	s_nop 0
	global_load_lds_dwordx4 v136, s[66:67]
	s_mov_b32 m0, s53
	s_nop 0
	global_load_lds_dwordx4 v132, s[56:57]
	s_mov_b32 m0, s58
	s_nop 0
	global_load_lds_dwordx4 v134, s[56:57]
	s_waitcnt vmcnt(8)
	s_waitcnt lgkmcnt(0)
	s_barrier
	s_setprio 1
	v_mfma_f32_16x16x32_bf16 v[64:67], v[142:145], v[198:201], v[64:67]
	v_mfma_f32_16x16x32_bf16 v[60:63], v[150:153], v[198:201], v[60:63]
	v_mfma_f32_16x16x32_bf16 v[56:59], v[142:145], v[206:209], v[56:59]
	v_mfma_f32_16x16x32_bf16 v[52:55], v[150:153], v[206:209], v[52:55]
	v_mfma_f32_16x16x32_bf16 v[48:51], v[142:145], v[214:217], v[48:51]
	v_mfma_f32_16x16x32_bf16 v[44:47], v[150:153], v[214:217], v[44:47]
	v_mfma_f32_16x16x32_bf16 v[40:43], v[142:145], v[222:225], v[40:43]
	v_mfma_f32_16x16x32_bf16 v[36:39], v[150:153], v[222:225], v[36:39]
	v_mfma_f32_16x16x32_bf16 v[64:67], v[146:149], v[202:205], v[64:67]
	v_mfma_f32_16x16x32_bf16 v[60:63], v[154:157], v[202:205], v[60:63]
	v_mfma_f32_16x16x32_bf16 v[56:59], v[146:149], v[210:213], v[56:59]
	v_mfma_f32_16x16x32_bf16 v[52:55], v[154:157], v[210:213], v[52:55]
	v_mfma_f32_16x16x32_bf16 v[48:51], v[146:149], v[218:221], v[48:51]
	v_mfma_f32_16x16x32_bf16 v[44:47], v[154:157], v[218:221], v[44:47]
	v_mfma_f32_16x16x32_bf16 v[40:43], v[146:149], v[238:241], v[40:43]
	v_mfma_f32_16x16x32_bf16 v[36:39], v[154:157], v[238:241], v[36:39]
	v_mfma_f32_16x16x32_bf16 v[30:33], v[158:161], v[198:201], v[30:33]
	v_mfma_f32_16x16x32_bf16 v[26:29], v[190:193], v[198:201], v[26:29]
	v_mfma_f32_16x16x32_bf16 v[22:25], v[158:161], v[206:209], v[22:25]
	v_mfma_f32_16x16x32_bf16 v[18:21], v[190:193], v[206:209], v[18:21]
	v_mfma_f32_16x16x32_bf16 v[14:17], v[158:161], v[214:217], v[14:17]
	v_mfma_f32_16x16x32_bf16 v[10:13], v[190:193], v[214:217], v[10:13]
	v_mfma_f32_16x16x32_bf16 v[6:9], v[158:161], v[222:225], v[6:9]
	v_mfma_f32_16x16x32_bf16 v[2:5], v[190:193], v[222:225], v[2:5]
	v_mfma_f32_16x16x32_bf16 v[30:33], v[186:189], v[202:205], v[30:33]
	v_mfma_f32_16x16x32_bf16 v[26:29], v[194:197], v[202:205], v[26:29]
	v_mfma_f32_16x16x32_bf16 v[22:25], v[186:189], v[210:213], v[22:25]
	v_mfma_f32_16x16x32_bf16 v[18:21], v[194:197], v[210:213], v[18:21]
	v_mfma_f32_16x16x32_bf16 v[14:17], v[186:189], v[218:221], v[14:17]
	v_mfma_f32_16x16x32_bf16 v[10:13], v[194:197], v[218:221], v[10:13]
	v_mfma_f32_16x16x32_bf16 v[6:9], v[186:189], v[238:241], v[6:9]
	v_mfma_f32_16x16x32_bf16 v[2:5], v[194:197], v[238:241], v[2:5]
	s_setprio 0
	s_barrier
; #define PG8_STAGE(bufoff, gbase, voff) do { _Pragma("unroll") for (int _i = 0; _i < 2; ++_i) \
;         __builtin_amdgcn_global_load_lds((const unsigned*)((const char*)(gbase) + (voff)[_i]), (PG8_LAS unsigned*)(lds + (bufoff) + ldsw + _i * 8192), 16, 0, 0); } while (0)
; #define PG8_LDA(dst, b, h) do { _Pragma("unroll") for (int m = 0; m < 4; ++m) _Pragma("unroll") for (int k = 0; k < 2; ++k) dst[m][k] = *(const PG8_LAS bf16x8*)(lds + PG8_SA(b, h) + aoff + m * 2048 + k * 1024); } while (0)
; #define PG8_LDB(dst, b, h) do { _Pragma("unroll") for (int n = 0; n < 2; ++n) _Pragma("unroll") for (int k = 0; k < 2; ++k) dst[n][k] = *(const PG8_LAS bf16x8*)(lds + PG8_SB(b, h) + boff + n * 2048 + k * 1024); } while (0)
; #define PG8_WAIT_V(n) asm volatile("s_waitcnt vmcnt(" #n ")" ::: "memory")
; #define PG8_WAIT_L(n) asm volatile("s_waitcnt lgkmcnt(" #n ")" ::: "memory")
; #define PG8_BAR __builtin_amdgcn_s_barrier()
; #define PG8_SCHED __builtin_amdgcn_sched_barrier(0)
;     ...
;             PG8_LDB(B0, 1, 0); PG8_LDB(B1, 1, 1); PG8_SCHED; PG8_LDA(At, 1, 0); PG8_STAGE(PG8_SA(0, 1), a2 + hstepA, voffA);
;             PG8_WAIT_V(8); PG8_WAIT_L(0); PG8_BAR; PG8_MMA(0, 0, At, B0); PG8_MMA(0, 1, At, B1); PG8_BAR; PG8_SCHED;
;             PG8_LDA(At, 1, 1); PG8_STAGE(PG8_SB(1, 0), b3, voffB); PG8_STAGE(PG8_SB(1, 1), b3 + hstepB, voffB); PG8_STAGE(PG8_SA(1, 0), a3, voffA);
;             PG8_WAIT_V(8); PG8_WAIT_L(0); PG8_BAR; PG8_MMA(1, 0, At, B0); PG8_MMA(1, 1, At, B1); PG8_BAR; PG8_SCHED;
	s_add_i32 s35, 0, 0x18000
	s_add_i32 s37, 0, 0x1c000
	ds_read_b128 v[142:145], v163 offset:32768
	ds_read_b128 v[146:149], v163 offset:33792
	ds_read_b128 v[150:153], v163 offset:34816
	ds_read_b128 v[154:157], v163 offset:35840
	ds_read_b128 v[158:161], v163 offset:49152
	ds_read_b128 v[186:189], v163 offset:50176
	ds_read_b128 v[190:193], v163 offset:51200
	ds_read_b128 v[194:197], v163 offset:52224
	s_add_u32 s56, s56, 0x40000
	s_addc_u32 s57, s57, 0
	s_mov_b32 m0, s59
	ds_read_b128 v[198:201], v237 offset:32768
	ds_read_b128 v[202:205], v237 offset:33792
	ds_read_b128 v[206:209], v237 offset:34816
	ds_read_b128 v[210:213], v237 offset:35840
	ds_read_b128 v[214:217], v237 offset:36864
	ds_read_b128 v[218:221], v237 offset:37888
	ds_read_b128 v[222:225], v237 offset:38912
	ds_read_b128 v[238:241], v237 offset:39936
	global_load_lds_dwordx4 v132, s[56:57]
	s_mov_b32 m0, s60
	s_nop 0
	global_load_lds_dwordx4 v134, s[56:57]
	s_waitcnt vmcnt(8)
	s_waitcnt lgkmcnt(0)
	s_barrier
	s_setprio 1
	v_mfma_f32_16x16x32_bf16 v[128:131], v[142:145], v[198:201], v[128:131]
	v_mfma_f32_16x16x32_bf16 v[124:127], v[150:153], v[198:201], v[124:127]
	v_mfma_f32_16x16x32_bf16 v[120:123], v[142:145], v[206:209], v[120:123]
	v_mfma_f32_16x16x32_bf16 v[116:119], v[150:153], v[206:209], v[116:119]
	v_mfma_f32_16x16x32_bf16 v[112:115], v[142:145], v[214:217], v[112:115]
	v_mfma_f32_16x16x32_bf16 v[108:111], v[150:153], v[214:217], v[108:111]
	v_mfma_f32_16x16x32_bf16 v[104:107], v[142:145], v[222:225], v[104:107]
	v_mfma_f32_16x16x32_bf16 v[100:103], v[150:153], v[222:225], v[100:103]
	v_mfma_f32_16x16x32_bf16 v[128:131], v[146:149], v[202:205], v[128:131]
	v_mfma_f32_16x16x32_bf16 v[124:127], v[154:157], v[202:205], v[124:127]
	v_mfma_f32_16x16x32_bf16 v[120:123], v[146:149], v[210:213], v[120:123]
	v_mfma_f32_16x16x32_bf16 v[116:119], v[154:157], v[210:213], v[116:119]
	v_mfma_f32_16x16x32_bf16 v[112:115], v[146:149], v[218:221], v[112:115]
	v_mfma_f32_16x16x32_bf16 v[108:111], v[154:157], v[218:221], v[108:111]
	v_mfma_f32_16x16x32_bf16 v[104:107], v[146:149], v[238:241], v[104:107]
	v_mfma_f32_16x16x32_bf16 v[100:103], v[154:157], v[238:241], v[100:103]
	v_mfma_f32_16x16x32_bf16 v[96:99], v[158:161], v[198:201], v[96:99]
	v_mfma_f32_16x16x32_bf16 v[92:95], v[190:193], v[198:201], v[92:95]
	v_mfma_f32_16x16x32_bf16 v[88:91], v[158:161], v[206:209], v[88:91]
	v_mfma_f32_16x16x32_bf16 v[84:87], v[190:193], v[206:209], v[84:87]
	v_mfma_f32_16x16x32_bf16 v[80:83], v[158:161], v[214:217], v[80:83]
	v_mfma_f32_16x16x32_bf16 v[76:79], v[190:193], v[214:217], v[76:79]
	v_mfma_f32_16x16x32_bf16 v[72:75], v[158:161], v[222:225], v[72:75]
	v_mfma_f32_16x16x32_bf16 v[68:71], v[190:193], v[222:225], v[68:71]
	v_mfma_f32_16x16x32_bf16 v[96:99], v[186:189], v[202:205], v[96:99]
	v_mfma_f32_16x16x32_bf16 v[92:95], v[194:197], v[202:205], v[92:95]
	v_mfma_f32_16x16x32_bf16 v[88:91], v[186:189], v[210:213], v[88:91]
	v_mfma_f32_16x16x32_bf16 v[84:87], v[194:197], v[210:213], v[84:87]
	v_mfma_f32_16x16x32_bf16 v[80:83], v[186:189], v[218:221], v[80:83]
	v_mfma_f32_16x16x32_bf16 v[76:79], v[194:197], v[218:221], v[76:79]
	v_mfma_f32_16x16x32_bf16 v[72:75], v[186:189], v[238:241], v[72:75]
	v_mfma_f32_16x16x32_bf16 v[68:71], v[194:197], v[238:241], v[68:71]
	s_setprio 0
	s_barrier
	s_add_i32 s35, s35, s21
	s_mov_b32 m0, s35
	ds_read_b128 v[198:201], v237 offset:49152
	ds_read_b128 v[202:205], v237 offset:50176
	ds_read_b128 v[206:209], v237 offset:51200
	ds_read_b128 v[210:213], v237 offset:52224
	ds_read_b128 v[214:217], v237 offset:53248
	ds_read_b128 v[218:221], v237 offset:54272
	ds_read_b128 v[222:225], v237 offset:55296
	ds_read_b128 v[238:241], v237 offset:56320
	s_add_u32 vcc_lo, s54, 0x80
	s_addc_u32 vcc_hi, s55, 0
	global_load_lds_dwordx4 v34, vcc
	s_add_i32 m0, s35, 0x2000
	s_add_u32 s54, s54, 0x40080
	s_addc_u32 s55, s55, 0
	s_add_i32 s35, s37, s21
	s_add_u32 vcc_lo, s54, 0xfffc0000
	s_addc_u32 vcc_hi, s55, -1
	global_load_lds_dwordx4 v136, vcc
	s_mov_b32 m0, s35
	s_nop 0
	global_load_lds_dwordx4 v34, s[54:55]
	s_add_i32 m0, s35, 0x2000
	s_nop 0
	global_load_lds_dwordx4 v136, s[54:55]
	s_mov_b32 m0, s61
	s_nop 0
	s_add_u32 vcc_lo, s56, 0xfffc0080
	s_addc_u32 vcc_hi, s57, -1
	global_load_lds_dwordx4 v132, vcc
	s_mov_b32 m0, s62
	s_nop 0
	s_add_u32 vcc_lo, s56, 0xfffc0080
	s_addc_u32 vcc_hi, s57, -1
	global_load_lds_dwordx4 v134, vcc
	s_waitcnt vmcnt(8)
	s_waitcnt lgkmcnt(0)
	s_barrier
	s_setprio 1
	v_mfma_f32_16x16x32_bf16 v[64:67], v[142:145], v[198:201], v[64:67]
	v_mfma_f32_16x16x32_bf16 v[60:63], v[150:153], v[198:201], v[60:63]
	v_mfma_f32_16x16x32_bf16 v[56:59], v[142:145], v[206:209], v[56:59]
	v_mfma_f32_16x16x32_bf16 v[52:55], v[150:153], v[206:209], v[52:55]
	v_mfma_f32_16x16x32_bf16 v[48:51], v[142:145], v[214:217], v[48:51]
	v_mfma_f32_16x16x32_bf16 v[44:47], v[150:153], v[214:217], v[44:47]
	v_mfma_f32_16x16x32_bf16 v[40:43], v[142:145], v[222:225], v[40:43]
	v_mfma_f32_16x16x32_bf16 v[36:39], v[150:153], v[222:225], v[36:39]
	v_mfma_f32_16x16x32_bf16 v[64:67], v[146:149], v[202:205], v[64:67]
	v_mfma_f32_16x16x32_bf16 v[60:63], v[154:157], v[202:205], v[60:63]
	v_mfma_f32_16x16x32_bf16 v[56:59], v[146:149], v[210:213], v[56:59]
	v_mfma_f32_16x16x32_bf16 v[52:55], v[154:157], v[210:213], v[52:55]
	v_mfma_f32_16x16x32_bf16 v[48:51], v[146:149], v[218:221], v[48:51]
	v_mfma_f32_16x16x32_bf16 v[44:47], v[154:157], v[218:221], v[44:47]
	v_mfma_f32_16x16x32_bf16 v[40:43], v[146:149], v[238:241], v[40:43]
	v_mfma_f32_16x16x32_bf16 v[36:39], v[154:157], v[238:241], v[36:39]
	v_mfma_f32_16x16x32_bf16 v[30:33], v[158:161], v[198:201], v[30:33]
	v_mfma_f32_16x16x32_bf16 v[26:29], v[190:193], v[198:201], v[26:29]
	v_mfma_f32_16x16x32_bf16 v[22:25], v[158:161], v[206:209], v[22:25]
	v_mfma_f32_16x16x32_bf16 v[18:21], v[190:193], v[206:209], v[18:21]
	v_mfma_f32_16x16x32_bf16 v[14:17], v[158:161], v[214:217], v[14:17]
	v_mfma_f32_16x16x32_bf16 v[10:13], v[190:193], v[214:217], v[10:13]
	v_mfma_f32_16x16x32_bf16 v[6:9], v[158:161], v[222:225], v[6:9]
	v_mfma_f32_16x16x32_bf16 v[2:5], v[190:193], v[222:225], v[2:5]
	v_mfma_f32_16x16x32_bf16 v[30:33], v[186:189], v[202:205], v[30:33]
	v_mfma_f32_16x16x32_bf16 v[26:29], v[194:197], v[202:205], v[26:29]
	v_mfma_f32_16x16x32_bf16 v[22:25], v[186:189], v[210:213], v[22:25]
	v_mfma_f32_16x16x32_bf16 v[18:21], v[194:197], v[210:213], v[18:21]
	v_mfma_f32_16x16x32_bf16 v[14:17], v[186:189], v[218:221], v[14:17]
	v_mfma_f32_16x16x32_bf16 v[10:13], v[194:197], v[218:221], v[10:13]
	v_mfma_f32_16x16x32_bf16 v[6:9], v[186:189], v[238:241], v[6:9]
	v_mfma_f32_16x16x32_bf16 v[2:5], v[194:197], v[238:241], v[2:5]
	s_setprio 0
	s_barrier
	s_add_i32 s34, s34, 2
	s_add_u32 s40, s40, 0x100
	s_addc_u32 s41, s41, 0
	s_add_u32 s15, s15, 0x100
	s_addc_u32 s24, s24, 0
	s_cmp_gt_u32 s34, 13
	s_cbranch_scc0 .LBB0_2023
	s_and_b64 vcc, exec, s[30:31]
	s_cbranch_vccz .LBB0_2026
	s_barrier

; #define PG8_STAGE(bufoff, gbase, voff) do { _Pragma("unroll") for (int _i = 0; _i < 2; ++_i) \
;         __builtin_amdgcn_global_load_lds((const unsigned*)((const char*)(gbase) + (voff)[_i]), (PG8_LAS unsigned*)(lds + (bufoff) + ldsw + _i * 8192), 16, 0, 0); } while (0)
; #define PG8_LDA(dst, b, h) do { _Pragma("unroll") for (int m = 0; m < 4; ++m) _Pragma("unroll") for (int k = 0; k < 2; ++k) dst[m][k] = *(const PG8_LAS bf16x8*)(lds + PG8_SA(b, h) + aoff + m * 2048 + k * 1024); } while (0)
; #define PG8_LDB(dst, b, h) do { _Pragma("unroll") for (int n = 0; n < 2; ++n) _Pragma("unroll") for (int k = 0; k < 2; ++k) dst[n][k] = *(const PG8_LAS bf16x8*)(lds + PG8_SB(b, h) + boff + n * 2048 + k * 1024); } while (0)
; #define PG8_WAIT_V(n) asm volatile("s_waitcnt vmcnt(" #n ")" ::: "memory")
; #define PG8_WAIT_L(n) asm volatile("s_waitcnt lgkmcnt(" #n ")" ::: "memory")
; #define PG8_BAR __builtin_amdgcn_s_barrier()
; #define PG8_SCHED __builtin_amdgcn_sched_barrier(0)
;     ...
;         for (int t = 0; t < nt; t += 2) {
;             const bool last = (t == nt - 2);
;             const char* a1 = cA + (size_t)(t + 1) * kstep;
;             const char* a2 = last ? nA : cA + (size_t)(t + 2) * kstep; const char* b2 = last ? nB : cB + (size_t)(t + 2) * kstep;
;             const char* a3 = a2 + kstep; const char* b3 = b2 + kstep;
;             if (last && has_next) S.a_ready(nxt);
;             if constexpr (SP2) {
;             PG8_LDB(B0, 0, 0); PG8_LDB(B1, 0, 1); PG8_SCHED; PG8_LDA(At, 0, 0); PG8_STAGE(PG8_SA(1, 1), a1 + hstepA, voffA);
;             PG8_WAIT_V(8); PG8_WAIT_L(0); PG8_BAR; PG8_MMA(0, 0, At, B0); PG8_MMA(0, 1, At, B1); PG8_BAR; PG8_SCHED;
;             PG8_LDA(At, 0, 1); PG8_STAGE(PG8_SB(0, 0), b2, voffB); PG8_STAGE(PG8_SB(0, 1), b2 + hstepB, voffB); PG8_STAGE(PG8_SA(0, 0), a2, voffA);
;             PG8_WAIT_V(8); PG8_WAIT_L(0); PG8_BAR; PG8_MMA(1, 0, At, B0); PG8_MMA(1, 1, At, B1); PG8_BAR; PG8_SCHED;
.LBB0_2138:
	v_add_u32_e32 v163, 0x10000, v143
	s_add_u32 s48, s46, 0xfff80080
	s_addc_u32 s49, s47, -1
	s_add_i32 s61, 0, 0x10000
	s_cmp_eq_u32 s60, 28
	s_cselect_b32 s51, s41, s49
	s_cselect_b32 s50, s56, s48
	s_cselect_b32 s49, s37, s59
	s_cselect_b32 s48, s57, s58
	s_add_i32 s64, 0, 0x14000
	ds_read_b128 v[146:149], v163
	ds_read_b128 v[150:153], v163 offset:1024
	ds_read_b128 v[154:157], v163 offset:2048
	ds_read_b128 v[158:161], v163 offset:3072
	ds_read_b128 v[186:189], v163 offset:16384
	ds_read_b128 v[190:193], v163 offset:17408
	ds_read_b128 v[194:197], v163 offset:18432
	ds_read_b128 v[198:201], v163 offset:19456
	s_add_i32 m0, s21, 0xc000
	ds_read_b128 v[202:205], v145
	ds_read_b128 v[206:209], v145 offset:1024
	ds_read_b128 v[210:213], v145 offset:2048
	ds_read_b128 v[214:217], v145 offset:3072
	ds_read_b128 v[218:221], v145 offset:4096
	ds_read_b128 v[222:225], v145 offset:5120
	ds_read_b128 v[234:237], v145 offset:6144
	ds_read_b128 v[238:241], v145 offset:7168
	global_load_lds_dwordx4 v138, s[46:47]
	s_add_i32 m0, s21, 0xe000
	s_nop 0
	global_load_lds_dwordx4 v140, s[46:47]
	s_waitcnt vmcnt(8)
	s_waitcnt lgkmcnt(0)
	s_barrier
	s_setprio 1
	v_mfma_f32_16x16x32_bf16 v[128:131], v[146:149], v[202:205], v[128:131]
	v_mfma_f32_16x16x32_bf16 v[124:127], v[154:157], v[202:205], v[124:127]
	v_mfma_f32_16x16x32_bf16 v[120:123], v[146:149], v[210:213], v[120:123]
	v_mfma_f32_16x16x32_bf16 v[116:119], v[154:157], v[210:213], v[116:119]
	v_mfma_f32_16x16x32_bf16 v[104:107], v[146:149], v[218:221], v[104:107]
	v_mfma_f32_16x16x32_bf16 v[100:103], v[154:157], v[218:221], v[100:103]
	v_mfma_f32_16x16x32_bf16 v[88:91], v[146:149], v[234:237], v[88:91]
	v_mfma_f32_16x16x32_bf16 v[84:87], v[154:157], v[234:237], v[84:87]
	v_mfma_f32_16x16x32_bf16 v[128:131], v[150:153], v[206:209], v[128:131]
	v_mfma_f32_16x16x32_bf16 v[124:127], v[158:161], v[206:209], v[124:127]
	v_mfma_f32_16x16x32_bf16 v[120:123], v[150:153], v[214:217], v[120:123]
	v_mfma_f32_16x16x32_bf16 v[116:119], v[158:161], v[214:217], v[116:119]
	v_mfma_f32_16x16x32_bf16 v[104:107], v[150:153], v[222:225], v[104:107]
	v_mfma_f32_16x16x32_bf16 v[100:103], v[158:161], v[222:225], v[100:103]
	v_mfma_f32_16x16x32_bf16 v[88:91], v[150:153], v[238:241], v[88:91]
	v_mfma_f32_16x16x32_bf16 v[84:87], v[158:161], v[238:241], v[84:87]
	v_mfma_f32_16x16x32_bf16 v[112:115], v[186:189], v[202:205], v[112:115]
	v_mfma_f32_16x16x32_bf16 v[108:111], v[194:197], v[202:205], v[108:111]
	v_mfma_f32_16x16x32_bf16 v[96:99], v[186:189], v[210:213], v[96:99]
	v_mfma_f32_16x16x32_bf16 v[92:95], v[194:197], v[210:213], v[92:95]
	v_mfma_f32_16x16x32_bf16 v[80:83], v[186:189], v[218:221], v[80:83]
	v_mfma_f32_16x16x32_bf16 v[76:79], v[194:197], v[218:221], v[76:79]
	v_mfma_f32_16x16x32_bf16 v[72:75], v[186:189], v[234:237], v[72:75]
	v_mfma_f32_16x16x32_bf16 v[68:71], v[194:197], v[234:237], v[68:71]
	v_mfma_f32_16x16x32_bf16 v[112:115], v[190:193], v[206:209], v[112:115]
	v_mfma_f32_16x16x32_bf16 v[108:111], v[198:201], v[206:209], v[108:111]
	v_mfma_f32_16x16x32_bf16 v[96:99], v[190:193], v[214:217], v[96:99]
	v_mfma_f32_16x16x32_bf16 v[92:95], v[198:201], v[214:217], v[92:95]
	v_mfma_f32_16x16x32_bf16 v[80:83], v[190:193], v[222:225], v[80:83]
	v_mfma_f32_16x16x32_bf16 v[76:79], v[198:201], v[222:225], v[76:79]
	v_mfma_f32_16x16x32_bf16 v[72:75], v[190:193], v[238:241], v[72:75]
	v_mfma_f32_16x16x32_bf16 v[68:71], v[198:201], v[238:241], v[68:71]
	s_setprio 0
	s_barrier
	s_add_i32 s61, s61, s15
	s_mov_b32 m0, s61
	ds_read_b128 v[202:205], v145 offset:16384
	ds_read_b128 v[206:209], v145 offset:17408
	ds_read_b128 v[210:213], v145 offset:18432
	ds_read_b128 v[214:217], v145 offset:19456
	ds_read_b128 v[218:221], v145 offset:20480
	ds_read_b128 v[222:225], v145 offset:21504
	ds_read_b128 v[234:237], v145 offset:22528
	ds_read_b128 v[238:241], v145 offset:23552
	global_load_lds_dwordx4 v34, s[48:49]
	s_add_i32 m0, s61, 0x2000
	s_add_u32 s62, s48, 0x80000
	s_addc_u32 s63, s49, 0
	s_add_i32 s61, s64, s15
	global_load_lds_dwordx4 v136, s[48:49]
	s_mov_b32 m0, s61
	s_add_u32 s98, s50, 0x80
	s_addc_u32 s99, s51, 0
	global_load_lds_dwordx4 v34, s[62:63]
	s_add_i32 m0, s61, 0x2000
	s_nop 0
	global_load_lds_dwordx4 v136, s[62:63]
	s_mov_b32 m0, s21
	s_nop 0
	global_load_lds_dwordx4 v132, s[50:51]
	s_mov_b32 m0, s34
	s_nop 0
	global_load_lds_dwordx4 v134, s[50:51]
	s_waitcnt vmcnt(8)
	s_waitcnt lgkmcnt(0)
	s_barrier
	s_setprio 1
	v_mfma_f32_16x16x32_bf16 v[64:67], v[146:149], v[202:205], v[64:67]
	v_mfma_f32_16x16x32_bf16 v[60:63], v[154:157], v[202:205], v[60:63]
	v_mfma_f32_16x16x32_bf16 v[56:59], v[146:149], v[210:213], v[56:59]
	v_mfma_f32_16x16x32_bf16 v[52:55], v[154:157], v[210:213], v[52:55]
	v_mfma_f32_16x16x32_bf16 v[40:43], v[146:149], v[218:221], v[40:43]
	v_mfma_f32_16x16x32_bf16 v[36:39], v[154:157], v[218:221], v[36:39]
	v_mfma_f32_16x16x32_bf16 v[22:25], v[146:149], v[234:237], v[22:25]
	v_mfma_f32_16x16x32_bf16 v[18:21], v[154:157], v[234:237], v[18:21]
	v_mfma_f32_16x16x32_bf16 v[64:67], v[150:153], v[206:209], v[64:67]
	v_mfma_f32_16x16x32_bf16 v[60:63], v[158:161], v[206:209], v[60:63]
	v_mfma_f32_16x16x32_bf16 v[56:59], v[150:153], v[214:217], v[56:59]
	v_mfma_f32_16x16x32_bf16 v[52:55], v[158:161], v[214:217], v[52:55]
	v_mfma_f32_16x16x32_bf16 v[40:43], v[150:153], v[222:225], v[40:43]
	v_mfma_f32_16x16x32_bf16 v[36:39], v[158:161], v[222:225], v[36:39]
	v_mfma_f32_16x16x32_bf16 v[22:25], v[150:153], v[238:241], v[22:25]
	v_mfma_f32_16x16x32_bf16 v[18:21], v[158:161], v[238:241], v[18:21]
	v_mfma_f32_16x16x32_bf16 v[48:51], v[186:189], v[202:205], v[48:51]
	v_mfma_f32_16x16x32_bf16 v[44:47], v[194:197], v[202:205], v[44:47]
	v_mfma_f32_16x16x32_bf16 v[30:33], v[186:189], v[210:213], v[30:33]
	v_mfma_f32_16x16x32_bf16 v[26:29], v[194:197], v[210:213], v[26:29]
	v_mfma_f32_16x16x32_bf16 v[14:17], v[186:189], v[218:221], v[14:17]
	v_mfma_f32_16x16x32_bf16 v[10:13], v[194:197], v[218:221], v[10:13]
	v_mfma_f32_16x16x32_bf16 v[6:9], v[186:189], v[234:237], v[6:9]
	v_mfma_f32_16x16x32_bf16 v[2:5], v[194:197], v[234:237], v[2:5]
	v_mfma_f32_16x16x32_bf16 v[48:51], v[190:193], v[206:209], v[48:51]
	v_mfma_f32_16x16x32_bf16 v[44:47], v[198:201], v[206:209], v[44:47]
	v_mfma_f32_16x16x32_bf16 v[30:33], v[190:193], v[214:217], v[30:33]
	v_mfma_f32_16x16x32_bf16 v[26:29], v[198:201], v[214:217], v[26:29]
	v_mfma_f32_16x16x32_bf16 v[14:17], v[190:193], v[222:225], v[14:17]
	v_mfma_f32_16x16x32_bf16 v[10:13], v[198:201], v[222:225], v[10:13]
	v_mfma_f32_16x16x32_bf16 v[6:9], v[190:193], v[238:241], v[6:9]
	v_mfma_f32_16x16x32_bf16 v[2:5], v[198:201], v[238:241], v[2:5]
	s_setprio 0
	s_barrier
; #define PG8_STAGE(bufoff, gbase, voff) do { _Pragma("unroll") for (int _i = 0; _i < 2; ++_i) \
;         __builtin_amdgcn_global_load_lds((const unsigned*)((const char*)(gbase) + (voff)[_i]), (PG8_LAS unsigned*)(lds + (bufoff) + ldsw + _i * 8192), 16, 0, 0); } while (0)
; #define PG8_LDA(dst, b, h) do { _Pragma("unroll") for (int m = 0; m < 4; ++m) _Pragma("unroll") for (int k = 0; k < 2; ++k) dst[m][k] = *(const PG8_LAS bf16x8*)(lds + PG8_SA(b, h) + aoff + m * 2048 + k * 1024); } while (0)
; #define PG8_LDB(dst, b, h) do { _Pragma("unroll") for (int n = 0; n < 2; ++n) _Pragma("unroll") for (int k = 0; k < 2; ++k) dst[n][k] = *(const PG8_LAS bf16x8*)(lds + PG8_SB(b, h) + boff + n * 2048 + k * 1024); } while (0)
; #define PG8_WAIT_V(n) asm volatile("s_waitcnt vmcnt(" #n ")" ::: "memory")
; #define PG8_WAIT_L(n) asm volatile("s_waitcnt lgkmcnt(" #n ")" ::: "memory")
; #define PG8_BAR __builtin_amdgcn_s_barrier()
; #define PG8_SCHED __builtin_amdgcn_sched_barrier(0)
;     ...
;             PG8_LDB(B0, 1, 0); PG8_LDB(B1, 1, 1); PG8_SCHED; PG8_LDA(At, 1, 0); PG8_STAGE(PG8_SA(0, 1), a2 + hstepA, voffA);
;             PG8_WAIT_V(8); PG8_WAIT_L(0); PG8_BAR; PG8_MMA(0, 0, At, B0); PG8_MMA(0, 1, At, B1); PG8_BAR; PG8_SCHED;
;             PG8_LDA(At, 1, 1); PG8_STAGE(PG8_SB(1, 0), b3, voffB); PG8_STAGE(PG8_SB(1, 1), b3 + hstepB, voffB); PG8_STAGE(PG8_SA(1, 0), a3, voffA);
;             PG8_WAIT_V(8); PG8_WAIT_L(0); PG8_BAR; PG8_MMA(1, 0, At, B0); PG8_MMA(1, 1, At, B1); PG8_BAR; PG8_SCHED;
	s_add_i32 s61, 0, 0x18000
	s_add_i32 s62, 0, 0x1c000
	ds_read_b128 v[146:149], v163 offset:32768
	ds_read_b128 v[150:153], v163 offset:33792
	ds_read_b128 v[154:157], v163 offset:34816
	ds_read_b128 v[158:161], v163 offset:35840
	ds_read_b128 v[186:189], v163 offset:49152
	ds_read_b128 v[190:193], v163 offset:50176
	ds_read_b128 v[194:197], v163 offset:51200
	ds_read_b128 v[198:201], v163 offset:52224
	s_add_u32 s50, s50, 0x80000
	s_addc_u32 s51, s51, 0
	s_mov_b32 m0, s35
	ds_read_b128 v[202:205], v145 offset:32768
	ds_read_b128 v[206:209], v145 offset:33792
	ds_read_b128 v[210:213], v145 offset:34816
	ds_read_b128 v[214:217], v145 offset:35840
	ds_read_b128 v[218:221], v145 offset:36864
	ds_read_b128 v[222:225], v145 offset:37888
	ds_read_b128 v[234:237], v145 offset:38912
	ds_read_b128 v[238:241], v145 offset:39936
	global_load_lds_dwordx4 v132, s[50:51]
	s_mov_b32 m0, s52
	s_nop 0
	global_load_lds_dwordx4 v134, s[50:51]
	s_waitcnt vmcnt(8)
	s_waitcnt lgkmcnt(0)
	s_barrier
	s_setprio 1
	v_mfma_f32_16x16x32_bf16 v[128:131], v[146:149], v[202:205], v[128:131]
	v_mfma_f32_16x16x32_bf16 v[124:127], v[154:157], v[202:205], v[124:127]
	v_mfma_f32_16x16x32_bf16 v[120:123], v[146:149], v[210:213], v[120:123]
	v_mfma_f32_16x16x32_bf16 v[116:119], v[154:157], v[210:213], v[116:119]
	v_mfma_f32_16x16x32_bf16 v[104:107], v[146:149], v[218:221], v[104:107]
	v_mfma_f32_16x16x32_bf16 v[100:103], v[154:157], v[218:221], v[100:103]
	v_mfma_f32_16x16x32_bf16 v[88:91], v[146:149], v[234:237], v[88:91]
	v_mfma_f32_16x16x32_bf16 v[84:87], v[154:157], v[234:237], v[84:87]
	v_mfma_f32_16x16x32_bf16 v[128:131], v[150:153], v[206:209], v[128:131]
	v_mfma_f32_16x16x32_bf16 v[124:127], v[158:161], v[206:209], v[124:127]
	v_mfma_f32_16x16x32_bf16 v[120:123], v[150:153], v[214:217], v[120:123]
	v_mfma_f32_16x16x32_bf16 v[116:119], v[158:161], v[214:217], v[116:119]
	v_mfma_f32_16x16x32_bf16 v[104:107], v[150:153], v[222:225], v[104:107]
	v_mfma_f32_16x16x32_bf16 v[100:103], v[158:161], v[222:225], v[100:103]
	v_mfma_f32_16x16x32_bf16 v[88:91], v[150:153], v[238:241], v[88:91]
	v_mfma_f32_16x16x32_bf16 v[84:87], v[158:161], v[238:241], v[84:87]
	v_mfma_f32_16x16x32_bf16 v[112:115], v[186:189], v[202:205], v[112:115]
	v_mfma_f32_16x16x32_bf16 v[108:111], v[194:197], v[202:205], v[108:111]
	v_mfma_f32_16x16x32_bf16 v[96:99], v[186:189], v[210:213], v[96:99]
	v_mfma_f32_16x16x32_bf16 v[92:95], v[194:197], v[210:213], v[92:95]
	v_mfma_f32_16x16x32_bf16 v[80:83], v[186:189], v[218:221], v[80:83]
	v_mfma_f32_16x16x32_bf16 v[76:79], v[194:197], v[218:221], v[76:79]
	v_mfma_f32_16x16x32_bf16 v[72:75], v[186:189], v[234:237], v[72:75]
	v_mfma_f32_16x16x32_bf16 v[68:71], v[194:197], v[234:237], v[68:71]
	v_mfma_f32_16x16x32_bf16 v[112:115], v[190:193], v[206:209], v[112:115]
	v_mfma_f32_16x16x32_bf16 v[108:111], v[198:201], v[206:209], v[108:111]
	v_mfma_f32_16x16x32_bf16 v[96:99], v[190:193], v[214:217], v[96:99]
	v_mfma_f32_16x16x32_bf16 v[92:95], v[198:201], v[214:217], v[92:95]
	v_mfma_f32_16x16x32_bf16 v[80:83], v[190:193], v[222:225], v[80:83]
	v_mfma_f32_16x16x32_bf16 v[76:79], v[198:201], v[222:225], v[76:79]
	v_mfma_f32_16x16x32_bf16 v[72:75], v[190:193], v[238:241], v[72:75]
	v_mfma_f32_16x16x32_bf16 v[68:71], v[198:201], v[238:241], v[68:71]
	s_setprio 0
	s_barrier
	s_add_i32 s50, s61, s15
	s_mov_b32 m0, s50
	ds_read_b128 v[202:205], v145 offset:49152
	ds_read_b128 v[206:209], v145 offset:50176
	ds_read_b128 v[210:213], v145 offset:51200
	ds_read_b128 v[214:217], v145 offset:52224
	ds_read_b128 v[218:221], v145 offset:53248
	ds_read_b128 v[222:225], v145 offset:54272
	ds_read_b128 v[234:237], v145 offset:55296
	ds_read_b128 v[238:241], v145 offset:56320
	s_add_u32 vcc_lo, s48, 0x80
	s_addc_u32 vcc_hi, s49, 0
	global_load_lds_dwordx4 v34, vcc
	s_add_i32 m0, s50, 0x2000
	s_add_u32 s48, s48, 0x80080
	s_addc_u32 s49, s49, 0
	s_add_i32 s50, s62, s15
	s_add_u32 vcc_lo, s48, 0xfff80000
	s_addc_u32 vcc_hi, s49, -1
	global_load_lds_dwordx4 v136, vcc
	s_mov_b32 m0, s50
	s_nop 0
	global_load_lds_dwordx4 v34, s[48:49]
	s_add_i32 m0, s50, 0x2000
	s_nop 0
	global_load_lds_dwordx4 v136, s[48:49]
	s_mov_b32 m0, s24
	s_nop 0
	global_load_lds_dwordx4 v132, s[98:99]
	s_mov_b32 m0, s53
	s_nop 0
	global_load_lds_dwordx4 v134, s[98:99]
	s_waitcnt vmcnt(8)
	s_waitcnt lgkmcnt(0)
	s_barrier
	s_setprio 1
	v_mfma_f32_16x16x32_bf16 v[64:67], v[146:149], v[202:205], v[64:67]
	v_mfma_f32_16x16x32_bf16 v[60:63], v[154:157], v[202:205], v[60:63]
	v_mfma_f32_16x16x32_bf16 v[56:59], v[146:149], v[210:213], v[56:59]
	v_mfma_f32_16x16x32_bf16 v[52:55], v[154:157], v[210:213], v[52:55]
	v_mfma_f32_16x16x32_bf16 v[40:43], v[146:149], v[218:221], v[40:43]
	v_mfma_f32_16x16x32_bf16 v[36:39], v[154:157], v[218:221], v[36:39]
	v_mfma_f32_16x16x32_bf16 v[22:25], v[146:149], v[234:237], v[22:25]
	v_mfma_f32_16x16x32_bf16 v[18:21], v[154:157], v[234:237], v[18:21]
	v_mfma_f32_16x16x32_bf16 v[64:67], v[150:153], v[206:209], v[64:67]
	v_mfma_f32_16x16x32_bf16 v[60:63], v[158:161], v[206:209], v[60:63]
	v_mfma_f32_16x16x32_bf16 v[56:59], v[150:153], v[214:217], v[56:59]
	v_mfma_f32_16x16x32_bf16 v[52:55], v[158:161], v[214:217], v[52:55]
	v_mfma_f32_16x16x32_bf16 v[40:43], v[150:153], v[222:225], v[40:43]
	v_mfma_f32_16x16x32_bf16 v[36:39], v[158:161], v[222:225], v[36:39]
	v_mfma_f32_16x16x32_bf16 v[22:25], v[150:153], v[238:241], v[22:25]
	v_mfma_f32_16x16x32_bf16 v[18:21], v[158:161], v[238:241], v[18:21]
	v_mfma_f32_16x16x32_bf16 v[48:51], v[186:189], v[202:205], v[48:51]
	v_mfma_f32_16x16x32_bf16 v[44:47], v[194:197], v[202:205], v[44:47]
	v_mfma_f32_16x16x32_bf16 v[30:33], v[186:189], v[210:213], v[30:33]
	v_mfma_f32_16x16x32_bf16 v[26:29], v[194:197], v[210:213], v[26:29]
	v_mfma_f32_16x16x32_bf16 v[14:17], v[186:189], v[218:221], v[14:17]
	v_mfma_f32_16x16x32_bf16 v[10:13], v[194:197], v[218:221], v[10:13]
	v_mfma_f32_16x16x32_bf16 v[6:9], v[186:189], v[234:237], v[6:9]
	v_mfma_f32_16x16x32_bf16 v[2:5], v[194:197], v[234:237], v[2:5]
	v_mfma_f32_16x16x32_bf16 v[48:51], v[190:193], v[206:209], v[48:51]
	v_mfma_f32_16x16x32_bf16 v[44:47], v[198:201], v[206:209], v[44:47]
	v_mfma_f32_16x16x32_bf16 v[30:33], v[190:193], v[214:217], v[30:33]
	v_mfma_f32_16x16x32_bf16 v[26:29], v[198:201], v[214:217], v[26:29]
	v_mfma_f32_16x16x32_bf16 v[14:17], v[190:193], v[222:225], v[14:17]
	v_mfma_f32_16x16x32_bf16 v[10:13], v[198:201], v[222:225], v[10:13]
	v_mfma_f32_16x16x32_bf16 v[6:9], v[190:193], v[238:241], v[6:9]
	v_mfma_f32_16x16x32_bf16 v[2:5], v[198:201], v[238:241], v[2:5]
	s_setprio 0
	s_barrier
	s_add_i32 s60, s60, 2
	s_add_u32 s46, s46, 0x100
	s_addc_u32 s47, s47, 0
	s_add_u32 s58, s58, 0x100
	s_addc_u32 s59, s59, 0
	s_cmp_gt_u32 s60, 29
	s_cbranch_scc0 .LBB0_2138
	s_and_b64 vcc, exec, s[28:29]
	s_cbranch_vccz .LBB0_2141
	s_barrier
